# GEMM K-loops: first iteration peeled with zero SrcC so the 128-register accumulator zeroing per unit is gone (all GEMM phases except the mid-hook one)
# baseline (speedup 1.0000x reference)
; #define PG8_STAGE(bufoff, gbase, voff) do { _Pragma("unroll") for (int _i = 0; _i < 2; ++_i) \
;         __builtin_amdgcn_global_load_lds((const unsigned*)((const char*)(gbase) + (voff)[_i]), (PG8_LAS unsigned*)(lds + (bufoff) + ldsw + _i * 8192), 16, 0, 0); } while (0)
; #define PG8_LDA(dst, b, h) do { _Pragma("unroll") for (int m = 0; m < 4; ++m) _Pragma("unroll") for (int k = 0; k < 2; ++k) dst[m][k] = *(const PG8_LAS bf16x8*)(lds + PG8_SA(b, h) + aoff + m * 2048 + k * 1024); } while (0)
; #define PG8_LDB(dst, b, h) do { _Pragma("unroll") for (int n = 0; n < 2; ++n) _Pragma("unroll") for (int k = 0; k < 2; ++k) dst[n][k] = *(const PG8_LAS bf16x8*)(lds + PG8_SB(b, h) + boff + n * 2048 + k * 1024); } while (0)
; #define PG8_MMA(ai, bj, At, Bt) do { __builtin_amdgcn_s_setprio(1); _Pragma("unroll") for (int m = 0; m < 4; ++m) _Pragma("unroll") for (int n = 0; n < 2; ++n) _Pragma("unroll") for (int k = 0; k < 2; ++k) \
;         acc[ai][bj][m][n] = __builtin_amdgcn_mfma_f32_16x16x32_bf16(Bt[n][k], At[m][k], acc[ai][bj][m][n], 0, 0, 0); __builtin_amdgcn_s_setprio(0); } while (0)
; #define PG8_WAIT_V(n) asm volatile("s_waitcnt vmcnt(" #n ")" ::: "memory")
; template <class Epi, class Sched, bool ALIGN_EPI = false, bool SP2 = false>
; __device__ __forceinline__ void gemm_phase(PG8_LAS unsigned char* lds, const Gemm g, const Sched& S, const Epi& E) {
;     ...
;         const char* nA = has_next ? (const char*)g.A + (size_t)nxt.pm * tstep : cA; const char* nB = has_next ? (const char*)g.Bt + (size_t)nxt.pn * tstep : cB;
;         for (int t = 0; t < nt; t += 2) {
;             const bool last = (t == nt - 2);
;             const char* a1 = cA + (size_t)(t + 1) * kstep;
;             const char* a2 = last ? nA : cA + (size_t)(t + 2) * kstep; const char* b2 = last ? nB : cB + (size_t)(t + 2) * kstep;
;             const char* a3 = a2 + kstep; const char* b3 = b2 + kstep;
;             if (last && has_next) S.a_ready(nxt);
;             if constexpr (SP2) {
;             PG8_LDB(B0, 0, 0); PG8_LDB(B1, 0, 1); PG8_SCHED; PG8_LDA(At, 0, 0); PG8_STAGE(PG8_SA(1, 1), a1 + hstep, voffA);
;             PG8_WAIT_V(8); PG8_WAIT_L(0); PG8_BAR; PG8_MMA(0, 0, At, B0); PG8_MMA(0, 1, At, B1); PG8_BAR; PG8_SCHED;
;             PG8_LDA(At, 0, 1); PG8_STAGE(PG8_SB(0, 0), b2, voffB); PG8_STAGE(PG8_SB(0, 1), b2 + hstep, voffB); PG8_STAGE(PG8_SA(0, 0), a2, voffA);
.LBB0_127:
	s_ashr_i32 s3, s2, 31
	s_lshl_b64 s[12:13], s[2:3], 19
	s_add_u32 s62, s15, s12
	s_addc_u32 s63, s16, s13
	s_and_b64 s[12:13], s[4:5], exec
	s_cselect_b32 s1, s63, s57
	s_cselect_b32 s3, s62, s56
	s_ashr_i32 s55, s54, 31
	s_lshl_b64 s[12:13], s[54:55], 19
	s_add_u32 s64, s18, s12
	s_addc_u32 s65, s19, s13
	s_and_b64 s[12:13], s[4:5], exec
	s_cselect_b32 s12, s65, s41
	s_cselect_b32 s13, s64, s40
	s_add_u32 vcc_lo, s56, 0x40080
	s_addc_u32 vcc_hi, s57, 0
	s_add_u32 s55, s40, 0x100
	s_addc_u32 s61, s41, 0
	s_mov_b32 s60, -2
	v_mov_b32_e32 v129, v0
	s_add_u32 s40, vcc_lo, 0xfffc0080
	s_addc_u32 s41, vcc_hi, -1
	s_add_i32 s68, 0, 0x10000
	s_cmp_eq_u32 s60, 12
	s_cselect_b32 s57, s1, s41
	s_cselect_b32 s56, s3, s40
	v_add_u32_e32 v112, s68, v176
	s_cselect_b32 s41, s12, s61
	s_cselect_b32 s40, s13, s55
	s_add_i32 s70, 0, 0x14000
	ds_read_b128 v[130:133], v112
	ds_read_b128 v[134:137], v112 offset:1024
	ds_read_b128 v[152:155], v112 offset:2048
	ds_read_b128 v[156:159], v112 offset:3072
	v_add_u32_e32 v112, s70, v176
	ds_read_b128 v[160:163], v112
	ds_read_b128 v[164:167], v112 offset:1024
	ds_read_b128 v[168:171], v112 offset:2048
	ds_read_b128 v[172:175], v112 offset:3072
	v_lshl_add_u64 v[180:181], vcc, 0, v[148:149]
	s_add_i32 m0, s22, 0xc000
	ds_read_b128 v[200:203], v179
	ds_read_b128 v[204:207], v179 offset:1024
	ds_read_b128 v[208:211], v179 offset:2048
	ds_read_b128 v[222:225], v179 offset:3072
	ds_read_b128 v[226:229], v179 offset:4096
	ds_read_b128 v[230:233], v179 offset:5120
	ds_read_b128 v[234:237], v179 offset:6144
	ds_read_b128 v[238:241], v179 offset:7168
	global_load_lds_dwordx4 v[180:181], off
	v_lshl_add_u64 v[180:181], vcc, 0, v[150:151]
	s_add_i32 m0, s22, 0xe000
	s_nop 0
	global_load_lds_dwordx4 v[180:181], off
	s_waitcnt vmcnt(8)
	s_waitcnt lgkmcnt(0)
	s_barrier
	s_setprio 1
	s_waitcnt lgkmcnt(0)
	v_mfma_f32_16x16x32_bf16 v[126:129], v[130:133], v[200:203], 0
	v_mfma_f32_16x16x32_bf16 v[122:125], v[152:155], v[200:203], 0
	v_mfma_f32_16x16x32_bf16 v[108:111], v[130:133], v[208:211], 0
	v_mfma_f32_16x16x32_bf16 v[104:107], v[152:155], v[208:211], 0
	v_mfma_f32_16x16x32_bf16 v[92:95], v[130:133], v[226:229], 0
	v_mfma_f32_16x16x32_bf16 v[88:91], v[152:155], v[226:229], 0
	v_mfma_f32_16x16x32_bf16 v[76:79], v[130:133], v[234:237], 0
	v_mfma_f32_16x16x32_bf16 v[72:75], v[152:155], v[234:237], 0
	v_mfma_f32_16x16x32_bf16 v[126:129], v[134:137], v[204:207], v[126:129]
	v_mfma_f32_16x16x32_bf16 v[122:125], v[156:159], v[204:207], v[122:125]
	v_mfma_f32_16x16x32_bf16 v[108:111], v[134:137], v[222:225], v[108:111]
	v_mfma_f32_16x16x32_bf16 v[104:107], v[156:159], v[222:225], v[104:107]
	v_mfma_f32_16x16x32_bf16 v[92:95], v[134:137], v[230:233], v[92:95]
	v_mfma_f32_16x16x32_bf16 v[88:91], v[156:159], v[230:233], v[88:91]
	v_mfma_f32_16x16x32_bf16 v[76:79], v[134:137], v[238:241], v[76:79]
	v_mfma_f32_16x16x32_bf16 v[72:75], v[156:159], v[238:241], v[72:75]
	s_setprio 0
	s_setprio 1
	v_mfma_f32_16x16x32_bf16 v[118:121], v[160:163], v[200:203], 0
	v_mfma_f32_16x16x32_bf16 v[114:117], v[168:171], v[200:203], 0
	v_mfma_f32_16x16x32_bf16 v[100:103], v[160:163], v[208:211], 0
	v_mfma_f32_16x16x32_bf16 v[96:99], v[168:171], v[208:211], 0
	v_mfma_f32_16x16x32_bf16 v[84:87], v[160:163], v[226:229], 0
	v_mfma_f32_16x16x32_bf16 v[80:83], v[168:171], v[226:229], 0
	v_mfma_f32_16x16x32_bf16 v[68:71], v[160:163], v[234:237], 0
	v_mfma_f32_16x16x32_bf16 v[64:67], v[168:171], v[234:237], 0
	v_mfma_f32_16x16x32_bf16 v[118:121], v[164:167], v[204:207], v[118:121]
	v_mfma_f32_16x16x32_bf16 v[114:117], v[172:175], v[204:207], v[114:117]
	v_mfma_f32_16x16x32_bf16 v[100:103], v[164:167], v[222:225], v[100:103]
	v_mfma_f32_16x16x32_bf16 v[96:99], v[172:175], v[222:225], v[96:99]
	v_mfma_f32_16x16x32_bf16 v[84:87], v[164:167], v[230:233], v[84:87]
	v_mfma_f32_16x16x32_bf16 v[80:83], v[172:175], v[230:233], v[80:83]
	v_mfma_f32_16x16x32_bf16 v[68:71], v[164:167], v[238:241], v[68:71]
	v_mfma_f32_16x16x32_bf16 v[64:67], v[172:175], v[238:241], v[64:67]
	s_setprio 0
	s_barrier
	s_add_i32 s68, s68, s20
	v_lshl_add_u64 v[180:181], s[40:41], 0, v[142:143]
	s_mov_b32 m0, s68
	ds_read_b128 v[200:203], v179 offset:16384
	ds_read_b128 v[204:207], v179 offset:17408
	ds_read_b128 v[208:211], v179 offset:18432
	ds_read_b128 v[222:225], v179 offset:19456
	ds_read_b128 v[226:229], v179 offset:20480
	ds_read_b128 v[230:233], v179 offset:21504
	ds_read_b128 v[234:237], v179 offset:22528
	ds_read_b128 v[238:241], v179 offset:23552
	global_load_lds_dwordx4 v[180:181], off
	s_add_i32 m0, s68, 0x2000
	s_add_u32 s68, s40, 0x40000
	v_lshl_add_u64 v[184:185], s[40:41], 0, v[138:139]
	s_addc_u32 s69, s41, 0
	s_add_i32 s70, s70, s20
	global_load_lds_dwordx4 v[184:185], off
	v_lshl_add_u64 v[186:187], s[68:69], 0, v[142:143]
	s_mov_b32 m0, s70
	v_lshl_add_u64 v[212:213], s[56:57], 0, v[140:141]
	global_load_lds_dwordx4 v[186:187], off
	v_lshl_add_u64 v[186:187], s[68:69], 0, v[138:139]
	s_add_i32 m0, s70, 0x2000
	s_nop 0
	global_load_lds_dwordx4 v[186:187], off
	v_lshl_add_u64 v[186:187], s[56:57], 0, v[144:145]
	s_mov_b32 m0, s22
	s_nop 0
	global_load_lds_dwordx4 v[186:187], off
	s_mov_b32 m0, s23
	s_nop 0
	global_load_lds_dwordx4 v[212:213], off
	s_waitcnt vmcnt(8)
	s_waitcnt lgkmcnt(0)
	s_barrier
; #define PG8_STAGE(bufoff, gbase, voff) do { _Pragma("unroll") for (int _i = 0; _i < 2; ++_i) \
;         __builtin_amdgcn_global_load_lds((const unsigned*)((const char*)(gbase) + (voff)[_i]), (PG8_LAS unsigned*)(lds + (bufoff) + ldsw + _i * 8192), 16, 0, 0); } while (0)
; #define PG8_LDA(dst, b, h) do { _Pragma("unroll") for (int m = 0; m < 4; ++m) _Pragma("unroll") for (int k = 0; k < 2; ++k) dst[m][k] = *(const PG8_LAS bf16x8*)(lds + PG8_SA(b, h) + aoff + m * 2048 + k * 1024); } while (0)
; #define PG8_LDB(dst, b, h) do { _Pragma("unroll") for (int n = 0; n < 2; ++n) _Pragma("unroll") for (int k = 0; k < 2; ++k) dst[n][k] = *(const PG8_LAS bf16x8*)(lds + PG8_SB(b, h) + boff + n * 2048 + k * 1024); } while (0)
; #define PG8_MMA(ai, bj, At, Bt) do { __builtin_amdgcn_s_setprio(1); _Pragma("unroll") for (int m = 0; m < 4; ++m) _Pragma("unroll") for (int n = 0; n < 2; ++n) _Pragma("unroll") for (int k = 0; k < 2; ++k) \
;         acc[ai][bj][m][n] = __builtin_amdgcn_mfma_f32_16x16x32_bf16(Bt[n][k], At[m][k], acc[ai][bj][m][n], 0, 0, 0); __builtin_amdgcn_s_setprio(0); } while (0)
; #define PG8_WAIT_V(n) asm volatile("s_waitcnt vmcnt(" #n ")" ::: "memory")
; #define PG8_WAIT_L(n) asm volatile("s_waitcnt lgkmcnt(" #n ")" ::: "memory")
; #define PG8_BAR __builtin_amdgcn_s_barrier()
; #define PG8_SCHED __builtin_amdgcn_sched_barrier(0)
; template <class Epi, class Sched, bool ALIGN_EPI = false, bool SP2 = false>
; __device__ __forceinline__ void gemm_phase(PG8_LAS unsigned char* lds, const Gemm g, const Sched& S, const Epi& E) {
;     ...
;             PG8_WAIT_V(8); PG8_WAIT_L(0); PG8_BAR; PG8_MMA(1, 0, At, B0); PG8_MMA(1, 1, At, B1); PG8_BAR; PG8_SCHED;
;             PG8_LDB(B0, 1, 0); PG8_LDB(B1, 1, 1); PG8_SCHED; PG8_LDA(At, 1, 0); PG8_STAGE(PG8_SA(0, 1), a2 + hstep, voffA);
;             PG8_WAIT_V(8); PG8_WAIT_L(0); PG8_BAR; PG8_MMA(0, 0, At, B0); PG8_MMA(0, 1, At, B1); PG8_BAR; PG8_SCHED;
	s_setprio 1
	s_waitcnt lgkmcnt(0)
	v_mfma_f32_16x16x32_bf16 v[60:63], v[130:133], v[200:203], 0
	v_mfma_f32_16x16x32_bf16 v[56:59], v[152:155], v[200:203], 0
	v_mfma_f32_16x16x32_bf16 v[44:47], v[130:133], v[208:211], 0
	v_mfma_f32_16x16x32_bf16 v[40:43], v[152:155], v[208:211], 0
	v_mfma_f32_16x16x32_bf16 v[28:31], v[130:133], v[226:229], 0
	v_mfma_f32_16x16x32_bf16 v[24:27], v[152:155], v[226:229], 0
	v_mfma_f32_16x16x32_bf16 v[12:15], v[130:133], v[234:237], 0
	v_mfma_f32_16x16x32_bf16 v[8:11], v[152:155], v[234:237], 0
	v_mfma_f32_16x16x32_bf16 v[60:63], v[134:137], v[204:207], v[60:63]
	v_mfma_f32_16x16x32_bf16 v[56:59], v[156:159], v[204:207], v[56:59]
	v_mfma_f32_16x16x32_bf16 v[44:47], v[134:137], v[222:225], v[44:47]
	v_mfma_f32_16x16x32_bf16 v[40:43], v[156:159], v[222:225], v[40:43]
	v_mfma_f32_16x16x32_bf16 v[28:31], v[134:137], v[230:233], v[28:31]
	v_mfma_f32_16x16x32_bf16 v[24:27], v[156:159], v[230:233], v[24:27]
	v_mfma_f32_16x16x32_bf16 v[12:15], v[134:137], v[238:241], v[12:15]
	v_mfma_f32_16x16x32_bf16 v[8:11], v[156:159], v[238:241], v[8:11]
	s_setprio 0
	s_setprio 1
	v_mfma_f32_16x16x32_bf16 v[52:55], v[160:163], v[200:203], 0
	v_mfma_f32_16x16x32_bf16 v[48:51], v[168:171], v[200:203], 0
	v_mfma_f32_16x16x32_bf16 v[36:39], v[160:163], v[208:211], 0
	v_mfma_f32_16x16x32_bf16 v[32:35], v[168:171], v[208:211], 0
	v_mfma_f32_16x16x32_bf16 v[20:23], v[160:163], v[226:229], 0
	v_mfma_f32_16x16x32_bf16 v[16:19], v[168:171], v[226:229], 0
	v_mfma_f32_16x16x32_bf16 v[4:7], v[160:163], v[234:237], 0
	v_mfma_f32_16x16x32_bf16 v[0:3], v[168:171], v[234:237], 0
	v_mfma_f32_16x16x32_bf16 v[52:55], v[164:167], v[204:207], v[52:55]
	v_mfma_f32_16x16x32_bf16 v[48:51], v[172:175], v[204:207], v[48:51]
	v_mfma_f32_16x16x32_bf16 v[36:39], v[164:167], v[222:225], v[36:39]
	v_mfma_f32_16x16x32_bf16 v[32:35], v[172:175], v[222:225], v[32:35]
	v_mfma_f32_16x16x32_bf16 v[20:23], v[164:167], v[230:233], v[20:23]
	v_mfma_f32_16x16x32_bf16 v[16:19], v[172:175], v[230:233], v[16:19]
	v_mfma_f32_16x16x32_bf16 v[4:7], v[164:167], v[238:241], v[4:7]
	v_mfma_f32_16x16x32_bf16 v[0:3], v[172:175], v[238:241], v[0:3]
	s_setprio 0
	s_barrier
	s_add_i32 s68, 0, 0x18000
	v_add_u32_e32 v112, s68, v176
	s_add_i32 s69, 0, 0x1c000
	ds_read_b128 v[130:133], v112
	ds_read_b128 v[134:137], v112 offset:1024
	ds_read_b128 v[152:155], v112 offset:2048
	ds_read_b128 v[156:159], v112 offset:3072
	v_add_u32_e32 v112, s69, v176
	ds_read_b128 v[160:163], v112
	ds_read_b128 v[164:167], v112 offset:1024
	ds_read_b128 v[168:171], v112 offset:2048
	ds_read_b128 v[172:175], v112 offset:3072
	s_add_u32 s56, s56, 0x40000
	s_addc_u32 s57, s57, 0
	s_mov_b32 m0, s45
	v_lshl_add_u64 v[242:243], s[56:57], 0, v[144:145]
	ds_read_b128 v[200:203], v179 offset:32768
	ds_read_b128 v[204:207], v179 offset:33792
	ds_read_b128 v[208:211], v179 offset:34816
	ds_read_b128 v[222:225], v179 offset:35840
	ds_read_b128 v[226:229], v179 offset:36864
	ds_read_b128 v[230:233], v179 offset:37888
	ds_read_b128 v[234:237], v179 offset:38912
	ds_read_b128 v[238:241], v179 offset:39936
	global_load_lds_dwordx4 v[242:243], off
	v_lshl_add_u64 v[242:243], s[56:57], 0, v[140:141]
	s_mov_b32 m0, s53
	s_nop 0
	global_load_lds_dwordx4 v[242:243], off
	s_waitcnt vmcnt(8)
	s_waitcnt lgkmcnt(0)
	s_barrier
	s_setprio 1
	s_waitcnt lgkmcnt(0)
	v_mfma_f32_16x16x32_bf16 v[126:129], v[130:133], v[200:203], v[126:129]
	v_mfma_f32_16x16x32_bf16 v[122:125], v[152:155], v[200:203], v[122:125]
	v_mfma_f32_16x16x32_bf16 v[108:111], v[130:133], v[208:211], v[108:111]
	v_mfma_f32_16x16x32_bf16 v[104:107], v[152:155], v[208:211], v[104:107]
	v_mfma_f32_16x16x32_bf16 v[92:95], v[130:133], v[226:229], v[92:95]
	v_mfma_f32_16x16x32_bf16 v[88:91], v[152:155], v[226:229], v[88:91]
	v_mfma_f32_16x16x32_bf16 v[76:79], v[130:133], v[234:237], v[76:79]
	v_mfma_f32_16x16x32_bf16 v[72:75], v[152:155], v[234:237], v[72:75]
	v_mfma_f32_16x16x32_bf16 v[126:129], v[134:137], v[204:207], v[126:129]
	v_mfma_f32_16x16x32_bf16 v[122:125], v[156:159], v[204:207], v[122:125]
	v_mfma_f32_16x16x32_bf16 v[108:111], v[134:137], v[222:225], v[108:111]
	v_mfma_f32_16x16x32_bf16 v[104:107], v[156:159], v[222:225], v[104:107]
	v_mfma_f32_16x16x32_bf16 v[92:95], v[134:137], v[230:233], v[92:95]
	v_mfma_f32_16x16x32_bf16 v[88:91], v[156:159], v[230:233], v[88:91]
	v_mfma_f32_16x16x32_bf16 v[76:79], v[134:137], v[238:241], v[76:79]
	v_mfma_f32_16x16x32_bf16 v[72:75], v[156:159], v[238:241], v[72:75]
	s_setprio 0
	s_setprio 1
	v_mfma_f32_16x16x32_bf16 v[118:121], v[160:163], v[200:203], v[118:121]
	v_mfma_f32_16x16x32_bf16 v[114:117], v[168:171], v[200:203], v[114:117]
	v_mfma_f32_16x16x32_bf16 v[100:103], v[160:163], v[208:211], v[100:103]
	v_mfma_f32_16x16x32_bf16 v[96:99], v[168:171], v[208:211], v[96:99]
	v_mfma_f32_16x16x32_bf16 v[84:87], v[160:163], v[226:229], v[84:87]
	v_mfma_f32_16x16x32_bf16 v[80:83], v[168:171], v[226:229], v[80:83]
	v_mfma_f32_16x16x32_bf16 v[68:71], v[160:163], v[234:237], v[68:71]
	v_mfma_f32_16x16x32_bf16 v[64:67], v[168:171], v[234:237], v[64:67]
	v_mfma_f32_16x16x32_bf16 v[118:121], v[164:167], v[204:207], v[118:121]
	v_mfma_f32_16x16x32_bf16 v[114:117], v[172:175], v[204:207], v[114:117]
	v_mfma_f32_16x16x32_bf16 v[100:103], v[164:167], v[222:225], v[100:103]
	v_mfma_f32_16x16x32_bf16 v[96:99], v[172:175], v[222:225], v[96:99]
	v_mfma_f32_16x16x32_bf16 v[84:87], v[164:167], v[230:233], v[84:87]
	v_mfma_f32_16x16x32_bf16 v[80:83], v[172:175], v[230:233], v[80:83]
	v_mfma_f32_16x16x32_bf16 v[68:71], v[164:167], v[238:241], v[68:71]
	v_mfma_f32_16x16x32_bf16 v[64:67], v[172:175], v[238:241], v[64:67]
	s_setprio 0
	s_barrier
; #define PG8_STAGE(bufoff, gbase, voff) do { _Pragma("unroll") for (int _i = 0; _i < 2; ++_i) \
;         __builtin_amdgcn_global_load_lds((const unsigned*)((const char*)(gbase) + (voff)[_i]), (PG8_LAS unsigned*)(lds + (bufoff) + ldsw + _i * 8192), 16, 0, 0); } while (0)
; #define PG8_LDA(dst, b, h) do { _Pragma("unroll") for (int m = 0; m < 4; ++m) _Pragma("unroll") for (int k = 0; k < 2; ++k) dst[m][k] = *(const PG8_LAS bf16x8*)(lds + PG8_SA(b, h) + aoff + m * 2048 + k * 1024); } while (0)
; #define PG8_MMA(ai, bj, At, Bt) do { __builtin_amdgcn_s_setprio(1); _Pragma("unroll") for (int m = 0; m < 4; ++m) _Pragma("unroll") for (int n = 0; n < 2; ++n) _Pragma("unroll") for (int k = 0; k < 2; ++k) \
;         acc[ai][bj][m][n] = __builtin_amdgcn_mfma_f32_16x16x32_bf16(Bt[n][k], At[m][k], acc[ai][bj][m][n], 0, 0, 0); __builtin_amdgcn_s_setprio(0); } while (0)
; #define PG8_WAIT_V(n) asm volatile("s_waitcnt vmcnt(" #n ")" ::: "memory")
; #define PG8_WAIT_L(n) asm volatile("s_waitcnt lgkmcnt(" #n ")" ::: "memory")
; #define PG8_BAR __builtin_amdgcn_s_barrier()
; #define PG8_SCHED __builtin_amdgcn_sched_barrier(0)
; template <class Epi, class Sched, bool ALIGN_EPI = false, bool SP2 = false>
; __device__ __forceinline__ void gemm_phase(PG8_LAS unsigned char* lds, const Gemm g, const Sched& S, const Epi& E) {
;     ...
;             PG8_LDA(At, 1, 1); PG8_STAGE(PG8_SB(1, 0), b3, voffB); PG8_STAGE(PG8_SB(1, 1), b3 + hstep, voffB); PG8_STAGE(PG8_SA(1, 0), a3, voffA);
;             PG8_WAIT_V(8); PG8_WAIT_L(0); PG8_BAR; PG8_MMA(1, 0, At, B0); PG8_MMA(1, 1, At, B1); PG8_BAR; PG8_SCHED;
	s_add_i32 s56, s68, s20
	v_lshl_add_u64 v[180:181], v[180:181], 0, s[36:37]
	s_mov_b32 m0, s56
	ds_read_b128 v[200:203], v179 offset:49152
	ds_read_b128 v[204:207], v179 offset:50176
	ds_read_b128 v[208:211], v179 offset:51200
	ds_read_b128 v[222:225], v179 offset:52224
	ds_read_b128 v[226:229], v179 offset:53248
	ds_read_b128 v[230:233], v179 offset:54272
	ds_read_b128 v[234:237], v179 offset:55296
	ds_read_b128 v[238:241], v179 offset:56320
	global_load_lds_dwordx4 v[180:181], off
	s_add_i32 m0, s56, 0x2000
	s_add_u32 s40, s40, 0x40080
	v_lshl_add_u64 v[180:181], v[184:185], 0, s[36:37]
	s_addc_u32 s41, s41, 0
	s_add_i32 s56, s69, s20
	global_load_lds_dwordx4 v[180:181], off
	v_lshl_add_u64 v[180:181], s[40:41], 0, v[142:143]
	s_mov_b32 m0, s56
	s_nop 0
	global_load_lds_dwordx4 v[180:181], off
	v_lshl_add_u64 v[180:181], s[40:41], 0, v[138:139]
	s_add_i32 m0, s56, 0x2000
	s_nop 0
	global_load_lds_dwordx4 v[180:181], off
	v_lshl_add_u64 v[180:181], v[186:187], 0, s[36:37]
	s_mov_b32 m0, s11
	s_nop 0
	global_load_lds_dwordx4 v[180:181], off
	v_lshl_add_u64 v[180:181], v[212:213], 0, s[36:37]
	s_mov_b32 m0, s44
	s_nop 0
	global_load_lds_dwordx4 v[180:181], off
	s_waitcnt vmcnt(8)
	s_waitcnt lgkmcnt(0)
	s_barrier
	s_setprio 1
	s_waitcnt lgkmcnt(0)
	v_mfma_f32_16x16x32_bf16 v[60:63], v[130:133], v[200:203], v[60:63]
	v_mfma_f32_16x16x32_bf16 v[56:59], v[152:155], v[200:203], v[56:59]
	v_mfma_f32_16x16x32_bf16 v[44:47], v[130:133], v[208:211], v[44:47]
	v_mfma_f32_16x16x32_bf16 v[40:43], v[152:155], v[208:211], v[40:43]
	v_mfma_f32_16x16x32_bf16 v[28:31], v[130:133], v[226:229], v[28:31]
	v_mfma_f32_16x16x32_bf16 v[24:27], v[152:155], v[226:229], v[24:27]
	v_mfma_f32_16x16x32_bf16 v[12:15], v[130:133], v[234:237], v[12:15]
	v_mfma_f32_16x16x32_bf16 v[8:11], v[152:155], v[234:237], v[8:11]
	v_mfma_f32_16x16x32_bf16 v[60:63], v[134:137], v[204:207], v[60:63]
	v_mfma_f32_16x16x32_bf16 v[56:59], v[156:159], v[204:207], v[56:59]
	v_mfma_f32_16x16x32_bf16 v[44:47], v[134:137], v[222:225], v[44:47]
	v_mfma_f32_16x16x32_bf16 v[40:43], v[156:159], v[222:225], v[40:43]
	v_mfma_f32_16x16x32_bf16 v[28:31], v[134:137], v[230:233], v[28:31]
	v_mfma_f32_16x16x32_bf16 v[24:27], v[156:159], v[230:233], v[24:27]
	v_mfma_f32_16x16x32_bf16 v[12:15], v[134:137], v[238:241], v[12:15]
	v_mfma_f32_16x16x32_bf16 v[8:11], v[156:159], v[238:241], v[8:11]
	s_setprio 0
	s_setprio 1
	v_mfma_f32_16x16x32_bf16 v[52:55], v[160:163], v[200:203], v[52:55]
	v_mfma_f32_16x16x32_bf16 v[48:51], v[168:171], v[200:203], v[48:51]
	v_mfma_f32_16x16x32_bf16 v[36:39], v[160:163], v[208:211], v[36:39]
	v_mfma_f32_16x16x32_bf16 v[32:35], v[168:171], v[208:211], v[32:35]
	v_mfma_f32_16x16x32_bf16 v[20:23], v[160:163], v[226:229], v[20:23]
	v_mfma_f32_16x16x32_bf16 v[16:19], v[168:171], v[226:229], v[16:19]
	v_mfma_f32_16x16x32_bf16 v[4:7], v[160:163], v[234:237], v[4:7]
	v_mfma_f32_16x16x32_bf16 v[0:3], v[168:171], v[234:237], v[0:3]
	v_mfma_f32_16x16x32_bf16 v[52:55], v[164:167], v[204:207], v[52:55]
	v_mfma_f32_16x16x32_bf16 v[48:51], v[172:175], v[204:207], v[48:51]
	v_mfma_f32_16x16x32_bf16 v[36:39], v[164:167], v[222:225], v[36:39]
	v_mfma_f32_16x16x32_bf16 v[32:35], v[172:175], v[222:225], v[32:35]
	v_mfma_f32_16x16x32_bf16 v[20:23], v[164:167], v[230:233], v[20:23]
	v_mfma_f32_16x16x32_bf16 v[16:19], v[172:175], v[230:233], v[16:19]
	v_mfma_f32_16x16x32_bf16 v[4:7], v[164:167], v[238:241], v[4:7]
	v_mfma_f32_16x16x32_bf16 v[0:3], v[172:175], v[238:241], v[0:3]
	s_setprio 0
	s_barrier
	s_add_i32 s60, s60, 2
	s_add_u32 vcc_lo, vcc_lo, 0x100
	s_addc_u32 vcc_hi, vcc_hi, 0
	s_add_u32 s55, s55, 0x100
	s_addc_u32 s61, s61, 0
	s_cmp_gt_u32 s60, 13


; #define PG8_STAGE(bufoff, gbase, voff) do { _Pragma("unroll") for (int _i = 0; _i < 2; ++_i) \
;         __builtin_amdgcn_global_load_lds((const unsigned*)((const char*)(gbase) + (voff)[_i]), (PG8_LAS unsigned*)(lds + (bufoff) + ldsw + _i * 8192), 16, 0, 0); } while (0)
; #define PG8_LDA(dst, b, h) do { _Pragma("unroll") for (int m = 0; m < 4; ++m) _Pragma("unroll") for (int k = 0; k < 2; ++k) dst[m][k] = *(const PG8_LAS bf16x8*)(lds + PG8_SA(b, h) + aoff + m * 2048 + k * 1024); } while (0)
; #define PG8_LDB(dst, b, h) do { _Pragma("unroll") for (int n = 0; n < 2; ++n) _Pragma("unroll") for (int k = 0; k < 2; ++k) dst[n][k] = *(const PG8_LAS bf16x8*)(lds + PG8_SB(b, h) + boff + n * 2048 + k * 1024); } while (0)
; #define PG8_MMA(ai, bj, At, Bt) do { __builtin_amdgcn_s_setprio(1); _Pragma("unroll") for (int m = 0; m < 4; ++m) _Pragma("unroll") for (int n = 0; n < 2; ++n) _Pragma("unroll") for (int k = 0; k < 2; ++k) \
;         acc[ai][bj][m][n] = __builtin_amdgcn_mfma_f32_16x16x32_bf16(Bt[n][k], At[m][k], acc[ai][bj][m][n], 0, 0, 0); __builtin_amdgcn_s_setprio(0); } while (0)
; #define PG8_WAIT_V(n) asm volatile("s_waitcnt vmcnt(" #n ")" ::: "memory")
; template <class Epi, class Sched, bool ALIGN_EPI = false, bool SP2 = false>
; __device__ __forceinline__ void gemm_phase(PG8_LAS unsigned char* lds, const Gemm g, const Sched& S, const Epi& E) {
;     ...
;         const char* nA = has_next ? (const char*)g.A + (size_t)nxt.pm * tstep : cA; const char* nB = has_next ? (const char*)g.Bt + (size_t)nxt.pn * tstep : cB;
;         for (int t = 0; t < nt; t += 2) {
;             const bool last = (t == nt - 2);
;             const char* a1 = cA + (size_t)(t + 1) * kstep;
;             const char* a2 = last ? nA : cA + (size_t)(t + 2) * kstep; const char* b2 = last ? nB : cB + (size_t)(t + 2) * kstep;
;             const char* a3 = a2 + kstep; const char* b3 = b2 + kstep;
;             if (last && has_next) S.a_ready(nxt);
;             if constexpr (SP2) {
;             PG8_LDB(B0, 0, 0); PG8_LDB(B1, 0, 1); PG8_SCHED; PG8_LDA(At, 0, 0); PG8_STAGE(PG8_SA(1, 1), a1 + hstep, voffA);
;             PG8_WAIT_V(8); PG8_WAIT_L(0); PG8_BAR; PG8_MMA(0, 0, At, B0); PG8_MMA(0, 1, At, B1); PG8_BAR; PG8_SCHED;
;             PG8_LDA(At, 0, 1); PG8_STAGE(PG8_SB(0, 0), b2, voffB); PG8_STAGE(PG8_SB(0, 1), b2 + hstep, voffB); PG8_STAGE(PG8_SA(0, 0), a2, voffA);
.LBB0_159:
	s_ashr_i32 s43, s42, 31
	s_lshl_b64 s[12:13], s[42:43], 19
	s_add_u32 s46, s18, s12
	s_addc_u32 s47, s19, s13
	s_and_b64 s[12:13], s[4:5], exec
	s_cselect_b32 s12, s47, s55
	s_cselect_b32 s13, s46, s54
	s_ashr_i32 s39, s38, 31
	s_lshl_b64 s[50:51], s[38:39], 19
	s_add_u32 s50, s15, s50
	s_addc_u32 s51, s16, s51
	s_and_b64 s[56:57], s[4:5], exec
	s_cselect_b32 s39, s51, s41
	s_cselect_b32 s43, s50, s40
	s_add_u32 s54, s54, 0x40080
	s_addc_u32 s55, s55, 0
	s_add_u32 s65, s40, 0x100
	s_addc_u32 s61, s41, 0
	s_mov_b32 s60, -2
	v_mov_b32_e32 v129, v0
	s_add_u32 s40, s54, 0xfffc0080
	s_addc_u32 s41, s55, -1
	s_add_i32 s66, 0, 0x10000
	s_cmp_eq_u32 s60, 12
	s_cselect_b32 s57, s12, s41
	s_cselect_b32 s56, s13, s40
	v_add_u32_e32 v139, s66, v150
	s_cselect_b32 s41, s39, s61
	s_cselect_b32 s40, s43, s65
	s_add_i32 s68, 0, 0x14000
	ds_read_b128 v[144:147], v139
	ds_read_b128 v[154:157], v139 offset:1024
	ds_read_b128 v[158:161], v139 offset:2048
	ds_read_b128 v[162:165], v139 offset:3072
	v_add_u32_e32 v139, s68, v150
	ds_read_b128 v[166:169], v139
	ds_read_b128 v[170:173], v139 offset:1024
	ds_read_b128 v[174:177], v139 offset:2048
	ds_read_b128 v[178:181], v139 offset:3072
	v_lshl_add_u64 v[148:149], s[54:55], 0, v[134:135]
	s_add_i32 m0, s21, 0xc000
	ds_read_b128 v[200:203], v152
	ds_read_b128 v[204:207], v152 offset:1024
	ds_read_b128 v[208:211], v152 offset:2048
	ds_read_b128 v[222:225], v152 offset:3072
	ds_read_b128 v[226:229], v152 offset:4096
	ds_read_b128 v[230:233], v152 offset:5120
	ds_read_b128 v[234:237], v152 offset:6144
	ds_read_b128 v[238:241], v152 offset:7168
	global_load_lds_dwordx4 v[148:149], off
	v_lshl_add_u64 v[148:149], s[54:55], 0, v[136:137]
	s_add_i32 m0, s21, 0xe000
	s_nop 0
	global_load_lds_dwordx4 v[148:149], off
	s_waitcnt vmcnt(8)
	s_waitcnt lgkmcnt(0)
	s_barrier
	s_setprio 1
	s_waitcnt lgkmcnt(0)
	v_mfma_f32_16x16x32_bf16 v[126:129], v[144:147], v[200:203], 0
	v_mfma_f32_16x16x32_bf16 v[92:95], v[158:161], v[200:203], 0
	v_mfma_f32_16x16x32_bf16 v[122:125], v[144:147], v[208:211], 0
	v_mfma_f32_16x16x32_bf16 v[88:91], v[158:161], v[208:211], 0
	v_mfma_f32_16x16x32_bf16 v[118:121], v[144:147], v[226:229], 0
	v_mfma_f32_16x16x32_bf16 v[84:87], v[158:161], v[226:229], 0
	v_mfma_f32_16x16x32_bf16 v[114:117], v[144:147], v[234:237], 0
	v_mfma_f32_16x16x32_bf16 v[80:83], v[158:161], v[234:237], 0
	v_mfma_f32_16x16x32_bf16 v[126:129], v[154:157], v[204:207], v[126:129]
	v_mfma_f32_16x16x32_bf16 v[92:95], v[162:165], v[204:207], v[92:95]
	v_mfma_f32_16x16x32_bf16 v[122:125], v[154:157], v[222:225], v[122:125]
	v_mfma_f32_16x16x32_bf16 v[88:91], v[162:165], v[222:225], v[88:91]
	v_mfma_f32_16x16x32_bf16 v[118:121], v[154:157], v[230:233], v[118:121]
	v_mfma_f32_16x16x32_bf16 v[84:87], v[162:165], v[230:233], v[84:87]
	v_mfma_f32_16x16x32_bf16 v[114:117], v[154:157], v[238:241], v[114:117]
	v_mfma_f32_16x16x32_bf16 v[80:83], v[162:165], v[238:241], v[80:83]
	s_setprio 0
	s_setprio 1
	v_mfma_f32_16x16x32_bf16 v[60:63], v[166:169], v[200:203], 0
	v_mfma_f32_16x16x32_bf16 v[28:31], v[174:177], v[200:203], 0
	v_mfma_f32_16x16x32_bf16 v[56:59], v[166:169], v[208:211], 0
	v_mfma_f32_16x16x32_bf16 v[24:27], v[174:177], v[208:211], 0
	v_mfma_f32_16x16x32_bf16 v[52:55], v[166:169], v[226:229], 0
	v_mfma_f32_16x16x32_bf16 v[20:23], v[174:177], v[226:229], 0
	v_mfma_f32_16x16x32_bf16 v[48:51], v[166:169], v[234:237], 0
	v_mfma_f32_16x16x32_bf16 v[16:19], v[174:177], v[234:237], 0
	v_mfma_f32_16x16x32_bf16 v[60:63], v[170:173], v[204:207], v[60:63]
	v_mfma_f32_16x16x32_bf16 v[28:31], v[178:181], v[204:207], v[28:31]
	v_mfma_f32_16x16x32_bf16 v[56:59], v[170:173], v[222:225], v[56:59]
	v_mfma_f32_16x16x32_bf16 v[24:27], v[178:181], v[222:225], v[24:27]
	v_mfma_f32_16x16x32_bf16 v[52:55], v[170:173], v[230:233], v[52:55]
	v_mfma_f32_16x16x32_bf16 v[20:23], v[178:181], v[230:233], v[20:23]
	v_mfma_f32_16x16x32_bf16 v[48:51], v[170:173], v[238:241], v[48:51]
	v_mfma_f32_16x16x32_bf16 v[16:19], v[178:181], v[238:241], v[16:19]
	s_setprio 0
	s_barrier
	s_add_i32 s66, s66, s20
	v_lshl_add_u64 v[148:149], s[40:41], 0, v[130:131]
	s_mov_b32 m0, s66
	ds_read_b128 v[200:203], v152 offset:16384
	ds_read_b128 v[204:207], v152 offset:17408
	ds_read_b128 v[208:211], v152 offset:18432
	ds_read_b128 v[222:225], v152 offset:19456
	ds_read_b128 v[226:229], v152 offset:20480
	ds_read_b128 v[230:233], v152 offset:21504
	ds_read_b128 v[234:237], v152 offset:22528
	ds_read_b128 v[238:241], v152 offset:23552
	global_load_lds_dwordx4 v[148:149], off
	s_add_i32 m0, s66, 0x2000
	s_add_u32 s66, s40, 0x40000
	v_lshl_add_u64 v[184:185], s[40:41], 0, v[132:133]
	s_addc_u32 s67, s41, 0
	s_add_i32 s68, s68, s20
	global_load_lds_dwordx4 v[184:185], off
	v_lshl_add_u64 v[186:187], s[66:67], 0, v[130:131]
	s_mov_b32 m0, s68
	v_lshl_add_u64 v[212:213], s[56:57], 0, v[132:133]
	global_load_lds_dwordx4 v[186:187], off
	v_lshl_add_u64 v[186:187], s[66:67], 0, v[132:133]
	s_add_i32 m0, s68, 0x2000
	s_nop 0
	global_load_lds_dwordx4 v[186:187], off
	v_lshl_add_u64 v[186:187], s[56:57], 0, v[130:131]
	s_mov_b32 m0, s21
	s_nop 0
	global_load_lds_dwordx4 v[186:187], off
	s_mov_b32 m0, s22
	s_nop 0
	global_load_lds_dwordx4 v[212:213], off
	s_waitcnt vmcnt(8)
	s_waitcnt lgkmcnt(0)
	s_barrier
; #define PG8_STAGE(bufoff, gbase, voff) do { _Pragma("unroll") for (int _i = 0; _i < 2; ++_i) \
;         __builtin_amdgcn_global_load_lds((const unsigned*)((const char*)(gbase) + (voff)[_i]), (PG8_LAS unsigned*)(lds + (bufoff) + ldsw + _i * 8192), 16, 0, 0); } while (0)
; #define PG8_LDA(dst, b, h) do { _Pragma("unroll") for (int m = 0; m < 4; ++m) _Pragma("unroll") for (int k = 0; k < 2; ++k) dst[m][k] = *(const PG8_LAS bf16x8*)(lds + PG8_SA(b, h) + aoff + m * 2048 + k * 1024); } while (0)
; #define PG8_LDB(dst, b, h) do { _Pragma("unroll") for (int n = 0; n < 2; ++n) _Pragma("unroll") for (int k = 0; k < 2; ++k) dst[n][k] = *(const PG8_LAS bf16x8*)(lds + PG8_SB(b, h) + boff + n * 2048 + k * 1024); } while (0)
; #define PG8_MMA(ai, bj, At, Bt) do { __builtin_amdgcn_s_setprio(1); _Pragma("unroll") for (int m = 0; m < 4; ++m) _Pragma("unroll") for (int n = 0; n < 2; ++n) _Pragma("unroll") for (int k = 0; k < 2; ++k) \
;         acc[ai][bj][m][n] = __builtin_amdgcn_mfma_f32_16x16x32_bf16(Bt[n][k], At[m][k], acc[ai][bj][m][n], 0, 0, 0); __builtin_amdgcn_s_setprio(0); } while (0)
; #define PG8_WAIT_V(n) asm volatile("s_waitcnt vmcnt(" #n ")" ::: "memory")
; #define PG8_WAIT_L(n) asm volatile("s_waitcnt lgkmcnt(" #n ")" ::: "memory")
; #define PG8_BAR __builtin_amdgcn_s_barrier()
; #define PG8_SCHED __builtin_amdgcn_sched_barrier(0)
; template <class Epi, class Sched, bool ALIGN_EPI = false, bool SP2 = false>
; __device__ __forceinline__ void gemm_phase(PG8_LAS unsigned char* lds, const Gemm g, const Sched& S, const Epi& E) {
;     ...
;             PG8_WAIT_V(8); PG8_WAIT_L(0); PG8_BAR; PG8_MMA(1, 0, At, B0); PG8_MMA(1, 1, At, B1); PG8_BAR; PG8_SCHED;
;             PG8_LDB(B0, 1, 0); PG8_LDB(B1, 1, 1); PG8_SCHED; PG8_LDA(At, 1, 0); PG8_STAGE(PG8_SA(0, 1), a2 + hstep, voffA);
;             PG8_WAIT_V(8); PG8_WAIT_L(0); PG8_BAR; PG8_MMA(0, 0, At, B0); PG8_MMA(0, 1, At, B1); PG8_BAR; PG8_SCHED;
	s_setprio 1
	s_waitcnt lgkmcnt(0)
	v_mfma_f32_16x16x32_bf16 v[108:111], v[144:147], v[200:203], 0
	v_mfma_f32_16x16x32_bf16 v[76:79], v[158:161], v[200:203], 0
	v_mfma_f32_16x16x32_bf16 v[104:107], v[144:147], v[208:211], 0
	v_mfma_f32_16x16x32_bf16 v[72:75], v[158:161], v[208:211], 0
	v_mfma_f32_16x16x32_bf16 v[100:103], v[144:147], v[226:229], 0
	v_mfma_f32_16x16x32_bf16 v[68:71], v[158:161], v[226:229], 0
	v_mfma_f32_16x16x32_bf16 v[96:99], v[144:147], v[234:237], 0
	v_mfma_f32_16x16x32_bf16 v[64:67], v[158:161], v[234:237], 0
	v_mfma_f32_16x16x32_bf16 v[108:111], v[154:157], v[204:207], v[108:111]
	v_mfma_f32_16x16x32_bf16 v[76:79], v[162:165], v[204:207], v[76:79]
	v_mfma_f32_16x16x32_bf16 v[104:107], v[154:157], v[222:225], v[104:107]
	v_mfma_f32_16x16x32_bf16 v[72:75], v[162:165], v[222:225], v[72:75]
	v_mfma_f32_16x16x32_bf16 v[100:103], v[154:157], v[230:233], v[100:103]
	v_mfma_f32_16x16x32_bf16 v[68:71], v[162:165], v[230:233], v[68:71]
	v_mfma_f32_16x16x32_bf16 v[96:99], v[154:157], v[238:241], v[96:99]
	v_mfma_f32_16x16x32_bf16 v[64:67], v[162:165], v[238:241], v[64:67]
	s_setprio 0
	s_setprio 1
	v_mfma_f32_16x16x32_bf16 v[44:47], v[166:169], v[200:203], 0
	v_mfma_f32_16x16x32_bf16 v[12:15], v[174:177], v[200:203], 0
	v_mfma_f32_16x16x32_bf16 v[40:43], v[166:169], v[208:211], 0
	v_mfma_f32_16x16x32_bf16 v[8:11], v[174:177], v[208:211], 0
	v_mfma_f32_16x16x32_bf16 v[36:39], v[166:169], v[226:229], 0
	v_mfma_f32_16x16x32_bf16 v[4:7], v[174:177], v[226:229], 0
	v_mfma_f32_16x16x32_bf16 v[32:35], v[166:169], v[234:237], 0
	v_mfma_f32_16x16x32_bf16 v[0:3], v[174:177], v[234:237], 0
	v_mfma_f32_16x16x32_bf16 v[44:47], v[170:173], v[204:207], v[44:47]
	v_mfma_f32_16x16x32_bf16 v[12:15], v[178:181], v[204:207], v[12:15]
	v_mfma_f32_16x16x32_bf16 v[40:43], v[170:173], v[222:225], v[40:43]
	v_mfma_f32_16x16x32_bf16 v[8:11], v[178:181], v[222:225], v[8:11]
	v_mfma_f32_16x16x32_bf16 v[36:39], v[170:173], v[230:233], v[36:39]
	v_mfma_f32_16x16x32_bf16 v[4:7], v[178:181], v[230:233], v[4:7]
	v_mfma_f32_16x16x32_bf16 v[32:35], v[170:173], v[238:241], v[32:35]
	v_mfma_f32_16x16x32_bf16 v[0:3], v[178:181], v[238:241], v[0:3]
	s_setprio 0
	s_barrier
	s_add_i32 s66, 0, 0x18000
	v_add_u32_e32 v139, s66, v150
	s_add_i32 s67, 0, 0x1c000
	ds_read_b128 v[144:147], v139
	ds_read_b128 v[154:157], v139 offset:1024
	ds_read_b128 v[158:161], v139 offset:2048
	ds_read_b128 v[162:165], v139 offset:3072
	v_add_u32_e32 v139, s67, v150
	ds_read_b128 v[166:169], v139
	ds_read_b128 v[170:173], v139 offset:1024
	ds_read_b128 v[174:177], v139 offset:2048
	ds_read_b128 v[178:181], v139 offset:3072
	s_add_u32 s56, s56, 0x40000
	s_addc_u32 s57, s57, 0
	s_mov_b32 m0, s23
	v_lshl_add_u64 v[242:243], s[56:57], 0, v[130:131]
	ds_read_b128 v[200:203], v152 offset:32768
	ds_read_b128 v[204:207], v152 offset:33792
	ds_read_b128 v[208:211], v152 offset:34816
	ds_read_b128 v[222:225], v152 offset:35840
	ds_read_b128 v[226:229], v152 offset:36864
	ds_read_b128 v[230:233], v152 offset:37888
	ds_read_b128 v[234:237], v152 offset:38912
	ds_read_b128 v[238:241], v152 offset:39936
	global_load_lds_dwordx4 v[242:243], off
	v_lshl_add_u64 v[242:243], s[56:57], 0, v[132:133]
	s_mov_b32 m0, s24
	s_nop 0
	global_load_lds_dwordx4 v[242:243], off
	s_waitcnt vmcnt(8)
	s_waitcnt lgkmcnt(0)
	s_barrier
	s_setprio 1
	s_waitcnt lgkmcnt(0)
	v_mfma_f32_16x16x32_bf16 v[126:129], v[144:147], v[200:203], v[126:129]
	v_mfma_f32_16x16x32_bf16 v[92:95], v[158:161], v[200:203], v[92:95]
	v_mfma_f32_16x16x32_bf16 v[122:125], v[144:147], v[208:211], v[122:125]
	v_mfma_f32_16x16x32_bf16 v[88:91], v[158:161], v[208:211], v[88:91]
	v_mfma_f32_16x16x32_bf16 v[118:121], v[144:147], v[226:229], v[118:121]
	v_mfma_f32_16x16x32_bf16 v[84:87], v[158:161], v[226:229], v[84:87]
	v_mfma_f32_16x16x32_bf16 v[114:117], v[144:147], v[234:237], v[114:117]
	v_mfma_f32_16x16x32_bf16 v[80:83], v[158:161], v[234:237], v[80:83]
	v_mfma_f32_16x16x32_bf16 v[126:129], v[154:157], v[204:207], v[126:129]
	v_mfma_f32_16x16x32_bf16 v[92:95], v[162:165], v[204:207], v[92:95]
	v_mfma_f32_16x16x32_bf16 v[122:125], v[154:157], v[222:225], v[122:125]
	v_mfma_f32_16x16x32_bf16 v[88:91], v[162:165], v[222:225], v[88:91]
	v_mfma_f32_16x16x32_bf16 v[118:121], v[154:157], v[230:233], v[118:121]
	v_mfma_f32_16x16x32_bf16 v[84:87], v[162:165], v[230:233], v[84:87]
	v_mfma_f32_16x16x32_bf16 v[114:117], v[154:157], v[238:241], v[114:117]
	v_mfma_f32_16x16x32_bf16 v[80:83], v[162:165], v[238:241], v[80:83]
	s_setprio 0
	s_setprio 1
	v_mfma_f32_16x16x32_bf16 v[60:63], v[166:169], v[200:203], v[60:63]
	v_mfma_f32_16x16x32_bf16 v[28:31], v[174:177], v[200:203], v[28:31]
	v_mfma_f32_16x16x32_bf16 v[56:59], v[166:169], v[208:211], v[56:59]
	v_mfma_f32_16x16x32_bf16 v[24:27], v[174:177], v[208:211], v[24:27]
	v_mfma_f32_16x16x32_bf16 v[52:55], v[166:169], v[226:229], v[52:55]
	v_mfma_f32_16x16x32_bf16 v[20:23], v[174:177], v[226:229], v[20:23]
	v_mfma_f32_16x16x32_bf16 v[48:51], v[166:169], v[234:237], v[48:51]
	v_mfma_f32_16x16x32_bf16 v[16:19], v[174:177], v[234:237], v[16:19]
	v_mfma_f32_16x16x32_bf16 v[60:63], v[170:173], v[204:207], v[60:63]
	v_mfma_f32_16x16x32_bf16 v[28:31], v[178:181], v[204:207], v[28:31]
	v_mfma_f32_16x16x32_bf16 v[56:59], v[170:173], v[222:225], v[56:59]
	v_mfma_f32_16x16x32_bf16 v[24:27], v[178:181], v[222:225], v[24:27]
	v_mfma_f32_16x16x32_bf16 v[52:55], v[170:173], v[230:233], v[52:55]
	v_mfma_f32_16x16x32_bf16 v[20:23], v[178:181], v[230:233], v[20:23]
	v_mfma_f32_16x16x32_bf16 v[48:51], v[170:173], v[238:241], v[48:51]
	v_mfma_f32_16x16x32_bf16 v[16:19], v[178:181], v[238:241], v[16:19]
	s_setprio 0
	s_barrier
; #define PG8_STAGE(bufoff, gbase, voff) do { _Pragma("unroll") for (int _i = 0; _i < 2; ++_i) \
;         __builtin_amdgcn_global_load_lds((const unsigned*)((const char*)(gbase) + (voff)[_i]), (PG8_LAS unsigned*)(lds + (bufoff) + ldsw + _i * 8192), 16, 0, 0); } while (0)
; #define PG8_LDA(dst, b, h) do { _Pragma("unroll") for (int m = 0; m < 4; ++m) _Pragma("unroll") for (int k = 0; k < 2; ++k) dst[m][k] = *(const PG8_LAS bf16x8*)(lds + PG8_SA(b, h) + aoff + m * 2048 + k * 1024); } while (0)
; #define PG8_MMA(ai, bj, At, Bt) do { __builtin_amdgcn_s_setprio(1); _Pragma("unroll") for (int m = 0; m < 4; ++m) _Pragma("unroll") for (int n = 0; n < 2; ++n) _Pragma("unroll") for (int k = 0; k < 2; ++k) \
;         acc[ai][bj][m][n] = __builtin_amdgcn_mfma_f32_16x16x32_bf16(Bt[n][k], At[m][k], acc[ai][bj][m][n], 0, 0, 0); __builtin_amdgcn_s_setprio(0); } while (0)
; #define PG8_WAIT_V(n) asm volatile("s_waitcnt vmcnt(" #n ")" ::: "memory")
; #define PG8_WAIT_L(n) asm volatile("s_waitcnt lgkmcnt(" #n ")" ::: "memory")
; #define PG8_BAR __builtin_amdgcn_s_barrier()
; #define PG8_SCHED __builtin_amdgcn_sched_barrier(0)
; template <class Epi, class Sched, bool ALIGN_EPI = false, bool SP2 = false>
; __device__ __forceinline__ void gemm_phase(PG8_LAS unsigned char* lds, const Gemm g, const Sched& S, const Epi& E) {
;     ...
;             PG8_LDA(At, 1, 1); PG8_STAGE(PG8_SB(1, 0), b3, voffB); PG8_STAGE(PG8_SB(1, 1), b3 + hstep, voffB); PG8_STAGE(PG8_SA(1, 0), a3, voffA);
;             PG8_WAIT_V(8); PG8_WAIT_L(0); PG8_BAR; PG8_MMA(1, 0, At, B0); PG8_MMA(1, 1, At, B1); PG8_BAR; PG8_SCHED;
	s_add_i32 s56, s66, s20
	v_lshl_add_u64 v[148:149], v[148:149], 0, s[36:37]
	s_mov_b32 m0, s56
	ds_read_b128 v[200:203], v152 offset:49152
	ds_read_b128 v[204:207], v152 offset:50176
	ds_read_b128 v[208:211], v152 offset:51200
	ds_read_b128 v[222:225], v152 offset:52224
	ds_read_b128 v[226:229], v152 offset:53248
	ds_read_b128 v[230:233], v152 offset:54272
	ds_read_b128 v[234:237], v152 offset:55296
	ds_read_b128 v[238:241], v152 offset:56320
	global_load_lds_dwordx4 v[148:149], off
	s_add_i32 m0, s56, 0x2000
	s_add_u32 s40, s40, 0x40080
	v_lshl_add_u64 v[148:149], v[184:185], 0, s[36:37]
	s_addc_u32 s41, s41, 0
	s_add_i32 s56, s67, s20
	global_load_lds_dwordx4 v[148:149], off
	v_lshl_add_u64 v[148:149], s[40:41], 0, v[130:131]
	s_mov_b32 m0, s56
	s_nop 0
	global_load_lds_dwordx4 v[148:149], off
	v_lshl_add_u64 v[148:149], s[40:41], 0, v[132:133]
	s_add_i32 m0, s56, 0x2000
	s_nop 0
	global_load_lds_dwordx4 v[148:149], off
	v_lshl_add_u64 v[148:149], v[186:187], 0, s[36:37]
	s_mov_b32 m0, s45
	s_nop 0
	global_load_lds_dwordx4 v[148:149], off
	v_lshl_add_u64 v[148:149], v[212:213], 0, s[36:37]
	s_mov_b32 m0, s53
	s_nop 0
	global_load_lds_dwordx4 v[148:149], off
	s_waitcnt vmcnt(8)
	s_waitcnt lgkmcnt(0)
	s_barrier
	s_setprio 1
	s_waitcnt lgkmcnt(0)
	v_mfma_f32_16x16x32_bf16 v[108:111], v[144:147], v[200:203], v[108:111]
	v_mfma_f32_16x16x32_bf16 v[76:79], v[158:161], v[200:203], v[76:79]
	v_mfma_f32_16x16x32_bf16 v[104:107], v[144:147], v[208:211], v[104:107]
	v_mfma_f32_16x16x32_bf16 v[72:75], v[158:161], v[208:211], v[72:75]
	v_mfma_f32_16x16x32_bf16 v[100:103], v[144:147], v[226:229], v[100:103]
	v_mfma_f32_16x16x32_bf16 v[68:71], v[158:161], v[226:229], v[68:71]
	v_mfma_f32_16x16x32_bf16 v[96:99], v[144:147], v[234:237], v[96:99]
	v_mfma_f32_16x16x32_bf16 v[64:67], v[158:161], v[234:237], v[64:67]
	v_mfma_f32_16x16x32_bf16 v[108:111], v[154:157], v[204:207], v[108:111]
	v_mfma_f32_16x16x32_bf16 v[76:79], v[162:165], v[204:207], v[76:79]
	v_mfma_f32_16x16x32_bf16 v[104:107], v[154:157], v[222:225], v[104:107]
	v_mfma_f32_16x16x32_bf16 v[72:75], v[162:165], v[222:225], v[72:75]
	v_mfma_f32_16x16x32_bf16 v[100:103], v[154:157], v[230:233], v[100:103]
	v_mfma_f32_16x16x32_bf16 v[68:71], v[162:165], v[230:233], v[68:71]
	v_mfma_f32_16x16x32_bf16 v[96:99], v[154:157], v[238:241], v[96:99]
	v_mfma_f32_16x16x32_bf16 v[64:67], v[162:165], v[238:241], v[64:67]
	s_setprio 0
	s_setprio 1
	v_mfma_f32_16x16x32_bf16 v[44:47], v[166:169], v[200:203], v[44:47]
	v_mfma_f32_16x16x32_bf16 v[12:15], v[174:177], v[200:203], v[12:15]
	v_mfma_f32_16x16x32_bf16 v[40:43], v[166:169], v[208:211], v[40:43]
	v_mfma_f32_16x16x32_bf16 v[8:11], v[174:177], v[208:211], v[8:11]
	v_mfma_f32_16x16x32_bf16 v[36:39], v[166:169], v[226:229], v[36:39]
	v_mfma_f32_16x16x32_bf16 v[4:7], v[174:177], v[226:229], v[4:7]
	v_mfma_f32_16x16x32_bf16 v[32:35], v[166:169], v[234:237], v[32:35]
	v_mfma_f32_16x16x32_bf16 v[0:3], v[174:177], v[234:237], v[0:3]
	v_mfma_f32_16x16x32_bf16 v[44:47], v[170:173], v[204:207], v[44:47]
	v_mfma_f32_16x16x32_bf16 v[12:15], v[178:181], v[204:207], v[12:15]
	v_mfma_f32_16x16x32_bf16 v[40:43], v[170:173], v[222:225], v[40:43]
	v_mfma_f32_16x16x32_bf16 v[8:11], v[178:181], v[222:225], v[8:11]
	v_mfma_f32_16x16x32_bf16 v[36:39], v[170:173], v[230:233], v[36:39]
	v_mfma_f32_16x16x32_bf16 v[4:7], v[178:181], v[230:233], v[4:7]
	v_mfma_f32_16x16x32_bf16 v[32:35], v[170:173], v[238:241], v[32:35]
	v_mfma_f32_16x16x32_bf16 v[0:3], v[178:181], v[238:241], v[0:3]
	s_setprio 0
	s_barrier
	s_add_i32 s60, s60, 2
	s_add_u32 s54, s54, 0x100
	s_addc_u32 s55, s55, 0
	s_add_u32 s65, s65, 0x100
	s_addc_u32 s61, s61, 0
	s_cmp_gt_u32 s60, 13


; #define PG8_STAGE(bufoff, gbase, voff) do { _Pragma("unroll") for (int _i = 0; _i < 2; ++_i) \
;         __builtin_amdgcn_global_load_lds((const unsigned*)((const char*)(gbase) + (voff)[_i]), (PG8_LAS unsigned*)(lds + (bufoff) + ldsw + _i * 8192), 16, 0, 0); } while (0)
; #define PG8_LDA(dst, b, h) do { _Pragma("unroll") for (int m = 0; m < 4; ++m) _Pragma("unroll") for (int k = 0; k < 2; ++k) dst[m][k] = *(const PG8_LAS bf16x8*)(lds + PG8_SA(b, h) + aoff + m * 2048 + k * 1024); } while (0)
; #define PG8_LDB(dst, b, h) do { _Pragma("unroll") for (int n = 0; n < 2; ++n) _Pragma("unroll") for (int k = 0; k < 2; ++k) dst[n][k] = *(const PG8_LAS bf16x8*)(lds + PG8_SB(b, h) + boff + n * 2048 + k * 1024); } while (0)
; #define PG8_MMA(ai, bj, At, Bt) do { __builtin_amdgcn_s_setprio(1); _Pragma("unroll") for (int m = 0; m < 4; ++m) _Pragma("unroll") for (int n = 0; n < 2; ++n) _Pragma("unroll") for (int k = 0; k < 2; ++k) \
;         acc[ai][bj][m][n] = __builtin_amdgcn_mfma_f32_16x16x32_bf16(Bt[n][k], At[m][k], acc[ai][bj][m][n], 0, 0, 0); __builtin_amdgcn_s_setprio(0); } while (0)
; #define PG8_WAIT_V(n) asm volatile("s_waitcnt vmcnt(" #n ")" ::: "memory")
; template <class Epi, class Sched, bool ALIGN_EPI = false, bool SP2 = false>
; __device__ __forceinline__ void gemm_phase(PG8_LAS unsigned char* lds, const Gemm g, const Sched& S, const Epi& E) {
;     ...
;         const char* nA = has_next ? (const char*)g.A + (size_t)nxt.pm * tstep : cA; const char* nB = has_next ? (const char*)g.Bt + (size_t)nxt.pn * tstep : cB;
;         for (int t = 0; t < nt; t += 2) {
;             const bool last = (t == nt - 2);
;             const char* a1 = cA + (size_t)(t + 1) * kstep;
;             const char* a2 = last ? nA : cA + (size_t)(t + 2) * kstep; const char* b2 = last ? nB : cB + (size_t)(t + 2) * kstep;
;             const char* a3 = a2 + kstep; const char* b3 = b2 + kstep;
;             if (last && has_next) S.a_ready(nxt);
;             if constexpr (SP2) {
;             PG8_LDB(B0, 0, 0); PG8_LDB(B1, 0, 1); PG8_SCHED; PG8_LDA(At, 0, 0); PG8_STAGE(PG8_SA(1, 1), a1 + hstep, voffA);
;             PG8_WAIT_V(8); PG8_WAIT_L(0); PG8_BAR; PG8_MMA(0, 0, At, B0); PG8_MMA(0, 1, At, B1); PG8_BAR; PG8_SCHED;
;             PG8_LDA(At, 0, 1); PG8_STAGE(PG8_SB(0, 0), b2, voffB); PG8_STAGE(PG8_SB(0, 1), b2 + hstep, voffB); PG8_STAGE(PG8_SA(0, 0), a2, voffA);
.LBB0_510:
	s_ashr_i32 s49, s48, 31
	s_lshl_b64 s[12:13], s[48:49], 19
	s_add_u32 s50, s15, s12
	s_addc_u32 s51, s16, s13
	s_and_b64 s[12:13], s[6:7], exec
	s_cselect_b32 s12, s51, s1
	s_cselect_b32 s13, s50, s0
	s_ashr_i32 s47, s46, 31
	s_lshl_b64 s[54:55], s[46:47], 19
	s_add_u32 s54, s17, s54
	s_addc_u32 s55, s18, s55
	s_and_b64 s[56:57], s[6:7], exec
	s_cselect_b32 s47, s55, s41
	s_cselect_b32 s49, s54, s40
	s_add_u32 s58, s40, 0x100
	s_addc_u32 s61, s41, 0
	s_mov_b32 s60, -2
	s_waitcnt lgkmcnt(0)
	v_mov_b32_e32 v129, v0
	s_add_u32 s40, s0, 0x100
	s_addc_u32 s41, s1, 0
	s_add_i32 s63, 0, 0x10000
	s_cmp_eq_u32 s60, 12
	s_cselect_b32 vcc_hi, s12, s41
	s_cselect_b32 vcc_lo, s13, s40
	s_cselect_b32 s57, s47, s61
	s_cselect_b32 s56, s49, s58
	s_add_i32 s65, 0, 0x14000
	v_add_u32_e32 v148, s63, v179
	v_add_u32_e32 v164, s65, v179
	ds_read_b128 v[136:139], v148
	ds_read_b128 v[140:143], v148 offset:1024
	ds_read_b128 v[144:147], v148 offset:2048
	ds_read_b128 v[148:151], v148 offset:3072
	ds_read_b128 v[152:155], v164
	ds_read_b128 v[156:159], v164 offset:1024
	ds_read_b128 v[160:163], v164 offset:2048
	ds_read_b128 v[164:167], v164 offset:3072
	v_lshl_add_u64 v[176:177], s[0:1], 0, v[132:133]
	s_add_i32 m0, s20, 0xc000
	ds_read_b128 v[168:171], v181
	ds_read_b128 v[172:175], v181 offset:1024
	ds_read_b128 v[184:187], v181 offset:2048
	ds_read_b128 v[200:203], v181 offset:3072
	ds_read_b128 v[204:207], v181 offset:4096
	ds_read_b128 v[208:211], v181 offset:5120
	ds_read_b128 v[224:227], v181 offset:6144
	ds_read_b128 v[228:231], v181 offset:7168
	global_load_lds_dwordx4 v[176:177], off
	v_lshl_add_u64 v[176:177], s[0:1], 0, v[134:135]
	s_add_i32 m0, s20, 0xe000
	s_nop 0
	global_load_lds_dwordx4 v[176:177], off
	s_waitcnt vmcnt(8)
	s_waitcnt lgkmcnt(0)
	s_barrier
	s_setprio 1
	s_waitcnt lgkmcnt(0)
	v_mfma_f32_16x16x32_bf16 v[126:129], v[136:139], v[168:171], 0
	v_mfma_f32_16x16x32_bf16 v[122:125], v[144:147], v[168:171], 0
	v_mfma_f32_16x16x32_bf16 v[108:111], v[136:139], v[184:187], 0
	v_mfma_f32_16x16x32_bf16 v[104:107], v[144:147], v[184:187], 0
	v_mfma_f32_16x16x32_bf16 v[92:95], v[136:139], v[204:207], 0
	v_mfma_f32_16x16x32_bf16 v[88:91], v[144:147], v[204:207], 0
	v_mfma_f32_16x16x32_bf16 v[76:79], v[136:139], v[224:227], 0
	v_mfma_f32_16x16x32_bf16 v[72:75], v[144:147], v[224:227], 0
	v_mfma_f32_16x16x32_bf16 v[126:129], v[140:143], v[172:175], v[126:129]
	v_mfma_f32_16x16x32_bf16 v[122:125], v[148:151], v[172:175], v[122:125]
	v_mfma_f32_16x16x32_bf16 v[108:111], v[140:143], v[200:203], v[108:111]
	v_mfma_f32_16x16x32_bf16 v[104:107], v[148:151], v[200:203], v[104:107]
	v_mfma_f32_16x16x32_bf16 v[92:95], v[140:143], v[208:211], v[92:95]
	v_mfma_f32_16x16x32_bf16 v[88:91], v[148:151], v[208:211], v[88:91]
	v_mfma_f32_16x16x32_bf16 v[76:79], v[140:143], v[228:231], v[76:79]
	v_mfma_f32_16x16x32_bf16 v[72:75], v[148:151], v[228:231], v[72:75]
	s_setprio 0
	s_setprio 1
	v_mfma_f32_16x16x32_bf16 v[118:121], v[152:155], v[168:171], 0
	v_mfma_f32_16x16x32_bf16 v[114:117], v[160:163], v[168:171], 0
	v_mfma_f32_16x16x32_bf16 v[100:103], v[152:155], v[184:187], 0
	v_mfma_f32_16x16x32_bf16 v[96:99], v[160:163], v[184:187], 0
	v_mfma_f32_16x16x32_bf16 v[84:87], v[152:155], v[204:207], 0
	v_mfma_f32_16x16x32_bf16 v[80:83], v[160:163], v[204:207], 0
	v_mfma_f32_16x16x32_bf16 v[68:71], v[152:155], v[224:227], 0
	v_mfma_f32_16x16x32_bf16 v[64:67], v[160:163], v[224:227], 0
	v_mfma_f32_16x16x32_bf16 v[118:121], v[156:159], v[172:175], v[118:121]
	v_mfma_f32_16x16x32_bf16 v[114:117], v[164:167], v[172:175], v[114:117]
	v_mfma_f32_16x16x32_bf16 v[100:103], v[156:159], v[200:203], v[100:103]
	v_mfma_f32_16x16x32_bf16 v[96:99], v[164:167], v[200:203], v[96:99]
	v_mfma_f32_16x16x32_bf16 v[84:87], v[156:159], v[208:211], v[84:87]
	v_mfma_f32_16x16x32_bf16 v[80:83], v[164:167], v[208:211], v[80:83]
	v_mfma_f32_16x16x32_bf16 v[68:71], v[156:159], v[228:231], v[68:71]
	v_mfma_f32_16x16x32_bf16 v[64:67], v[164:167], v[228:231], v[64:67]
	s_setprio 0
	s_barrier
	s_add_i32 s0, s63, s19
	v_lshl_add_u64 v[176:177], s[56:57], 0, v[112:113]
	s_mov_b32 m0, s0
	ds_read_b128 v[168:171], v181 offset:16384
	ds_read_b128 v[172:175], v181 offset:17408
	ds_read_b128 v[184:187], v181 offset:18432
	ds_read_b128 v[200:203], v181 offset:19456
	ds_read_b128 v[204:207], v181 offset:20480
	ds_read_b128 v[208:211], v181 offset:21504
	ds_read_b128 v[224:227], v181 offset:22528
	ds_read_b128 v[228:231], v181 offset:23552
	global_load_lds_dwordx4 v[176:177], off
	s_add_i32 m0, s0, 0x2000
	s_add_u32 s0, s56, 0x40000
	v_lshl_add_u64 v[212:213], s[56:57], 0, v[130:131]
	s_addc_u32 s1, s57, 0
	s_add_i32 s63, s65, s19
	global_load_lds_dwordx4 v[212:213], off
	v_lshl_add_u64 v[232:233], s[0:1], 0, v[112:113]
	s_mov_b32 m0, s63
	v_lshl_add_u64 v[234:235], vcc, 0, v[130:131]
	global_load_lds_dwordx4 v[232:233], off
	v_lshl_add_u64 v[232:233], s[0:1], 0, v[130:131]
	s_add_i32 m0, s63, 0x2000
	s_nop 0
	global_load_lds_dwordx4 v[232:233], off
	v_lshl_add_u64 v[232:233], vcc, 0, v[112:113]
	s_mov_b32 m0, s20
	s_nop 0
	global_load_lds_dwordx4 v[232:233], off
	s_mov_b32 m0, s21
	s_nop 0
	global_load_lds_dwordx4 v[234:235], off
	s_waitcnt vmcnt(8)
	s_waitcnt lgkmcnt(0)
	s_barrier
; #define PG8_STAGE(bufoff, gbase, voff) do { _Pragma("unroll") for (int _i = 0; _i < 2; ++_i) \
;         __builtin_amdgcn_global_load_lds((const unsigned*)((const char*)(gbase) + (voff)[_i]), (PG8_LAS unsigned*)(lds + (bufoff) + ldsw + _i * 8192), 16, 0, 0); } while (0)
; #define PG8_LDA(dst, b, h) do { _Pragma("unroll") for (int m = 0; m < 4; ++m) _Pragma("unroll") for (int k = 0; k < 2; ++k) dst[m][k] = *(const PG8_LAS bf16x8*)(lds + PG8_SA(b, h) + aoff + m * 2048 + k * 1024); } while (0)
; #define PG8_LDB(dst, b, h) do { _Pragma("unroll") for (int n = 0; n < 2; ++n) _Pragma("unroll") for (int k = 0; k < 2; ++k) dst[n][k] = *(const PG8_LAS bf16x8*)(lds + PG8_SB(b, h) + boff + n * 2048 + k * 1024); } while (0)
; #define PG8_MMA(ai, bj, At, Bt) do { __builtin_amdgcn_s_setprio(1); _Pragma("unroll") for (int m = 0; m < 4; ++m) _Pragma("unroll") for (int n = 0; n < 2; ++n) _Pragma("unroll") for (int k = 0; k < 2; ++k) \
;         acc[ai][bj][m][n] = __builtin_amdgcn_mfma_f32_16x16x32_bf16(Bt[n][k], At[m][k], acc[ai][bj][m][n], 0, 0, 0); __builtin_amdgcn_s_setprio(0); } while (0)
; #define PG8_WAIT_V(n) asm volatile("s_waitcnt vmcnt(" #n ")" ::: "memory")
; #define PG8_WAIT_L(n) asm volatile("s_waitcnt lgkmcnt(" #n ")" ::: "memory")
; #define PG8_BAR __builtin_amdgcn_s_barrier()
; #define PG8_SCHED __builtin_amdgcn_sched_barrier(0)
; template <class Epi, class Sched, bool ALIGN_EPI = false, bool SP2 = false>
; __device__ __forceinline__ void gemm_phase(PG8_LAS unsigned char* lds, const Gemm g, const Sched& S, const Epi& E) {
;     ...
;             PG8_WAIT_V(8); PG8_WAIT_L(0); PG8_BAR; PG8_MMA(1, 0, At, B0); PG8_MMA(1, 1, At, B1); PG8_BAR; PG8_SCHED;
;             PG8_LDB(B0, 1, 0); PG8_LDB(B1, 1, 1); PG8_SCHED; PG8_LDA(At, 1, 0); PG8_STAGE(PG8_SA(0, 1), a2 + hstep, voffA);
;             PG8_WAIT_V(8); PG8_WAIT_L(0); PG8_BAR; PG8_MMA(0, 0, At, B0); PG8_MMA(0, 1, At, B1); PG8_BAR; PG8_SCHED;
	s_setprio 1
	s_waitcnt lgkmcnt(0)
	v_mfma_f32_16x16x32_bf16 v[60:63], v[136:139], v[168:171], 0
	v_mfma_f32_16x16x32_bf16 v[56:59], v[144:147], v[168:171], 0
	v_mfma_f32_16x16x32_bf16 v[44:47], v[136:139], v[184:187], 0
	v_mfma_f32_16x16x32_bf16 v[40:43], v[144:147], v[184:187], 0
	v_mfma_f32_16x16x32_bf16 v[28:31], v[136:139], v[204:207], 0
	v_mfma_f32_16x16x32_bf16 v[24:27], v[144:147], v[204:207], 0
	v_mfma_f32_16x16x32_bf16 v[12:15], v[136:139], v[224:227], 0
	v_mfma_f32_16x16x32_bf16 v[8:11], v[144:147], v[224:227], 0
	v_mfma_f32_16x16x32_bf16 v[60:63], v[140:143], v[172:175], v[60:63]
	v_mfma_f32_16x16x32_bf16 v[56:59], v[148:151], v[172:175], v[56:59]
	v_mfma_f32_16x16x32_bf16 v[44:47], v[140:143], v[200:203], v[44:47]
	v_mfma_f32_16x16x32_bf16 v[40:43], v[148:151], v[200:203], v[40:43]
	v_mfma_f32_16x16x32_bf16 v[28:31], v[140:143], v[208:211], v[28:31]
	v_mfma_f32_16x16x32_bf16 v[24:27], v[148:151], v[208:211], v[24:27]
	v_mfma_f32_16x16x32_bf16 v[12:15], v[140:143], v[228:231], v[12:15]
	v_mfma_f32_16x16x32_bf16 v[8:11], v[148:151], v[228:231], v[8:11]
	s_setprio 0
	s_setprio 1
	v_mfma_f32_16x16x32_bf16 v[52:55], v[152:155], v[168:171], 0
	v_mfma_f32_16x16x32_bf16 v[48:51], v[160:163], v[168:171], 0
	v_mfma_f32_16x16x32_bf16 v[36:39], v[152:155], v[184:187], 0
	v_mfma_f32_16x16x32_bf16 v[32:35], v[160:163], v[184:187], 0
	v_mfma_f32_16x16x32_bf16 v[20:23], v[152:155], v[204:207], 0
	v_mfma_f32_16x16x32_bf16 v[16:19], v[160:163], v[204:207], 0
	v_mfma_f32_16x16x32_bf16 v[4:7], v[152:155], v[224:227], 0
	v_mfma_f32_16x16x32_bf16 v[0:3], v[160:163], v[224:227], 0
	v_mfma_f32_16x16x32_bf16 v[52:55], v[156:159], v[172:175], v[52:55]
	v_mfma_f32_16x16x32_bf16 v[48:51], v[164:167], v[172:175], v[48:51]
	v_mfma_f32_16x16x32_bf16 v[36:39], v[156:159], v[200:203], v[36:39]
	v_mfma_f32_16x16x32_bf16 v[32:35], v[164:167], v[200:203], v[32:35]
	v_mfma_f32_16x16x32_bf16 v[20:23], v[156:159], v[208:211], v[20:23]
	v_mfma_f32_16x16x32_bf16 v[16:19], v[164:167], v[208:211], v[16:19]
	v_mfma_f32_16x16x32_bf16 v[4:7], v[156:159], v[228:231], v[4:7]
	v_mfma_f32_16x16x32_bf16 v[0:3], v[164:167], v[228:231], v[0:3]
	s_setprio 0
	s_barrier
	s_add_i32 s63, 0, 0x18000
	s_add_i32 s65, 0, 0x1c000
	v_add_u32_e32 v148, s63, v179
	v_add_u32_e32 v164, s65, v179
	ds_read_b128 v[136:139], v148
	ds_read_b128 v[140:143], v148 offset:1024
	ds_read_b128 v[144:147], v148 offset:2048
	ds_read_b128 v[148:151], v148 offset:3072
	ds_read_b128 v[152:155], v164
	ds_read_b128 v[156:159], v164 offset:1024
	ds_read_b128 v[160:163], v164 offset:2048
	ds_read_b128 v[164:167], v164 offset:3072
	s_add_u32 s0, vcc_lo, 0x40000
	s_addc_u32 s1, vcc_hi, 0
	s_mov_b32 m0, s22
	v_lshl_add_u64 v[236:237], s[0:1], 0, v[112:113]
	ds_read_b128 v[168:171], v181 offset:32768
	ds_read_b128 v[172:175], v181 offset:33792
	ds_read_b128 v[184:187], v181 offset:34816
	ds_read_b128 v[200:203], v181 offset:35840
	ds_read_b128 v[204:207], v181 offset:36864
	ds_read_b128 v[208:211], v181 offset:37888
	ds_read_b128 v[224:227], v181 offset:38912
	ds_read_b128 v[228:231], v181 offset:39936
	global_load_lds_dwordx4 v[236:237], off
	v_lshl_add_u64 v[236:237], s[0:1], 0, v[130:131]
	s_mov_b32 m0, s23
	s_nop 0
	global_load_lds_dwordx4 v[236:237], off
	s_waitcnt vmcnt(8)
	s_waitcnt lgkmcnt(0)
	s_barrier
	s_setprio 1
	s_waitcnt lgkmcnt(0)
	v_mfma_f32_16x16x32_bf16 v[126:129], v[136:139], v[168:171], v[126:129]
	v_mfma_f32_16x16x32_bf16 v[122:125], v[144:147], v[168:171], v[122:125]
	v_mfma_f32_16x16x32_bf16 v[108:111], v[136:139], v[184:187], v[108:111]
	v_mfma_f32_16x16x32_bf16 v[104:107], v[144:147], v[184:187], v[104:107]
	v_mfma_f32_16x16x32_bf16 v[92:95], v[136:139], v[204:207], v[92:95]
	v_mfma_f32_16x16x32_bf16 v[88:91], v[144:147], v[204:207], v[88:91]
	v_mfma_f32_16x16x32_bf16 v[76:79], v[136:139], v[224:227], v[76:79]
	v_mfma_f32_16x16x32_bf16 v[72:75], v[144:147], v[224:227], v[72:75]
	v_mfma_f32_16x16x32_bf16 v[126:129], v[140:143], v[172:175], v[126:129]
	v_mfma_f32_16x16x32_bf16 v[122:125], v[148:151], v[172:175], v[122:125]
	v_mfma_f32_16x16x32_bf16 v[108:111], v[140:143], v[200:203], v[108:111]
	v_mfma_f32_16x16x32_bf16 v[104:107], v[148:151], v[200:203], v[104:107]
	v_mfma_f32_16x16x32_bf16 v[92:95], v[140:143], v[208:211], v[92:95]
	v_mfma_f32_16x16x32_bf16 v[88:91], v[148:151], v[208:211], v[88:91]
	v_mfma_f32_16x16x32_bf16 v[76:79], v[140:143], v[228:231], v[76:79]
	v_mfma_f32_16x16x32_bf16 v[72:75], v[148:151], v[228:231], v[72:75]
	s_setprio 0
	s_setprio 1
	v_mfma_f32_16x16x32_bf16 v[118:121], v[152:155], v[168:171], v[118:121]
	v_mfma_f32_16x16x32_bf16 v[114:117], v[160:163], v[168:171], v[114:117]
	v_mfma_f32_16x16x32_bf16 v[100:103], v[152:155], v[184:187], v[100:103]
	v_mfma_f32_16x16x32_bf16 v[96:99], v[160:163], v[184:187], v[96:99]
	v_mfma_f32_16x16x32_bf16 v[84:87], v[152:155], v[204:207], v[84:87]
	v_mfma_f32_16x16x32_bf16 v[80:83], v[160:163], v[204:207], v[80:83]
	v_mfma_f32_16x16x32_bf16 v[68:71], v[152:155], v[224:227], v[68:71]
	v_mfma_f32_16x16x32_bf16 v[64:67], v[160:163], v[224:227], v[64:67]
	v_mfma_f32_16x16x32_bf16 v[118:121], v[156:159], v[172:175], v[118:121]
	v_mfma_f32_16x16x32_bf16 v[114:117], v[164:167], v[172:175], v[114:117]
	v_mfma_f32_16x16x32_bf16 v[100:103], v[156:159], v[200:203], v[100:103]
	v_mfma_f32_16x16x32_bf16 v[96:99], v[164:167], v[200:203], v[96:99]
	v_mfma_f32_16x16x32_bf16 v[84:87], v[156:159], v[208:211], v[84:87]
	v_mfma_f32_16x16x32_bf16 v[80:83], v[164:167], v[208:211], v[80:83]
	v_mfma_f32_16x16x32_bf16 v[68:71], v[156:159], v[228:231], v[68:71]
	v_mfma_f32_16x16x32_bf16 v[64:67], v[164:167], v[228:231], v[64:67]
	s_setprio 0
	s_barrier
; #define PG8_STAGE(bufoff, gbase, voff) do { _Pragma("unroll") for (int _i = 0; _i < 2; ++_i) \
;         __builtin_amdgcn_global_load_lds((const unsigned*)((const char*)(gbase) + (voff)[_i]), (PG8_LAS unsigned*)(lds + (bufoff) + ldsw + _i * 8192), 16, 0, 0); } while (0)
; #define PG8_LDA(dst, b, h) do { _Pragma("unroll") for (int m = 0; m < 4; ++m) _Pragma("unroll") for (int k = 0; k < 2; ++k) dst[m][k] = *(const PG8_LAS bf16x8*)(lds + PG8_SA(b, h) + aoff + m * 2048 + k * 1024); } while (0)
; #define PG8_MMA(ai, bj, At, Bt) do { __builtin_amdgcn_s_setprio(1); _Pragma("unroll") for (int m = 0; m < 4; ++m) _Pragma("unroll") for (int n = 0; n < 2; ++n) _Pragma("unroll") for (int k = 0; k < 2; ++k) \
;         acc[ai][bj][m][n] = __builtin_amdgcn_mfma_f32_16x16x32_bf16(Bt[n][k], At[m][k], acc[ai][bj][m][n], 0, 0, 0); __builtin_amdgcn_s_setprio(0); } while (0)
; #define PG8_WAIT_V(n) asm volatile("s_waitcnt vmcnt(" #n ")" ::: "memory")
; #define PG8_WAIT_L(n) asm volatile("s_waitcnt lgkmcnt(" #n ")" ::: "memory")
; #define PG8_BAR __builtin_amdgcn_s_barrier()
; #define PG8_SCHED __builtin_amdgcn_sched_barrier(0)
; template <class Epi, class Sched, bool ALIGN_EPI = false, bool SP2 = false>
; __device__ __forceinline__ void gemm_phase(PG8_LAS unsigned char* lds, const Gemm g, const Sched& S, const Epi& E) {
;     ...
;             PG8_LDA(At, 1, 1); PG8_STAGE(PG8_SB(1, 0), b3, voffB); PG8_STAGE(PG8_SB(1, 1), b3 + hstep, voffB); PG8_STAGE(PG8_SA(1, 0), a3, voffA);
;             PG8_WAIT_V(8); PG8_WAIT_L(0); PG8_BAR; PG8_MMA(1, 0, At, B0); PG8_MMA(1, 1, At, B1); PG8_BAR; PG8_SCHED;
	s_add_i32 s0, s63, s19
	v_lshl_add_u64 v[176:177], v[176:177], 0, s[36:37]
	s_mov_b32 m0, s0
	ds_read_b128 v[168:171], v181 offset:49152
	ds_read_b128 v[172:175], v181 offset:50176
	ds_read_b128 v[184:187], v181 offset:51200
	ds_read_b128 v[200:203], v181 offset:52224
	ds_read_b128 v[204:207], v181 offset:53248
	ds_read_b128 v[208:211], v181 offset:54272
	ds_read_b128 v[224:227], v181 offset:55296
	ds_read_b128 v[228:231], v181 offset:56320
	global_load_lds_dwordx4 v[176:177], off
	s_add_i32 m0, s0, 0x2000
	s_add_u32 s0, s56, 0x40080
	v_lshl_add_u64 v[176:177], v[212:213], 0, s[36:37]
	s_addc_u32 s1, s57, 0
	s_add_i32 s56, s65, s19
	global_load_lds_dwordx4 v[176:177], off
	v_lshl_add_u64 v[176:177], s[0:1], 0, v[112:113]
	s_mov_b32 m0, s56
	s_nop 0
	global_load_lds_dwordx4 v[176:177], off
	v_lshl_add_u64 v[176:177], s[0:1], 0, v[130:131]
	s_add_i32 m0, s56, 0x2000
	s_nop 0
	global_load_lds_dwordx4 v[176:177], off
	v_lshl_add_u64 v[176:177], v[232:233], 0, s[36:37]
	s_mov_b32 m0, s26
	s_nop 0
	global_load_lds_dwordx4 v[176:177], off
	v_lshl_add_u64 v[176:177], v[234:235], 0, s[36:37]
	s_mov_b32 m0, s33
	s_nop 0
	global_load_lds_dwordx4 v[176:177], off
	s_waitcnt vmcnt(8)
	s_waitcnt lgkmcnt(0)
	s_barrier
	s_setprio 1
	s_waitcnt lgkmcnt(0)
	v_mfma_f32_16x16x32_bf16 v[60:63], v[136:139], v[168:171], v[60:63]
	v_mfma_f32_16x16x32_bf16 v[56:59], v[144:147], v[168:171], v[56:59]
	v_mfma_f32_16x16x32_bf16 v[44:47], v[136:139], v[184:187], v[44:47]
	v_mfma_f32_16x16x32_bf16 v[40:43], v[144:147], v[184:187], v[40:43]
	v_mfma_f32_16x16x32_bf16 v[28:31], v[136:139], v[204:207], v[28:31]
	v_mfma_f32_16x16x32_bf16 v[24:27], v[144:147], v[204:207], v[24:27]
	v_mfma_f32_16x16x32_bf16 v[12:15], v[136:139], v[224:227], v[12:15]
	v_mfma_f32_16x16x32_bf16 v[8:11], v[144:147], v[224:227], v[8:11]
	v_mfma_f32_16x16x32_bf16 v[60:63], v[140:143], v[172:175], v[60:63]
	v_mfma_f32_16x16x32_bf16 v[56:59], v[148:151], v[172:175], v[56:59]
	v_mfma_f32_16x16x32_bf16 v[44:47], v[140:143], v[200:203], v[44:47]
	v_mfma_f32_16x16x32_bf16 v[40:43], v[148:151], v[200:203], v[40:43]
	v_mfma_f32_16x16x32_bf16 v[28:31], v[140:143], v[208:211], v[28:31]
	v_mfma_f32_16x16x32_bf16 v[24:27], v[148:151], v[208:211], v[24:27]
	v_mfma_f32_16x16x32_bf16 v[12:15], v[140:143], v[228:231], v[12:15]
	v_mfma_f32_16x16x32_bf16 v[8:11], v[148:151], v[228:231], v[8:11]
	s_setprio 0
	s_setprio 1
	v_mfma_f32_16x16x32_bf16 v[52:55], v[152:155], v[168:171], v[52:55]
	v_mfma_f32_16x16x32_bf16 v[48:51], v[160:163], v[168:171], v[48:51]
	v_mfma_f32_16x16x32_bf16 v[36:39], v[152:155], v[184:187], v[36:39]
	v_mfma_f32_16x16x32_bf16 v[32:35], v[160:163], v[184:187], v[32:35]
	v_mfma_f32_16x16x32_bf16 v[20:23], v[152:155], v[204:207], v[20:23]
	v_mfma_f32_16x16x32_bf16 v[16:19], v[160:163], v[204:207], v[16:19]
	v_mfma_f32_16x16x32_bf16 v[4:7], v[152:155], v[224:227], v[4:7]
	v_mfma_f32_16x16x32_bf16 v[0:3], v[160:163], v[224:227], v[0:3]
	v_mfma_f32_16x16x32_bf16 v[52:55], v[156:159], v[172:175], v[52:55]
	v_mfma_f32_16x16x32_bf16 v[48:51], v[164:167], v[172:175], v[48:51]
	v_mfma_f32_16x16x32_bf16 v[36:39], v[156:159], v[200:203], v[36:39]
	v_mfma_f32_16x16x32_bf16 v[32:35], v[164:167], v[200:203], v[32:35]
	v_mfma_f32_16x16x32_bf16 v[20:23], v[156:159], v[208:211], v[20:23]
	v_mfma_f32_16x16x32_bf16 v[16:19], v[164:167], v[208:211], v[16:19]
	v_mfma_f32_16x16x32_bf16 v[4:7], v[156:159], v[228:231], v[4:7]
	v_mfma_f32_16x16x32_bf16 v[0:3], v[164:167], v[228:231], v[0:3]
	s_setprio 0
	s_barrier
	s_add_i32 s60, s60, 2
	s_add_u32 s58, s58, 0x100
	s_addc_u32 s61, s61, 0
	s_cmp_gt_u32 s60, 13
	s_mov_b64 s[0:1], s[40:41]


; #define PG8_STAGE(bufoff, gbase, voff) do { _Pragma("unroll") for (int _i = 0; _i < 2; ++_i) \
;         __builtin_amdgcn_global_load_lds((const unsigned*)((const char*)(gbase) + (voff)[_i]), (PG8_LAS unsigned*)(lds + (bufoff) + ldsw + _i * 8192), 16, 0, 0); } while (0)
; #define PG8_LDA(dst, b, h) do { _Pragma("unroll") for (int m = 0; m < 4; ++m) _Pragma("unroll") for (int k = 0; k < 2; ++k) dst[m][k] = *(const PG8_LAS bf16x8*)(lds + PG8_SA(b, h) + aoff + m * 2048 + k * 1024); } while (0)
; #define PG8_LDB(dst, b, h) do { _Pragma("unroll") for (int n = 0; n < 2; ++n) _Pragma("unroll") for (int k = 0; k < 2; ++k) dst[n][k] = *(const PG8_LAS bf16x8*)(lds + PG8_SB(b, h) + boff + n * 2048 + k * 1024); } while (0)
; #define PG8_MMA(ai, bj, At, Bt) do { __builtin_amdgcn_s_setprio(1); _Pragma("unroll") for (int m = 0; m < 4; ++m) _Pragma("unroll") for (int n = 0; n < 2; ++n) _Pragma("unroll") for (int k = 0; k < 2; ++k) \
;         acc[ai][bj][m][n] = __builtin_amdgcn_mfma_f32_16x16x32_bf16(Bt[n][k], At[m][k], acc[ai][bj][m][n], 0, 0, 0); __builtin_amdgcn_s_setprio(0); } while (0)
; #define PG8_WAIT_V(n) asm volatile("s_waitcnt vmcnt(" #n ")" ::: "memory")
; template <class Epi, class Sched, bool ALIGN_EPI = false, bool SP2 = false>
; __device__ __forceinline__ void gemm_phase(PG8_LAS unsigned char* lds, const Gemm g, const Sched& S, const Epi& E) {
;     ...
;         const char* nA = has_next ? (const char*)g.A + (size_t)nxt.pm * tstep : cA; const char* nB = has_next ? (const char*)g.Bt + (size_t)nxt.pn * tstep : cB;
;         for (int t = 0; t < nt; t += 2) {
;             const bool last = (t == nt - 2);
;             const char* a1 = cA + (size_t)(t + 1) * kstep;
;             const char* a2 = last ? nA : cA + (size_t)(t + 2) * kstep; const char* b2 = last ? nB : cB + (size_t)(t + 2) * kstep;
;             const char* a3 = a2 + kstep; const char* b3 = b2 + kstep;
;             if (last && has_next) S.a_ready(nxt);
;             if constexpr (SP2) {
;             PG8_LDB(B0, 0, 0); PG8_LDB(B1, 0, 1); PG8_SCHED; PG8_LDA(At, 0, 0); PG8_STAGE(PG8_SA(1, 1), a1 + hstep, voffA);
;             PG8_WAIT_V(8); PG8_WAIT_L(0); PG8_BAR; PG8_MMA(0, 0, At, B0); PG8_MMA(0, 1, At, B1); PG8_BAR; PG8_SCHED;
;             PG8_LDA(At, 0, 1); PG8_STAGE(PG8_SB(0, 0), b2, voffB); PG8_STAGE(PG8_SB(0, 1), b2 + hstep, voffB); PG8_STAGE(PG8_SA(0, 0), a2, voffA);
.LBB0_554:
	s_ashr_i32 s49, s48, 31
	s_lshl_b64 s[12:13], s[48:49], 19
	s_add_u32 s50, s15, s12
	s_addc_u32 s51, s16, s13
	s_and_b64 s[12:13], s[6:7], exec
	s_cselect_b32 s12, s51, s1
	s_cselect_b32 s13, s50, s0
	s_ashr_i32 s47, s46, 31
	s_lshl_b64 s[54:55], s[46:47], 19
	s_add_u32 s54, s17, s54
	s_addc_u32 s55, s18, s55
	s_and_b64 s[56:57], s[6:7], exec
	s_cselect_b32 s47, s55, s41
	s_cselect_b32 s49, s54, s40
	s_add_u32 s0, s0, 0x40080
	s_addc_u32 s1, s1, 0
	s_add_u32 s58, s40, 0x100
	s_addc_u32 s61, s41, 0
	s_mov_b32 s60, -2
	s_waitcnt lgkmcnt(0)
	s_waitcnt vmcnt(0)
	s_add_u32 s40, s0, 0xfffc0080
	s_addc_u32 s41, s1, -1
	s_add_i32 s63, 0, 0x10000
	s_cmp_eq_u32 s60, 12
	s_cselect_b32 s57, s12, s41
	s_cselect_b32 s56, s13, s40
	s_cselect_b32 s41, s47, s61
	s_cselect_b32 s40, s49, s58
	s_add_i32 s65, 0, 0x14000
	v_add_u32_e32 v142, s63, v224
	v_add_u32_e32 v158, s65, v224
	ds_read_b128 v[130:133], v142
	ds_read_b128 v[134:137], v142 offset:1024
	ds_read_b128 v[138:141], v142 offset:2048
	ds_read_b128 v[142:145], v142 offset:3072
	ds_read_b128 v[146:149], v158
	ds_read_b128 v[150:153], v158 offset:1024
	ds_read_b128 v[154:157], v158 offset:2048
	ds_read_b128 v[158:161], v158 offset:3072
	v_lshl_add_u64 v[228:229], s[0:1], 0, v[180:181]
	s_add_i32 m0, s20, 0xc000
	ds_read_b128 v[162:165], v226
	ds_read_b128 v[166:169], v226 offset:1024
	ds_read_b128 v[170:173], v226 offset:2048
	ds_read_b128 v[174:177], v226 offset:3072
	ds_read_b128 v[184:187], v226 offset:4096
	ds_read_b128 v[202:205], v226 offset:5120
	ds_read_b128 v[206:209], v226 offset:6144
	ds_read_b128 v[210:213], v226 offset:7168
	global_load_lds_dwordx4 v[228:229], off
	v_lshl_add_u64 v[228:229], s[0:1], 0, v[200:201]
	s_add_i32 m0, s20, 0xe000
	s_nop 0
	global_load_lds_dwordx4 v[228:229], off
	s_waitcnt vmcnt(8)
	s_waitcnt lgkmcnt(0)
	s_barrier
	s_setprio 1
	s_waitcnt lgkmcnt(0)
	v_mfma_f32_16x16x32_bf16 v[126:129], v[130:133], v[162:165], 0
	v_mfma_f32_16x16x32_bf16 v[122:125], v[138:141], v[162:165], 0
	v_mfma_f32_16x16x32_bf16 v[108:111], v[130:133], v[170:173], 0
	v_mfma_f32_16x16x32_bf16 v[104:107], v[138:141], v[170:173], 0
	v_mfma_f32_16x16x32_bf16 v[92:95], v[130:133], v[184:187], 0
	v_mfma_f32_16x16x32_bf16 v[88:91], v[138:141], v[184:187], 0
	v_mfma_f32_16x16x32_bf16 v[76:79], v[130:133], v[206:209], 0
	v_mfma_f32_16x16x32_bf16 v[72:75], v[138:141], v[206:209], 0
	v_mfma_f32_16x16x32_bf16 v[126:129], v[134:137], v[166:169], v[126:129]
	v_mfma_f32_16x16x32_bf16 v[122:125], v[142:145], v[166:169], v[122:125]
	v_mfma_f32_16x16x32_bf16 v[108:111], v[134:137], v[174:177], v[108:111]
	v_mfma_f32_16x16x32_bf16 v[104:107], v[142:145], v[174:177], v[104:107]
	v_mfma_f32_16x16x32_bf16 v[92:95], v[134:137], v[202:205], v[92:95]
	v_mfma_f32_16x16x32_bf16 v[88:91], v[142:145], v[202:205], v[88:91]
	v_mfma_f32_16x16x32_bf16 v[76:79], v[134:137], v[210:213], v[76:79]
	v_mfma_f32_16x16x32_bf16 v[72:75], v[142:145], v[210:213], v[72:75]
	s_setprio 0
	s_setprio 1
	v_mfma_f32_16x16x32_bf16 v[118:121], v[146:149], v[162:165], 0
	v_mfma_f32_16x16x32_bf16 v[114:117], v[154:157], v[162:165], 0
	v_mfma_f32_16x16x32_bf16 v[100:103], v[146:149], v[170:173], 0
	v_mfma_f32_16x16x32_bf16 v[96:99], v[154:157], v[170:173], 0
	v_mfma_f32_16x16x32_bf16 v[84:87], v[146:149], v[184:187], 0
	v_mfma_f32_16x16x32_bf16 v[80:83], v[154:157], v[184:187], 0
	v_mfma_f32_16x16x32_bf16 v[68:71], v[146:149], v[206:209], 0
	v_mfma_f32_16x16x32_bf16 v[64:67], v[154:157], v[206:209], 0
	v_mfma_f32_16x16x32_bf16 v[118:121], v[150:153], v[166:169], v[118:121]
	v_mfma_f32_16x16x32_bf16 v[114:117], v[158:161], v[166:169], v[114:117]
	v_mfma_f32_16x16x32_bf16 v[100:103], v[150:153], v[174:177], v[100:103]
	v_mfma_f32_16x16x32_bf16 v[96:99], v[158:161], v[174:177], v[96:99]
	v_mfma_f32_16x16x32_bf16 v[84:87], v[150:153], v[202:205], v[84:87]
	v_mfma_f32_16x16x32_bf16 v[80:83], v[158:161], v[202:205], v[80:83]
	v_mfma_f32_16x16x32_bf16 v[68:71], v[150:153], v[210:213], v[68:71]
	v_mfma_f32_16x16x32_bf16 v[64:67], v[158:161], v[210:213], v[64:67]
	s_setprio 0
	s_barrier
	s_add_i32 s63, s63, s19
	v_lshl_add_u64 v[228:229], s[40:41], 0, v[112:113]
	s_mov_b32 m0, s63
	ds_read_b128 v[162:165], v226 offset:16384
	ds_read_b128 v[166:169], v226 offset:17408
	ds_read_b128 v[170:173], v226 offset:18432
	ds_read_b128 v[174:177], v226 offset:19456
	ds_read_b128 v[184:187], v226 offset:20480
	ds_read_b128 v[202:205], v226 offset:21504
	ds_read_b128 v[206:209], v226 offset:22528
	ds_read_b128 v[210:213], v226 offset:23552
	global_load_lds_dwordx4 v[228:229], off
	s_add_i32 m0, s63, 0x2000
	s_add_u32 s66, s40, 0x40000
	v_lshl_add_u64 v[230:231], s[40:41], 0, v[178:179]
	s_addc_u32 s67, s41, 0
	s_add_i32 s63, s65, s19
	global_load_lds_dwordx4 v[230:231], off
	v_lshl_add_u64 v[232:233], s[66:67], 0, v[112:113]
	s_mov_b32 m0, s63
	v_lshl_add_u64 v[234:235], s[56:57], 0, v[178:179]
	global_load_lds_dwordx4 v[232:233], off
	v_lshl_add_u64 v[232:233], s[66:67], 0, v[178:179]
	s_add_i32 m0, s63, 0x2000
	s_nop 0
	global_load_lds_dwordx4 v[232:233], off
	v_lshl_add_u64 v[232:233], s[56:57], 0, v[112:113]
	s_mov_b32 m0, s20
	s_nop 0
	global_load_lds_dwordx4 v[232:233], off
	s_mov_b32 m0, s21
	s_nop 0
	global_load_lds_dwordx4 v[234:235], off
	s_waitcnt vmcnt(8)
	s_waitcnt lgkmcnt(0)
	s_barrier
; #define PG8_STAGE(bufoff, gbase, voff) do { _Pragma("unroll") for (int _i = 0; _i < 2; ++_i) \
;         __builtin_amdgcn_global_load_lds((const unsigned*)((const char*)(gbase) + (voff)[_i]), (PG8_LAS unsigned*)(lds + (bufoff) + ldsw + _i * 8192), 16, 0, 0); } while (0)
; #define PG8_LDA(dst, b, h) do { _Pragma("unroll") for (int m = 0; m < 4; ++m) _Pragma("unroll") for (int k = 0; k < 2; ++k) dst[m][k] = *(const PG8_LAS bf16x8*)(lds + PG8_SA(b, h) + aoff + m * 2048 + k * 1024); } while (0)
; #define PG8_LDB(dst, b, h) do { _Pragma("unroll") for (int n = 0; n < 2; ++n) _Pragma("unroll") for (int k = 0; k < 2; ++k) dst[n][k] = *(const PG8_LAS bf16x8*)(lds + PG8_SB(b, h) + boff + n * 2048 + k * 1024); } while (0)
; #define PG8_MMA(ai, bj, At, Bt) do { __builtin_amdgcn_s_setprio(1); _Pragma("unroll") for (int m = 0; m < 4; ++m) _Pragma("unroll") for (int n = 0; n < 2; ++n) _Pragma("unroll") for (int k = 0; k < 2; ++k) \
;         acc[ai][bj][m][n] = __builtin_amdgcn_mfma_f32_16x16x32_bf16(Bt[n][k], At[m][k], acc[ai][bj][m][n], 0, 0, 0); __builtin_amdgcn_s_setprio(0); } while (0)
; #define PG8_WAIT_V(n) asm volatile("s_waitcnt vmcnt(" #n ")" ::: "memory")
; #define PG8_WAIT_L(n) asm volatile("s_waitcnt lgkmcnt(" #n ")" ::: "memory")
; #define PG8_BAR __builtin_amdgcn_s_barrier()
; #define PG8_SCHED __builtin_amdgcn_sched_barrier(0)
; template <class Epi, class Sched, bool ALIGN_EPI = false, bool SP2 = false>
; __device__ __forceinline__ void gemm_phase(PG8_LAS unsigned char* lds, const Gemm g, const Sched& S, const Epi& E) {
;     ...
;             PG8_WAIT_V(8); PG8_WAIT_L(0); PG8_BAR; PG8_MMA(1, 0, At, B0); PG8_MMA(1, 1, At, B1); PG8_BAR; PG8_SCHED;
;             PG8_LDB(B0, 1, 0); PG8_LDB(B1, 1, 1); PG8_SCHED; PG8_LDA(At, 1, 0); PG8_STAGE(PG8_SA(0, 1), a2 + hstep, voffA);
;             PG8_WAIT_V(8); PG8_WAIT_L(0); PG8_BAR; PG8_MMA(0, 0, At, B0); PG8_MMA(0, 1, At, B1); PG8_BAR; PG8_SCHED;
	s_setprio 1
	s_waitcnt lgkmcnt(0)
	v_mfma_f32_16x16x32_bf16 v[60:63], v[130:133], v[162:165], 0
	v_mfma_f32_16x16x32_bf16 v[56:59], v[138:141], v[162:165], 0
	v_mfma_f32_16x16x32_bf16 v[44:47], v[130:133], v[170:173], 0
	v_mfma_f32_16x16x32_bf16 v[40:43], v[138:141], v[170:173], 0
	v_mfma_f32_16x16x32_bf16 v[28:31], v[130:133], v[184:187], 0
	v_mfma_f32_16x16x32_bf16 v[24:27], v[138:141], v[184:187], 0
	v_mfma_f32_16x16x32_bf16 v[12:15], v[130:133], v[206:209], 0
	v_mfma_f32_16x16x32_bf16 v[8:11], v[138:141], v[206:209], 0
	v_mfma_f32_16x16x32_bf16 v[60:63], v[134:137], v[166:169], v[60:63]
	v_mfma_f32_16x16x32_bf16 v[56:59], v[142:145], v[166:169], v[56:59]
	v_mfma_f32_16x16x32_bf16 v[44:47], v[134:137], v[174:177], v[44:47]
	v_mfma_f32_16x16x32_bf16 v[40:43], v[142:145], v[174:177], v[40:43]
	v_mfma_f32_16x16x32_bf16 v[28:31], v[134:137], v[202:205], v[28:31]
	v_mfma_f32_16x16x32_bf16 v[24:27], v[142:145], v[202:205], v[24:27]
	v_mfma_f32_16x16x32_bf16 v[12:15], v[134:137], v[210:213], v[12:15]
	v_mfma_f32_16x16x32_bf16 v[8:11], v[142:145], v[210:213], v[8:11]
	s_setprio 0
	s_setprio 1
	v_mfma_f32_16x16x32_bf16 v[52:55], v[146:149], v[162:165], 0
	v_mfma_f32_16x16x32_bf16 v[48:51], v[154:157], v[162:165], 0
	v_mfma_f32_16x16x32_bf16 v[36:39], v[146:149], v[170:173], 0
	v_mfma_f32_16x16x32_bf16 v[32:35], v[154:157], v[170:173], 0
	v_mfma_f32_16x16x32_bf16 v[20:23], v[146:149], v[184:187], 0
	v_mfma_f32_16x16x32_bf16 v[16:19], v[154:157], v[184:187], 0
	v_mfma_f32_16x16x32_bf16 v[4:7], v[146:149], v[206:209], 0
	v_mfma_f32_16x16x32_bf16 v[0:3], v[154:157], v[206:209], 0
	v_mfma_f32_16x16x32_bf16 v[52:55], v[150:153], v[166:169], v[52:55]
	v_mfma_f32_16x16x32_bf16 v[48:51], v[158:161], v[166:169], v[48:51]
	v_mfma_f32_16x16x32_bf16 v[36:39], v[150:153], v[174:177], v[36:39]
	v_mfma_f32_16x16x32_bf16 v[32:35], v[158:161], v[174:177], v[32:35]
	v_mfma_f32_16x16x32_bf16 v[20:23], v[150:153], v[202:205], v[20:23]
	v_mfma_f32_16x16x32_bf16 v[16:19], v[158:161], v[202:205], v[16:19]
	v_mfma_f32_16x16x32_bf16 v[4:7], v[150:153], v[210:213], v[4:7]
	v_mfma_f32_16x16x32_bf16 v[0:3], v[158:161], v[210:213], v[0:3]
	s_setprio 0
	s_barrier
	s_add_i32 s63, 0, 0x18000
	s_add_i32 s65, 0, 0x1c000
	v_add_u32_e32 v142, s63, v224
	v_add_u32_e32 v158, s65, v224
	ds_read_b128 v[130:133], v142
	ds_read_b128 v[134:137], v142 offset:1024
	ds_read_b128 v[138:141], v142 offset:2048
	ds_read_b128 v[142:145], v142 offset:3072
	ds_read_b128 v[146:149], v158
	ds_read_b128 v[150:153], v158 offset:1024
	ds_read_b128 v[154:157], v158 offset:2048
	ds_read_b128 v[158:161], v158 offset:3072
	s_add_u32 s56, s56, 0x40000
	s_addc_u32 s57, s57, 0
	s_mov_b32 m0, s22
	v_lshl_add_u64 v[236:237], s[56:57], 0, v[112:113]
	ds_read_b128 v[162:165], v226 offset:32768
	ds_read_b128 v[166:169], v226 offset:33792
	ds_read_b128 v[170:173], v226 offset:34816
	ds_read_b128 v[174:177], v226 offset:35840
	ds_read_b128 v[184:187], v226 offset:36864
	ds_read_b128 v[202:205], v226 offset:37888
	ds_read_b128 v[206:209], v226 offset:38912
	ds_read_b128 v[210:213], v226 offset:39936
	global_load_lds_dwordx4 v[236:237], off
	v_lshl_add_u64 v[236:237], s[56:57], 0, v[178:179]
	s_mov_b32 m0, s23
	s_nop 0
	global_load_lds_dwordx4 v[236:237], off
	s_waitcnt vmcnt(8)
	s_waitcnt lgkmcnt(0)
	s_barrier
	s_setprio 1
	s_waitcnt lgkmcnt(0)
	v_mfma_f32_16x16x32_bf16 v[126:129], v[130:133], v[162:165], v[126:129]
	v_mfma_f32_16x16x32_bf16 v[122:125], v[138:141], v[162:165], v[122:125]
	v_mfma_f32_16x16x32_bf16 v[108:111], v[130:133], v[170:173], v[108:111]
	v_mfma_f32_16x16x32_bf16 v[104:107], v[138:141], v[170:173], v[104:107]
	v_mfma_f32_16x16x32_bf16 v[92:95], v[130:133], v[184:187], v[92:95]
	v_mfma_f32_16x16x32_bf16 v[88:91], v[138:141], v[184:187], v[88:91]
	v_mfma_f32_16x16x32_bf16 v[76:79], v[130:133], v[206:209], v[76:79]
	v_mfma_f32_16x16x32_bf16 v[72:75], v[138:141], v[206:209], v[72:75]
	v_mfma_f32_16x16x32_bf16 v[126:129], v[134:137], v[166:169], v[126:129]
	v_mfma_f32_16x16x32_bf16 v[122:125], v[142:145], v[166:169], v[122:125]
	v_mfma_f32_16x16x32_bf16 v[108:111], v[134:137], v[174:177], v[108:111]
	v_mfma_f32_16x16x32_bf16 v[104:107], v[142:145], v[174:177], v[104:107]
	v_mfma_f32_16x16x32_bf16 v[92:95], v[134:137], v[202:205], v[92:95]
	v_mfma_f32_16x16x32_bf16 v[88:91], v[142:145], v[202:205], v[88:91]
	v_mfma_f32_16x16x32_bf16 v[76:79], v[134:137], v[210:213], v[76:79]
	v_mfma_f32_16x16x32_bf16 v[72:75], v[142:145], v[210:213], v[72:75]
	s_setprio 0
	s_setprio 1
	v_mfma_f32_16x16x32_bf16 v[118:121], v[146:149], v[162:165], v[118:121]
	v_mfma_f32_16x16x32_bf16 v[114:117], v[154:157], v[162:165], v[114:117]
	v_mfma_f32_16x16x32_bf16 v[100:103], v[146:149], v[170:173], v[100:103]
	v_mfma_f32_16x16x32_bf16 v[96:99], v[154:157], v[170:173], v[96:99]
	v_mfma_f32_16x16x32_bf16 v[84:87], v[146:149], v[184:187], v[84:87]
	v_mfma_f32_16x16x32_bf16 v[80:83], v[154:157], v[184:187], v[80:83]
	v_mfma_f32_16x16x32_bf16 v[68:71], v[146:149], v[206:209], v[68:71]
	v_mfma_f32_16x16x32_bf16 v[64:67], v[154:157], v[206:209], v[64:67]
	v_mfma_f32_16x16x32_bf16 v[118:121], v[150:153], v[166:169], v[118:121]
	v_mfma_f32_16x16x32_bf16 v[114:117], v[158:161], v[166:169], v[114:117]
	v_mfma_f32_16x16x32_bf16 v[100:103], v[150:153], v[174:177], v[100:103]
	v_mfma_f32_16x16x32_bf16 v[96:99], v[158:161], v[174:177], v[96:99]
	v_mfma_f32_16x16x32_bf16 v[84:87], v[150:153], v[202:205], v[84:87]
	v_mfma_f32_16x16x32_bf16 v[80:83], v[158:161], v[202:205], v[80:83]
	v_mfma_f32_16x16x32_bf16 v[68:71], v[150:153], v[210:213], v[68:71]
	v_mfma_f32_16x16x32_bf16 v[64:67], v[158:161], v[210:213], v[64:67]
	s_setprio 0
	s_barrier
; #define PG8_STAGE(bufoff, gbase, voff) do { _Pragma("unroll") for (int _i = 0; _i < 2; ++_i) \
;         __builtin_amdgcn_global_load_lds((const unsigned*)((const char*)(gbase) + (voff)[_i]), (PG8_LAS unsigned*)(lds + (bufoff) + ldsw + _i * 8192), 16, 0, 0); } while (0)
; #define PG8_LDA(dst, b, h) do { _Pragma("unroll") for (int m = 0; m < 4; ++m) _Pragma("unroll") for (int k = 0; k < 2; ++k) dst[m][k] = *(const PG8_LAS bf16x8*)(lds + PG8_SA(b, h) + aoff + m * 2048 + k * 1024); } while (0)
; #define PG8_MMA(ai, bj, At, Bt) do { __builtin_amdgcn_s_setprio(1); _Pragma("unroll") for (int m = 0; m < 4; ++m) _Pragma("unroll") for (int n = 0; n < 2; ++n) _Pragma("unroll") for (int k = 0; k < 2; ++k) \
;         acc[ai][bj][m][n] = __builtin_amdgcn_mfma_f32_16x16x32_bf16(Bt[n][k], At[m][k], acc[ai][bj][m][n], 0, 0, 0); __builtin_amdgcn_s_setprio(0); } while (0)
; #define PG8_WAIT_V(n) asm volatile("s_waitcnt vmcnt(" #n ")" ::: "memory")
; #define PG8_WAIT_L(n) asm volatile("s_waitcnt lgkmcnt(" #n ")" ::: "memory")
; #define PG8_BAR __builtin_amdgcn_s_barrier()
; #define PG8_SCHED __builtin_amdgcn_sched_barrier(0)
; template <class Epi, class Sched, bool ALIGN_EPI = false, bool SP2 = false>
; __device__ __forceinline__ void gemm_phase(PG8_LAS unsigned char* lds, const Gemm g, const Sched& S, const Epi& E) {
;     ...
;             PG8_LDA(At, 1, 1); PG8_STAGE(PG8_SB(1, 0), b3, voffB); PG8_STAGE(PG8_SB(1, 1), b3 + hstep, voffB); PG8_STAGE(PG8_SA(1, 0), a3, voffA);
;             PG8_WAIT_V(8); PG8_WAIT_L(0); PG8_BAR; PG8_MMA(1, 0, At, B0); PG8_MMA(1, 1, At, B1); PG8_BAR; PG8_SCHED;
	s_add_i32 s56, s63, s19
	v_lshl_add_u64 v[228:229], v[228:229], 0, s[36:37]
	s_mov_b32 m0, s56
	ds_read_b128 v[162:165], v226 offset:49152
	ds_read_b128 v[166:169], v226 offset:50176
	ds_read_b128 v[170:173], v226 offset:51200
	ds_read_b128 v[174:177], v226 offset:52224
	ds_read_b128 v[184:187], v226 offset:53248
	ds_read_b128 v[202:205], v226 offset:54272
	ds_read_b128 v[206:209], v226 offset:55296
	ds_read_b128 v[210:213], v226 offset:56320
	global_load_lds_dwordx4 v[228:229], off
	s_add_i32 m0, s56, 0x2000
	s_add_u32 s40, s40, 0x40080
	v_lshl_add_u64 v[228:229], v[230:231], 0, s[36:37]
	s_addc_u32 s41, s41, 0
	s_add_i32 s56, s65, s19
	global_load_lds_dwordx4 v[228:229], off
	v_lshl_add_u64 v[228:229], s[40:41], 0, v[112:113]
	s_mov_b32 m0, s56
	s_nop 0
	global_load_lds_dwordx4 v[228:229], off
	v_lshl_add_u64 v[228:229], s[40:41], 0, v[178:179]
	s_add_i32 m0, s56, 0x2000
	s_nop 0
	global_load_lds_dwordx4 v[228:229], off
	v_lshl_add_u64 v[228:229], v[232:233], 0, s[36:37]
	s_mov_b32 m0, s26
	s_nop 0
	global_load_lds_dwordx4 v[228:229], off
	v_lshl_add_u64 v[228:229], v[234:235], 0, s[36:37]
	s_mov_b32 m0, s33
	s_nop 0
	global_load_lds_dwordx4 v[228:229], off
	s_waitcnt vmcnt(8)
	s_waitcnt lgkmcnt(0)
	s_barrier
	s_setprio 1
	s_waitcnt lgkmcnt(0)
	v_mfma_f32_16x16x32_bf16 v[60:63], v[130:133], v[162:165], v[60:63]
	v_mfma_f32_16x16x32_bf16 v[56:59], v[138:141], v[162:165], v[56:59]
	v_mfma_f32_16x16x32_bf16 v[44:47], v[130:133], v[170:173], v[44:47]
	v_mfma_f32_16x16x32_bf16 v[40:43], v[138:141], v[170:173], v[40:43]
	v_mfma_f32_16x16x32_bf16 v[28:31], v[130:133], v[184:187], v[28:31]
	v_mfma_f32_16x16x32_bf16 v[24:27], v[138:141], v[184:187], v[24:27]
	v_mfma_f32_16x16x32_bf16 v[12:15], v[130:133], v[206:209], v[12:15]
	v_mfma_f32_16x16x32_bf16 v[8:11], v[138:141], v[206:209], v[8:11]
	v_mfma_f32_16x16x32_bf16 v[60:63], v[134:137], v[166:169], v[60:63]
	v_mfma_f32_16x16x32_bf16 v[56:59], v[142:145], v[166:169], v[56:59]
	v_mfma_f32_16x16x32_bf16 v[44:47], v[134:137], v[174:177], v[44:47]
	v_mfma_f32_16x16x32_bf16 v[40:43], v[142:145], v[174:177], v[40:43]
	v_mfma_f32_16x16x32_bf16 v[28:31], v[134:137], v[202:205], v[28:31]
	v_mfma_f32_16x16x32_bf16 v[24:27], v[142:145], v[202:205], v[24:27]
	v_mfma_f32_16x16x32_bf16 v[12:15], v[134:137], v[210:213], v[12:15]
	v_mfma_f32_16x16x32_bf16 v[8:11], v[142:145], v[210:213], v[8:11]
	s_setprio 0
	s_setprio 1
	v_mfma_f32_16x16x32_bf16 v[52:55], v[146:149], v[162:165], v[52:55]
	v_mfma_f32_16x16x32_bf16 v[48:51], v[154:157], v[162:165], v[48:51]
	v_mfma_f32_16x16x32_bf16 v[36:39], v[146:149], v[170:173], v[36:39]
	v_mfma_f32_16x16x32_bf16 v[32:35], v[154:157], v[170:173], v[32:35]
	v_mfma_f32_16x16x32_bf16 v[20:23], v[146:149], v[184:187], v[20:23]
	v_mfma_f32_16x16x32_bf16 v[16:19], v[154:157], v[184:187], v[16:19]
	v_mfma_f32_16x16x32_bf16 v[4:7], v[146:149], v[206:209], v[4:7]
	v_mfma_f32_16x16x32_bf16 v[0:3], v[154:157], v[206:209], v[0:3]
	v_mfma_f32_16x16x32_bf16 v[52:55], v[150:153], v[166:169], v[52:55]
	v_mfma_f32_16x16x32_bf16 v[48:51], v[158:161], v[166:169], v[48:51]
	v_mfma_f32_16x16x32_bf16 v[36:39], v[150:153], v[174:177], v[36:39]
	v_mfma_f32_16x16x32_bf16 v[32:35], v[158:161], v[174:177], v[32:35]
	v_mfma_f32_16x16x32_bf16 v[20:23], v[150:153], v[202:205], v[20:23]
	v_mfma_f32_16x16x32_bf16 v[16:19], v[158:161], v[202:205], v[16:19]
	v_mfma_f32_16x16x32_bf16 v[4:7], v[150:153], v[210:213], v[4:7]
	v_mfma_f32_16x16x32_bf16 v[0:3], v[158:161], v[210:213], v[0:3]
	s_setprio 0
	s_barrier
	s_add_i32 s60, s60, 2
	s_add_u32 s0, s0, 0x100
	s_addc_u32 s1, s1, 0
	s_add_u32 s58, s58, 0x100
	s_addc_u32 s61, s61, 0
	s_cmp_gt_u32 s60, 13


; #define PG8_STAGE(bufoff, gbase, voff) do { _Pragma("unroll") for (int _i = 0; _i < 2; ++_i) \
;         __builtin_amdgcn_global_load_lds((const unsigned*)((const char*)(gbase) + (voff)[_i]), (PG8_LAS unsigned*)(lds + (bufoff) + ldsw + _i * 8192), 16, 0, 0); } while (0)
; #define PG8_LDA(dst, b, h) do { _Pragma("unroll") for (int m = 0; m < 4; ++m) _Pragma("unroll") for (int k = 0; k < 2; ++k) dst[m][k] = *(const PG8_LAS bf16x8*)(lds + PG8_SA(b, h) + aoff + m * 2048 + k * 1024); } while (0)
; #define PG8_LDB(dst, b, h) do { _Pragma("unroll") for (int n = 0; n < 2; ++n) _Pragma("unroll") for (int k = 0; k < 2; ++k) dst[n][k] = *(const PG8_LAS bf16x8*)(lds + PG8_SB(b, h) + boff + n * 2048 + k * 1024); } while (0)
; #define PG8_MMA(ai, bj, At, Bt) do { __builtin_amdgcn_s_setprio(1); _Pragma("unroll") for (int m = 0; m < 4; ++m) _Pragma("unroll") for (int n = 0; n < 2; ++n) _Pragma("unroll") for (int k = 0; k < 2; ++k) \
;         acc[ai][bj][m][n] = __builtin_amdgcn_mfma_f32_16x16x32_bf16(Bt[n][k], At[m][k], acc[ai][bj][m][n], 0, 0, 0); __builtin_amdgcn_s_setprio(0); } while (0)
; #define PG8_WAIT_V(n) asm volatile("s_waitcnt vmcnt(" #n ")" ::: "memory")
; template <class Epi, class Sched, bool ALIGN_EPI = false, bool SP2 = false>
; __device__ __forceinline__ void gemm_phase(PG8_LAS unsigned char* lds, const Gemm g, const Sched& S, const Epi& E) {
;     ...
;         const char* nA = has_next ? (const char*)g.A + (size_t)nxt.pm * tstep : cA; const char* nB = has_next ? (const char*)g.Bt + (size_t)nxt.pn * tstep : cB;
;         for (int t = 0; t < nt; t += 2) {
;             const bool last = (t == nt - 2);
;             const char* a1 = cA + (size_t)(t + 1) * kstep;
;             const char* a2 = last ? nA : cA + (size_t)(t + 2) * kstep; const char* b2 = last ? nB : cB + (size_t)(t + 2) * kstep;
;             const char* a3 = a2 + kstep; const char* b3 = b2 + kstep;
;             if (last && has_next) S.a_ready(nxt);
;             if constexpr (SP2) {
;             PG8_LDB(B0, 0, 0); PG8_LDB(B1, 0, 1); PG8_SCHED; PG8_LDA(At, 0, 0); PG8_STAGE(PG8_SA(1, 1), a1 + hstep, voffA);
;             PG8_WAIT_V(8); PG8_WAIT_L(0); PG8_BAR; PG8_MMA(0, 0, At, B0); PG8_MMA(0, 1, At, B1); PG8_BAR; PG8_SCHED;
;             PG8_LDA(At, 0, 1); PG8_STAGE(PG8_SB(0, 0), b2, voffB); PG8_STAGE(PG8_SB(0, 1), b2 + hstep, voffB); PG8_STAGE(PG8_SA(0, 0), a2, voffA);
.LBB0_642:
	s_ashr_i32 s47, s46, 31
	s_lshl_b64 s[12:13], s[46:47], 19
	s_add_u32 s48, s16, s12
	s_addc_u32 s49, s17, s13
	s_and_b64 s[12:13], s[4:5], exec
	s_cselect_b32 s12, s49, s55
	s_cselect_b32 s13, s48, s54
	s_ashr_i32 s43, s42, 31
	s_lshl_b64 s[50:51], s[42:43], 19
	s_add_u32 s50, s18, s50
	s_addc_u32 s51, s19, s51
	s_and_b64 s[56:57], s[4:5], exec
	s_cselect_b32 s43, s51, s41
	s_cselect_b32 s47, s50, s40
	s_add_u32 s54, s54, 0x40080
	s_addc_u32 s55, s55, 0
	s_add_u32 s53, s40, 0x100
	s_addc_u32 s58, s41, 0
	s_mov_b32 s60, -2
	v_mov_b32_e32 v129, v0
	s_add_u32 s40, s54, 0xfffc0080
	s_addc_u32 s41, s55, -1
	s_add_i32 s61, 0, 0x10000
	s_cmp_eq_u32 s60, 12
	s_cselect_b32 s57, s12, s41
	s_cselect_b32 s56, s13, s40
	v_add_u32_e32 v140, s61, v143
	s_cselect_b32 s41, s43, s58
	s_cselect_b32 s40, s47, s53
	s_add_i32 s64, 0, 0x14000
	ds_read_b128 v[146:149], v140
	ds_read_b128 v[150:153], v140 offset:1024
	ds_read_b128 v[154:157], v140 offset:2048
	ds_read_b128 v[158:161], v140 offset:3072
	v_add_u32_e32 v140, s64, v143
	ds_read_b128 v[162:165], v140
	ds_read_b128 v[166:169], v140 offset:1024
	ds_read_b128 v[170:173], v140 offset:2048
	ds_read_b128 v[174:177], v140 offset:3072
	v_lshl_add_u64 v[140:141], s[54:55], 0, v[136:137]
	s_add_i32 m0, s21, 0xc000
	ds_read_b128 v[178:181], v145
	ds_read_b128 v[184:187], v145 offset:1024
	ds_read_b128 v[200:203], v145 offset:2048
	ds_read_b128 v[204:207], v145 offset:3072
	ds_read_b128 v[208:211], v145 offset:4096
	ds_read_b128 v[224:227], v145 offset:5120
	ds_read_b128 v[228:231], v145 offset:6144
	ds_read_b128 v[232:235], v145 offset:7168
	global_load_lds_dwordx4 v[140:141], off
	v_lshl_add_u64 v[140:141], s[54:55], 0, v[138:139]
	s_add_i32 m0, s21, 0xe000
	s_nop 0
	global_load_lds_dwordx4 v[140:141], off
	s_waitcnt vmcnt(8)
	s_waitcnt lgkmcnt(0)
	s_barrier
	s_setprio 1
	s_waitcnt lgkmcnt(0)
	v_mfma_f32_16x16x32_bf16 v[126:129], v[146:149], v[178:181], 0
	v_mfma_f32_16x16x32_bf16 v[122:125], v[154:157], v[178:181], 0
	v_mfma_f32_16x16x32_bf16 v[108:111], v[146:149], v[200:203], 0
	v_mfma_f32_16x16x32_bf16 v[104:107], v[154:157], v[200:203], 0
	v_mfma_f32_16x16x32_bf16 v[92:95], v[146:149], v[208:211], 0
	v_mfma_f32_16x16x32_bf16 v[88:91], v[154:157], v[208:211], 0
	v_mfma_f32_16x16x32_bf16 v[76:79], v[146:149], v[228:231], 0
	v_mfma_f32_16x16x32_bf16 v[72:75], v[154:157], v[228:231], 0
	v_mfma_f32_16x16x32_bf16 v[126:129], v[150:153], v[184:187], v[126:129]
	v_mfma_f32_16x16x32_bf16 v[122:125], v[158:161], v[184:187], v[122:125]
	v_mfma_f32_16x16x32_bf16 v[108:111], v[150:153], v[204:207], v[108:111]
	v_mfma_f32_16x16x32_bf16 v[104:107], v[158:161], v[204:207], v[104:107]
	v_mfma_f32_16x16x32_bf16 v[92:95], v[150:153], v[224:227], v[92:95]
	v_mfma_f32_16x16x32_bf16 v[88:91], v[158:161], v[224:227], v[88:91]
	v_mfma_f32_16x16x32_bf16 v[76:79], v[150:153], v[232:235], v[76:79]
	v_mfma_f32_16x16x32_bf16 v[72:75], v[158:161], v[232:235], v[72:75]
	s_setprio 0
	s_setprio 1
	v_mfma_f32_16x16x32_bf16 v[118:121], v[162:165], v[178:181], 0
	v_mfma_f32_16x16x32_bf16 v[114:117], v[170:173], v[178:181], 0
	v_mfma_f32_16x16x32_bf16 v[100:103], v[162:165], v[200:203], 0
	v_mfma_f32_16x16x32_bf16 v[96:99], v[170:173], v[200:203], 0
	v_mfma_f32_16x16x32_bf16 v[84:87], v[162:165], v[208:211], 0
	v_mfma_f32_16x16x32_bf16 v[80:83], v[170:173], v[208:211], 0
	v_mfma_f32_16x16x32_bf16 v[68:71], v[162:165], v[228:231], 0
	v_mfma_f32_16x16x32_bf16 v[64:67], v[170:173], v[228:231], 0
	v_mfma_f32_16x16x32_bf16 v[118:121], v[166:169], v[184:187], v[118:121]
	v_mfma_f32_16x16x32_bf16 v[114:117], v[174:177], v[184:187], v[114:117]
	v_mfma_f32_16x16x32_bf16 v[100:103], v[166:169], v[204:207], v[100:103]
	v_mfma_f32_16x16x32_bf16 v[96:99], v[174:177], v[204:207], v[96:99]
	v_mfma_f32_16x16x32_bf16 v[84:87], v[166:169], v[224:227], v[84:87]
	v_mfma_f32_16x16x32_bf16 v[80:83], v[174:177], v[224:227], v[80:83]
	v_mfma_f32_16x16x32_bf16 v[68:71], v[166:169], v[232:235], v[68:71]
	v_mfma_f32_16x16x32_bf16 v[64:67], v[174:177], v[232:235], v[64:67]
	s_setprio 0
	s_barrier
	s_add_i32 s61, s61, s20
	v_lshl_add_u64 v[140:141], s[40:41], 0, v[112:113]
	s_mov_b32 m0, s61
	ds_read_b128 v[178:181], v145 offset:16384
	ds_read_b128 v[184:187], v145 offset:17408
	ds_read_b128 v[200:203], v145 offset:18432
	ds_read_b128 v[204:207], v145 offset:19456
	ds_read_b128 v[208:211], v145 offset:20480
	ds_read_b128 v[224:227], v145 offset:21504
	ds_read_b128 v[228:231], v145 offset:22528
	ds_read_b128 v[232:235], v145 offset:23552
	global_load_lds_dwordx4 v[140:141], off
	s_add_i32 m0, s61, 0x2000
	s_add_u32 s62, s40, 0x40000
	v_lshl_add_u64 v[212:213], s[40:41], 0, v[134:135]
	s_addc_u32 s63, s41, 0
	s_add_i32 s61, s64, s20
	global_load_lds_dwordx4 v[212:213], off
	v_lshl_add_u64 v[236:237], s[62:63], 0, v[112:113]
	s_mov_b32 m0, s61
	v_lshl_add_u64 v[238:239], s[56:57], 0, v[132:133]
	global_load_lds_dwordx4 v[236:237], off
	v_lshl_add_u64 v[236:237], s[62:63], 0, v[134:135]
	s_add_i32 m0, s61, 0x2000
	s_nop 0
	global_load_lds_dwordx4 v[236:237], off
	v_lshl_add_u64 v[236:237], s[56:57], 0, v[130:131]
	s_mov_b32 m0, s21
	s_nop 0
	global_load_lds_dwordx4 v[236:237], off
	s_mov_b32 m0, s22
	s_nop 0
	global_load_lds_dwordx4 v[238:239], off
	s_waitcnt vmcnt(8)
	s_waitcnt lgkmcnt(0)
	s_barrier
; #define PG8_STAGE(bufoff, gbase, voff) do { _Pragma("unroll") for (int _i = 0; _i < 2; ++_i) \
;         __builtin_amdgcn_global_load_lds((const unsigned*)((const char*)(gbase) + (voff)[_i]), (PG8_LAS unsigned*)(lds + (bufoff) + ldsw + _i * 8192), 16, 0, 0); } while (0)
; #define PG8_LDA(dst, b, h) do { _Pragma("unroll") for (int m = 0; m < 4; ++m) _Pragma("unroll") for (int k = 0; k < 2; ++k) dst[m][k] = *(const PG8_LAS bf16x8*)(lds + PG8_SA(b, h) + aoff + m * 2048 + k * 1024); } while (0)
; #define PG8_LDB(dst, b, h) do { _Pragma("unroll") for (int n = 0; n < 2; ++n) _Pragma("unroll") for (int k = 0; k < 2; ++k) dst[n][k] = *(const PG8_LAS bf16x8*)(lds + PG8_SB(b, h) + boff + n * 2048 + k * 1024); } while (0)
; #define PG8_MMA(ai, bj, At, Bt) do { __builtin_amdgcn_s_setprio(1); _Pragma("unroll") for (int m = 0; m < 4; ++m) _Pragma("unroll") for (int n = 0; n < 2; ++n) _Pragma("unroll") for (int k = 0; k < 2; ++k) \
;         acc[ai][bj][m][n] = __builtin_amdgcn_mfma_f32_16x16x32_bf16(Bt[n][k], At[m][k], acc[ai][bj][m][n], 0, 0, 0); __builtin_amdgcn_s_setprio(0); } while (0)
; #define PG8_WAIT_V(n) asm volatile("s_waitcnt vmcnt(" #n ")" ::: "memory")
; #define PG8_WAIT_L(n) asm volatile("s_waitcnt lgkmcnt(" #n ")" ::: "memory")
; #define PG8_BAR __builtin_amdgcn_s_barrier()
; #define PG8_SCHED __builtin_amdgcn_sched_barrier(0)
; template <class Epi, class Sched, bool ALIGN_EPI = false, bool SP2 = false>
; __device__ __forceinline__ void gemm_phase(PG8_LAS unsigned char* lds, const Gemm g, const Sched& S, const Epi& E) {
;     ...
;             PG8_WAIT_V(8); PG8_WAIT_L(0); PG8_BAR; PG8_MMA(1, 0, At, B0); PG8_MMA(1, 1, At, B1); PG8_BAR; PG8_SCHED;
;             PG8_LDB(B0, 1, 0); PG8_LDB(B1, 1, 1); PG8_SCHED; PG8_LDA(At, 1, 0); PG8_STAGE(PG8_SA(0, 1), a2 + hstep, voffA);
;             PG8_WAIT_V(8); PG8_WAIT_L(0); PG8_BAR; PG8_MMA(0, 0, At, B0); PG8_MMA(0, 1, At, B1); PG8_BAR; PG8_SCHED;
	s_setprio 1
	s_waitcnt lgkmcnt(0)
	v_mfma_f32_16x16x32_bf16 v[60:63], v[146:149], v[178:181], 0
	v_mfma_f32_16x16x32_bf16 v[56:59], v[154:157], v[178:181], 0
	v_mfma_f32_16x16x32_bf16 v[44:47], v[146:149], v[200:203], 0
	v_mfma_f32_16x16x32_bf16 v[40:43], v[154:157], v[200:203], 0
	v_mfma_f32_16x16x32_bf16 v[28:31], v[146:149], v[208:211], 0
	v_mfma_f32_16x16x32_bf16 v[24:27], v[154:157], v[208:211], 0
	v_mfma_f32_16x16x32_bf16 v[12:15], v[146:149], v[228:231], 0
	v_mfma_f32_16x16x32_bf16 v[8:11], v[154:157], v[228:231], 0
	v_mfma_f32_16x16x32_bf16 v[60:63], v[150:153], v[184:187], v[60:63]
	v_mfma_f32_16x16x32_bf16 v[56:59], v[158:161], v[184:187], v[56:59]
	v_mfma_f32_16x16x32_bf16 v[44:47], v[150:153], v[204:207], v[44:47]
	v_mfma_f32_16x16x32_bf16 v[40:43], v[158:161], v[204:207], v[40:43]
	v_mfma_f32_16x16x32_bf16 v[28:31], v[150:153], v[224:227], v[28:31]
	v_mfma_f32_16x16x32_bf16 v[24:27], v[158:161], v[224:227], v[24:27]
	v_mfma_f32_16x16x32_bf16 v[12:15], v[150:153], v[232:235], v[12:15]
	v_mfma_f32_16x16x32_bf16 v[8:11], v[158:161], v[232:235], v[8:11]
	s_setprio 0
	s_setprio 1
	v_mfma_f32_16x16x32_bf16 v[52:55], v[162:165], v[178:181], 0
	v_mfma_f32_16x16x32_bf16 v[48:51], v[170:173], v[178:181], 0
	v_mfma_f32_16x16x32_bf16 v[36:39], v[162:165], v[200:203], 0
	v_mfma_f32_16x16x32_bf16 v[32:35], v[170:173], v[200:203], 0
	v_mfma_f32_16x16x32_bf16 v[20:23], v[162:165], v[208:211], 0
	v_mfma_f32_16x16x32_bf16 v[16:19], v[170:173], v[208:211], 0
	v_mfma_f32_16x16x32_bf16 v[4:7], v[162:165], v[228:231], 0
	v_mfma_f32_16x16x32_bf16 v[0:3], v[170:173], v[228:231], 0
	v_mfma_f32_16x16x32_bf16 v[52:55], v[166:169], v[184:187], v[52:55]
	v_mfma_f32_16x16x32_bf16 v[48:51], v[174:177], v[184:187], v[48:51]
	v_mfma_f32_16x16x32_bf16 v[36:39], v[166:169], v[204:207], v[36:39]
	v_mfma_f32_16x16x32_bf16 v[32:35], v[174:177], v[204:207], v[32:35]
	v_mfma_f32_16x16x32_bf16 v[20:23], v[166:169], v[224:227], v[20:23]
	v_mfma_f32_16x16x32_bf16 v[16:19], v[174:177], v[224:227], v[16:19]
	v_mfma_f32_16x16x32_bf16 v[4:7], v[166:169], v[232:235], v[4:7]
	v_mfma_f32_16x16x32_bf16 v[0:3], v[174:177], v[232:235], v[0:3]
	s_setprio 0
	s_barrier
	s_add_i32 s61, 0, 0x18000
	s_add_i32 s62, 0, 0x1c000
	v_add_u32_e32 v158, s61, v143
	v_add_u32_e32 v174, s62, v143
	ds_read_b128 v[146:149], v158
	ds_read_b128 v[150:153], v158 offset:1024
	ds_read_b128 v[154:157], v158 offset:2048
	ds_read_b128 v[158:161], v158 offset:3072
	ds_read_b128 v[162:165], v174
	ds_read_b128 v[166:169], v174 offset:1024
	ds_read_b128 v[170:173], v174 offset:2048
	ds_read_b128 v[174:177], v174 offset:3072
	s_add_u32 s56, s56, 0x40000
	s_addc_u32 s57, s57, 0
	s_mov_b32 m0, s23
	v_lshl_add_u64 v[240:241], s[56:57], 0, v[130:131]
	ds_read_b128 v[178:181], v145 offset:32768
	ds_read_b128 v[184:187], v145 offset:33792
	ds_read_b128 v[200:203], v145 offset:34816
	ds_read_b128 v[204:207], v145 offset:35840
	ds_read_b128 v[208:211], v145 offset:36864
	ds_read_b128 v[224:227], v145 offset:37888
	ds_read_b128 v[228:231], v145 offset:38912
	ds_read_b128 v[232:235], v145 offset:39936
	global_load_lds_dwordx4 v[240:241], off
	v_lshl_add_u64 v[240:241], s[56:57], 0, v[132:133]
	s_mov_b32 m0, s24
	s_nop 0
	global_load_lds_dwordx4 v[240:241], off
	s_waitcnt vmcnt(8)
	s_waitcnt lgkmcnt(0)
	s_barrier
	s_setprio 1
	s_waitcnt lgkmcnt(0)
	v_mfma_f32_16x16x32_bf16 v[126:129], v[146:149], v[178:181], v[126:129]
	v_mfma_f32_16x16x32_bf16 v[122:125], v[154:157], v[178:181], v[122:125]
	v_mfma_f32_16x16x32_bf16 v[108:111], v[146:149], v[200:203], v[108:111]
	v_mfma_f32_16x16x32_bf16 v[104:107], v[154:157], v[200:203], v[104:107]
	v_mfma_f32_16x16x32_bf16 v[92:95], v[146:149], v[208:211], v[92:95]
	v_mfma_f32_16x16x32_bf16 v[88:91], v[154:157], v[208:211], v[88:91]
	v_mfma_f32_16x16x32_bf16 v[76:79], v[146:149], v[228:231], v[76:79]
	v_mfma_f32_16x16x32_bf16 v[72:75], v[154:157], v[228:231], v[72:75]
	v_mfma_f32_16x16x32_bf16 v[126:129], v[150:153], v[184:187], v[126:129]
	v_mfma_f32_16x16x32_bf16 v[122:125], v[158:161], v[184:187], v[122:125]
	v_mfma_f32_16x16x32_bf16 v[108:111], v[150:153], v[204:207], v[108:111]
	v_mfma_f32_16x16x32_bf16 v[104:107], v[158:161], v[204:207], v[104:107]
	v_mfma_f32_16x16x32_bf16 v[92:95], v[150:153], v[224:227], v[92:95]
	v_mfma_f32_16x16x32_bf16 v[88:91], v[158:161], v[224:227], v[88:91]
	v_mfma_f32_16x16x32_bf16 v[76:79], v[150:153], v[232:235], v[76:79]
	v_mfma_f32_16x16x32_bf16 v[72:75], v[158:161], v[232:235], v[72:75]
	s_setprio 0
	s_setprio 1
	v_mfma_f32_16x16x32_bf16 v[118:121], v[162:165], v[178:181], v[118:121]
	v_mfma_f32_16x16x32_bf16 v[114:117], v[170:173], v[178:181], v[114:117]
	v_mfma_f32_16x16x32_bf16 v[100:103], v[162:165], v[200:203], v[100:103]
	v_mfma_f32_16x16x32_bf16 v[96:99], v[170:173], v[200:203], v[96:99]
	v_mfma_f32_16x16x32_bf16 v[84:87], v[162:165], v[208:211], v[84:87]
	v_mfma_f32_16x16x32_bf16 v[80:83], v[170:173], v[208:211], v[80:83]
	v_mfma_f32_16x16x32_bf16 v[68:71], v[162:165], v[228:231], v[68:71]
	v_mfma_f32_16x16x32_bf16 v[64:67], v[170:173], v[228:231], v[64:67]
	v_mfma_f32_16x16x32_bf16 v[118:121], v[166:169], v[184:187], v[118:121]
	v_mfma_f32_16x16x32_bf16 v[114:117], v[174:177], v[184:187], v[114:117]
	v_mfma_f32_16x16x32_bf16 v[100:103], v[166:169], v[204:207], v[100:103]
	v_mfma_f32_16x16x32_bf16 v[96:99], v[174:177], v[204:207], v[96:99]
	v_mfma_f32_16x16x32_bf16 v[84:87], v[166:169], v[224:227], v[84:87]
	v_mfma_f32_16x16x32_bf16 v[80:83], v[174:177], v[224:227], v[80:83]
	v_mfma_f32_16x16x32_bf16 v[68:71], v[166:169], v[232:235], v[68:71]
	v_mfma_f32_16x16x32_bf16 v[64:67], v[174:177], v[232:235], v[64:67]
	s_setprio 0
	s_barrier
; #define PG8_STAGE(bufoff, gbase, voff) do { _Pragma("unroll") for (int _i = 0; _i < 2; ++_i) \
;         __builtin_amdgcn_global_load_lds((const unsigned*)((const char*)(gbase) + (voff)[_i]), (PG8_LAS unsigned*)(lds + (bufoff) + ldsw + _i * 8192), 16, 0, 0); } while (0)
; #define PG8_LDA(dst, b, h) do { _Pragma("unroll") for (int m = 0; m < 4; ++m) _Pragma("unroll") for (int k = 0; k < 2; ++k) dst[m][k] = *(const PG8_LAS bf16x8*)(lds + PG8_SA(b, h) + aoff + m * 2048 + k * 1024); } while (0)
; #define PG8_MMA(ai, bj, At, Bt) do { __builtin_amdgcn_s_setprio(1); _Pragma("unroll") for (int m = 0; m < 4; ++m) _Pragma("unroll") for (int n = 0; n < 2; ++n) _Pragma("unroll") for (int k = 0; k < 2; ++k) \
;         acc[ai][bj][m][n] = __builtin_amdgcn_mfma_f32_16x16x32_bf16(Bt[n][k], At[m][k], acc[ai][bj][m][n], 0, 0, 0); __builtin_amdgcn_s_setprio(0); } while (0)
; #define PG8_WAIT_V(n) asm volatile("s_waitcnt vmcnt(" #n ")" ::: "memory")
; #define PG8_WAIT_L(n) asm volatile("s_waitcnt lgkmcnt(" #n ")" ::: "memory")
; #define PG8_BAR __builtin_amdgcn_s_barrier()
; #define PG8_SCHED __builtin_amdgcn_sched_barrier(0)
; template <class Epi, class Sched, bool ALIGN_EPI = false, bool SP2 = false>
; __device__ __forceinline__ void gemm_phase(PG8_LAS unsigned char* lds, const Gemm g, const Sched& S, const Epi& E) {
;     ...
;             PG8_LDA(At, 1, 1); PG8_STAGE(PG8_SB(1, 0), b3, voffB); PG8_STAGE(PG8_SB(1, 1), b3 + hstep, voffB); PG8_STAGE(PG8_SA(1, 0), a3, voffA);
;             PG8_WAIT_V(8); PG8_WAIT_L(0); PG8_BAR; PG8_MMA(1, 0, At, B0); PG8_MMA(1, 1, At, B1); PG8_BAR; PG8_SCHED;
	s_add_i32 s56, s61, s20
	v_lshl_add_u64 v[140:141], v[140:141], 0, s[36:37]
	s_mov_b32 m0, s56
	ds_read_b128 v[178:181], v145 offset:49152
	ds_read_b128 v[184:187], v145 offset:50176
	ds_read_b128 v[200:203], v145 offset:51200
	ds_read_b128 v[204:207], v145 offset:52224
	ds_read_b128 v[208:211], v145 offset:53248
	ds_read_b128 v[224:227], v145 offset:54272
	ds_read_b128 v[228:231], v145 offset:55296
	ds_read_b128 v[232:235], v145 offset:56320
	global_load_lds_dwordx4 v[140:141], off
	s_add_i32 m0, s56, 0x2000
	s_add_u32 s40, s40, 0x40080
	v_lshl_add_u64 v[140:141], v[212:213], 0, s[36:37]
	s_addc_u32 s41, s41, 0
	s_add_i32 s56, s62, s20
	global_load_lds_dwordx4 v[140:141], off
	v_lshl_add_u64 v[140:141], s[40:41], 0, v[112:113]
	s_mov_b32 m0, s56
	s_nop 0
	global_load_lds_dwordx4 v[140:141], off
	v_lshl_add_u64 v[140:141], s[40:41], 0, v[134:135]
	s_add_i32 m0, s56, 0x2000
	s_nop 0
	global_load_lds_dwordx4 v[140:141], off
	v_lshl_add_u64 v[140:141], v[236:237], 0, s[36:37]
	s_mov_b32 m0, s26
	s_nop 0
	global_load_lds_dwordx4 v[140:141], off
	v_lshl_add_u64 v[140:141], v[238:239], 0, s[36:37]
	s_mov_b32 m0, s33
	s_nop 0
	global_load_lds_dwordx4 v[140:141], off
	s_waitcnt vmcnt(8)
	s_waitcnt lgkmcnt(0)
	s_barrier
	s_setprio 1
	s_waitcnt lgkmcnt(0)
	v_mfma_f32_16x16x32_bf16 v[60:63], v[146:149], v[178:181], v[60:63]
	v_mfma_f32_16x16x32_bf16 v[56:59], v[154:157], v[178:181], v[56:59]
	v_mfma_f32_16x16x32_bf16 v[44:47], v[146:149], v[200:203], v[44:47]
	v_mfma_f32_16x16x32_bf16 v[40:43], v[154:157], v[200:203], v[40:43]
	v_mfma_f32_16x16x32_bf16 v[28:31], v[146:149], v[208:211], v[28:31]
	v_mfma_f32_16x16x32_bf16 v[24:27], v[154:157], v[208:211], v[24:27]
	v_mfma_f32_16x16x32_bf16 v[12:15], v[146:149], v[228:231], v[12:15]
	v_mfma_f32_16x16x32_bf16 v[8:11], v[154:157], v[228:231], v[8:11]
	v_mfma_f32_16x16x32_bf16 v[60:63], v[150:153], v[184:187], v[60:63]
	v_mfma_f32_16x16x32_bf16 v[56:59], v[158:161], v[184:187], v[56:59]
	v_mfma_f32_16x16x32_bf16 v[44:47], v[150:153], v[204:207], v[44:47]
	v_mfma_f32_16x16x32_bf16 v[40:43], v[158:161], v[204:207], v[40:43]
	v_mfma_f32_16x16x32_bf16 v[28:31], v[150:153], v[224:227], v[28:31]
	v_mfma_f32_16x16x32_bf16 v[24:27], v[158:161], v[224:227], v[24:27]
	v_mfma_f32_16x16x32_bf16 v[12:15], v[150:153], v[232:235], v[12:15]
	v_mfma_f32_16x16x32_bf16 v[8:11], v[158:161], v[232:235], v[8:11]
	s_setprio 0
	s_setprio 1
	v_mfma_f32_16x16x32_bf16 v[52:55], v[162:165], v[178:181], v[52:55]
	v_mfma_f32_16x16x32_bf16 v[48:51], v[170:173], v[178:181], v[48:51]
	v_mfma_f32_16x16x32_bf16 v[36:39], v[162:165], v[200:203], v[36:39]
	v_mfma_f32_16x16x32_bf16 v[32:35], v[170:173], v[200:203], v[32:35]
	v_mfma_f32_16x16x32_bf16 v[20:23], v[162:165], v[208:211], v[20:23]
	v_mfma_f32_16x16x32_bf16 v[16:19], v[170:173], v[208:211], v[16:19]
	v_mfma_f32_16x16x32_bf16 v[4:7], v[162:165], v[228:231], v[4:7]
	v_mfma_f32_16x16x32_bf16 v[0:3], v[170:173], v[228:231], v[0:3]
	v_mfma_f32_16x16x32_bf16 v[52:55], v[166:169], v[184:187], v[52:55]
	v_mfma_f32_16x16x32_bf16 v[48:51], v[174:177], v[184:187], v[48:51]
	v_mfma_f32_16x16x32_bf16 v[36:39], v[166:169], v[204:207], v[36:39]
	v_mfma_f32_16x16x32_bf16 v[32:35], v[174:177], v[204:207], v[32:35]
	v_mfma_f32_16x16x32_bf16 v[20:23], v[166:169], v[224:227], v[20:23]
	v_mfma_f32_16x16x32_bf16 v[16:19], v[174:177], v[224:227], v[16:19]
	v_mfma_f32_16x16x32_bf16 v[4:7], v[166:169], v[232:235], v[4:7]
	v_mfma_f32_16x16x32_bf16 v[0:3], v[174:177], v[232:235], v[0:3]
	s_setprio 0
	s_barrier
	s_add_i32 s60, s60, 2
	s_add_u32 s54, s54, 0x100
	s_addc_u32 s55, s55, 0
	s_add_u32 s53, s53, 0x100
	s_addc_u32 s58, s58, 0
	s_cmp_gt_u32 s60, 13


; #define PG8_STAGE(bufoff, gbase, voff) do { _Pragma("unroll") for (int _i = 0; _i < 2; ++_i) \
;         __builtin_amdgcn_global_load_lds((const unsigned*)((const char*)(gbase) + (voff)[_i]), (PG8_LAS unsigned*)(lds + (bufoff) + ldsw + _i * 8192), 16, 0, 0); } while (0)
; #define PG8_LDA(dst, b, h) do { _Pragma("unroll") for (int m = 0; m < 4; ++m) _Pragma("unroll") for (int k = 0; k < 2; ++k) dst[m][k] = *(const PG8_LAS bf16x8*)(lds + PG8_SA(b, h) + aoff + m * 2048 + k * 1024); } while (0)
; #define PG8_LDB(dst, b, h) do { _Pragma("unroll") for (int n = 0; n < 2; ++n) _Pragma("unroll") for (int k = 0; k < 2; ++k) dst[n][k] = *(const PG8_LAS bf16x8*)(lds + PG8_SB(b, h) + boff + n * 2048 + k * 1024); } while (0)
; #define PG8_MMA(ai, bj, At, Bt) do { __builtin_amdgcn_s_setprio(1); _Pragma("unroll") for (int m = 0; m < 4; ++m) _Pragma("unroll") for (int n = 0; n < 2; ++n) _Pragma("unroll") for (int k = 0; k < 2; ++k) \
;         acc[ai][bj][m][n] = __builtin_amdgcn_mfma_f32_16x16x32_bf16(Bt[n][k], At[m][k], acc[ai][bj][m][n], 0, 0, 0); __builtin_amdgcn_s_setprio(0); } while (0)
; #define PG8_WAIT_V(n) asm volatile("s_waitcnt vmcnt(" #n ")" ::: "memory")
; template <class Epi, class Sched, bool ALIGN_EPI = false, bool SP2 = false>
; __device__ __forceinline__ void gemm_phase(PG8_LAS unsigned char* lds, const Gemm g, const Sched& S, const Epi& E) {
;     ...
;         const char* nA = has_next ? (const char*)g.A + (size_t)nxt.pm * tstep : cA; const char* nB = has_next ? (const char*)g.Bt + (size_t)nxt.pn * tstep : cB;
;         for (int t = 0; t < nt; t += 2) {
;             const bool last = (t == nt - 2);
;             const char* a1 = cA + (size_t)(t + 1) * kstep;
;             const char* a2 = last ? nA : cA + (size_t)(t + 2) * kstep; const char* b2 = last ? nB : cB + (size_t)(t + 2) * kstep;
;             const char* a3 = a2 + kstep; const char* b3 = b2 + kstep;
;             if (last && has_next) S.a_ready(nxt);
;             if constexpr (SP2) {
;             PG8_LDB(B0, 0, 0); PG8_LDB(B1, 0, 1); PG8_SCHED; PG8_LDA(At, 0, 0); PG8_STAGE(PG8_SA(1, 1), a1 + hstep, voffA);
;             PG8_WAIT_V(8); PG8_WAIT_L(0); PG8_BAR; PG8_MMA(0, 0, At, B0); PG8_MMA(0, 1, At, B1); PG8_BAR; PG8_SCHED;
;             PG8_LDA(At, 0, 1); PG8_STAGE(PG8_SB(0, 0), b2, voffB); PG8_STAGE(PG8_SB(0, 1), b2 + hstep, voffB); PG8_STAGE(PG8_SA(0, 0), a2, voffA);
.LBB0_717:
	s_ashr_i32 s1, s0, 31
	s_lshl_b64 s[12:13], s[0:1], 21
	s_add_u32 s40, s15, s12
	s_addc_u32 s41, s16, s13
	s_and_b64 s[12:13], s[6:7], exec
	s_cselect_b32 s1, s41, s55
	s_cselect_b32 s51, s40, s54
	s_ashr_i32 s49, s48, 31
	s_lshl_b64 s[12:13], s[48:49], 21
	s_add_u32 s56, s17, s12
	s_addc_u32 s57, s18, s13
	s_and_b64 s[12:13], s[6:7], exec
	s_cselect_b32 s49, s57, s63
	s_cselect_b32 s58, s56, s62
	s_add_u32 s61, s62, 0x100
	s_addc_u32 s65, s63, 0
	s_mov_b32 s60, -2
	s_waitcnt lgkmcnt(0)
	v_mov_b32_e32 v129, v0
	s_add_u32 vcc_lo, s54, 0x100
	s_addc_u32 vcc_hi, s55, 0
	s_add_i32 s66, 0, 0x10000
	s_cmp_eq_u32 s60, 60
	s_cselect_b32 s13, s1, vcc_hi
	s_cselect_b32 s12, s51, vcc_lo
	s_cselect_b32 s63, s49, s65
	s_cselect_b32 s62, s58, s61
	s_add_i32 s67, 0, 0x14000
	v_add_u32_e32 v148, s66, v179
	v_add_u32_e32 v164, s67, v179
	ds_read_b128 v[136:139], v148
	ds_read_b128 v[140:143], v148 offset:1024
	ds_read_b128 v[144:147], v148 offset:2048
	ds_read_b128 v[148:151], v148 offset:3072
	ds_read_b128 v[152:155], v164
	ds_read_b128 v[156:159], v164 offset:1024
	ds_read_b128 v[160:163], v164 offset:2048
	ds_read_b128 v[164:167], v164 offset:3072
	v_lshl_add_u64 v[176:177], s[54:55], 0, v[132:133]
	s_add_i32 m0, s20, 0xc000
	ds_read_b128 v[168:171], v181
	ds_read_b128 v[172:175], v181 offset:1024
	ds_read_b128 v[184:187], v181 offset:2048
	ds_read_b128 v[200:203], v181 offset:3072
	ds_read_b128 v[204:207], v181 offset:4096
	ds_read_b128 v[208:211], v181 offset:5120
	ds_read_b128 v[224:227], v181 offset:6144
	ds_read_b128 v[228:231], v181 offset:7168
	global_load_lds_dwordx4 v[176:177], off
	v_lshl_add_u64 v[176:177], s[54:55], 0, v[134:135]
	s_add_i32 m0, s20, 0xe000
	s_nop 0
	global_load_lds_dwordx4 v[176:177], off
	s_waitcnt vmcnt(8)
	s_waitcnt lgkmcnt(0)
	s_barrier
	s_setprio 1
	s_waitcnt lgkmcnt(0)
	v_mfma_f32_16x16x32_bf16 v[126:129], v[136:139], v[168:171], 0
	v_mfma_f32_16x16x32_bf16 v[122:125], v[144:147], v[168:171], 0
	v_mfma_f32_16x16x32_bf16 v[108:111], v[136:139], v[184:187], 0
	v_mfma_f32_16x16x32_bf16 v[104:107], v[144:147], v[184:187], 0
	v_mfma_f32_16x16x32_bf16 v[92:95], v[136:139], v[204:207], 0
	v_mfma_f32_16x16x32_bf16 v[88:91], v[144:147], v[204:207], 0
	v_mfma_f32_16x16x32_bf16 v[76:79], v[136:139], v[224:227], 0
	v_mfma_f32_16x16x32_bf16 v[72:75], v[144:147], v[224:227], 0
	v_mfma_f32_16x16x32_bf16 v[126:129], v[140:143], v[172:175], v[126:129]
	v_mfma_f32_16x16x32_bf16 v[122:125], v[148:151], v[172:175], v[122:125]
	v_mfma_f32_16x16x32_bf16 v[108:111], v[140:143], v[200:203], v[108:111]
	v_mfma_f32_16x16x32_bf16 v[104:107], v[148:151], v[200:203], v[104:107]
	v_mfma_f32_16x16x32_bf16 v[92:95], v[140:143], v[208:211], v[92:95]
	v_mfma_f32_16x16x32_bf16 v[88:91], v[148:151], v[208:211], v[88:91]
	v_mfma_f32_16x16x32_bf16 v[76:79], v[140:143], v[228:231], v[76:79]
	v_mfma_f32_16x16x32_bf16 v[72:75], v[148:151], v[228:231], v[72:75]
	s_setprio 0
	s_setprio 1
	v_mfma_f32_16x16x32_bf16 v[118:121], v[152:155], v[168:171], 0
	v_mfma_f32_16x16x32_bf16 v[114:117], v[160:163], v[168:171], 0
	v_mfma_f32_16x16x32_bf16 v[100:103], v[152:155], v[184:187], 0
	v_mfma_f32_16x16x32_bf16 v[96:99], v[160:163], v[184:187], 0
	v_mfma_f32_16x16x32_bf16 v[84:87], v[152:155], v[204:207], 0
	v_mfma_f32_16x16x32_bf16 v[80:83], v[160:163], v[204:207], 0
	v_mfma_f32_16x16x32_bf16 v[68:71], v[152:155], v[224:227], 0
	v_mfma_f32_16x16x32_bf16 v[64:67], v[160:163], v[224:227], 0
	v_mfma_f32_16x16x32_bf16 v[118:121], v[156:159], v[172:175], v[118:121]
	v_mfma_f32_16x16x32_bf16 v[114:117], v[164:167], v[172:175], v[114:117]
	v_mfma_f32_16x16x32_bf16 v[100:103], v[156:159], v[200:203], v[100:103]
	v_mfma_f32_16x16x32_bf16 v[96:99], v[164:167], v[200:203], v[96:99]
	v_mfma_f32_16x16x32_bf16 v[84:87], v[156:159], v[208:211], v[84:87]
	v_mfma_f32_16x16x32_bf16 v[80:83], v[164:167], v[208:211], v[80:83]
	v_mfma_f32_16x16x32_bf16 v[68:71], v[156:159], v[228:231], v[68:71]
	v_mfma_f32_16x16x32_bf16 v[64:67], v[164:167], v[228:231], v[64:67]
	s_setprio 0
	s_barrier
	s_add_i32 s54, s66, s19
	v_lshl_add_u64 v[176:177], s[62:63], 0, v[112:113]
	s_mov_b32 m0, s54
	ds_read_b128 v[168:171], v181 offset:16384
	ds_read_b128 v[172:175], v181 offset:17408
	ds_read_b128 v[184:187], v181 offset:18432
	ds_read_b128 v[200:203], v181 offset:19456
	ds_read_b128 v[204:207], v181 offset:20480
	ds_read_b128 v[208:211], v181 offset:21504
	ds_read_b128 v[224:227], v181 offset:22528
	ds_read_b128 v[228:231], v181 offset:23552
	global_load_lds_dwordx4 v[176:177], off
	s_add_i32 m0, s54, 0x2000
	s_add_u32 s54, s62, 0x100000
	v_lshl_add_u64 v[212:213], s[62:63], 0, v[130:131]
	s_addc_u32 s55, s63, 0
	s_add_i32 s66, s67, s19
	global_load_lds_dwordx4 v[212:213], off
	v_lshl_add_u64 v[232:233], s[54:55], 0, v[112:113]
	s_mov_b32 m0, s66
	v_lshl_add_u64 v[234:235], s[12:13], 0, v[130:131]
	global_load_lds_dwordx4 v[232:233], off
	v_lshl_add_u64 v[232:233], s[54:55], 0, v[130:131]
	s_add_i32 m0, s66, 0x2000
	s_nop 0
	global_load_lds_dwordx4 v[232:233], off
	v_lshl_add_u64 v[232:233], s[12:13], 0, v[112:113]
	s_mov_b32 m0, s20
	s_nop 0
	global_load_lds_dwordx4 v[232:233], off
	s_mov_b32 m0, s21
	s_nop 0
	global_load_lds_dwordx4 v[234:235], off
	s_waitcnt vmcnt(8)
	s_waitcnt lgkmcnt(0)
	s_barrier
; #define PG8_STAGE(bufoff, gbase, voff) do { _Pragma("unroll") for (int _i = 0; _i < 2; ++_i) \
;         __builtin_amdgcn_global_load_lds((const unsigned*)((const char*)(gbase) + (voff)[_i]), (PG8_LAS unsigned*)(lds + (bufoff) + ldsw + _i * 8192), 16, 0, 0); } while (0)
; #define PG8_LDA(dst, b, h) do { _Pragma("unroll") for (int m = 0; m < 4; ++m) _Pragma("unroll") for (int k = 0; k < 2; ++k) dst[m][k] = *(const PG8_LAS bf16x8*)(lds + PG8_SA(b, h) + aoff + m * 2048 + k * 1024); } while (0)
; #define PG8_LDB(dst, b, h) do { _Pragma("unroll") for (int n = 0; n < 2; ++n) _Pragma("unroll") for (int k = 0; k < 2; ++k) dst[n][k] = *(const PG8_LAS bf16x8*)(lds + PG8_SB(b, h) + boff + n * 2048 + k * 1024); } while (0)
; #define PG8_MMA(ai, bj, At, Bt) do { __builtin_amdgcn_s_setprio(1); _Pragma("unroll") for (int m = 0; m < 4; ++m) _Pragma("unroll") for (int n = 0; n < 2; ++n) _Pragma("unroll") for (int k = 0; k < 2; ++k) \
;         acc[ai][bj][m][n] = __builtin_amdgcn_mfma_f32_16x16x32_bf16(Bt[n][k], At[m][k], acc[ai][bj][m][n], 0, 0, 0); __builtin_amdgcn_s_setprio(0); } while (0)
; #define PG8_WAIT_V(n) asm volatile("s_waitcnt vmcnt(" #n ")" ::: "memory")
; #define PG8_WAIT_L(n) asm volatile("s_waitcnt lgkmcnt(" #n ")" ::: "memory")
; #define PG8_BAR __builtin_amdgcn_s_barrier()
; #define PG8_SCHED __builtin_amdgcn_sched_barrier(0)
; template <class Epi, class Sched, bool ALIGN_EPI = false, bool SP2 = false>
; __device__ __forceinline__ void gemm_phase(PG8_LAS unsigned char* lds, const Gemm g, const Sched& S, const Epi& E) {
;     ...
;             PG8_WAIT_V(8); PG8_WAIT_L(0); PG8_BAR; PG8_MMA(1, 0, At, B0); PG8_MMA(1, 1, At, B1); PG8_BAR; PG8_SCHED;
;             PG8_LDB(B0, 1, 0); PG8_LDB(B1, 1, 1); PG8_SCHED; PG8_LDA(At, 1, 0); PG8_STAGE(PG8_SA(0, 1), a2 + hstep, voffA);
;             PG8_WAIT_V(8); PG8_WAIT_L(0); PG8_BAR; PG8_MMA(0, 0, At, B0); PG8_MMA(0, 1, At, B1); PG8_BAR; PG8_SCHED;
	s_setprio 1
	s_waitcnt lgkmcnt(0)
	v_mfma_f32_16x16x32_bf16 v[60:63], v[136:139], v[168:171], 0
	v_mfma_f32_16x16x32_bf16 v[56:59], v[144:147], v[168:171], 0
	v_mfma_f32_16x16x32_bf16 v[44:47], v[136:139], v[184:187], 0
	v_mfma_f32_16x16x32_bf16 v[40:43], v[144:147], v[184:187], 0
	v_mfma_f32_16x16x32_bf16 v[28:31], v[136:139], v[204:207], 0
	v_mfma_f32_16x16x32_bf16 v[24:27], v[144:147], v[204:207], 0
	v_mfma_f32_16x16x32_bf16 v[12:15], v[136:139], v[224:227], 0
	v_mfma_f32_16x16x32_bf16 v[8:11], v[144:147], v[224:227], 0
	v_mfma_f32_16x16x32_bf16 v[60:63], v[140:143], v[172:175], v[60:63]
	v_mfma_f32_16x16x32_bf16 v[56:59], v[148:151], v[172:175], v[56:59]
	v_mfma_f32_16x16x32_bf16 v[44:47], v[140:143], v[200:203], v[44:47]
	v_mfma_f32_16x16x32_bf16 v[40:43], v[148:151], v[200:203], v[40:43]
	v_mfma_f32_16x16x32_bf16 v[28:31], v[140:143], v[208:211], v[28:31]
	v_mfma_f32_16x16x32_bf16 v[24:27], v[148:151], v[208:211], v[24:27]
	v_mfma_f32_16x16x32_bf16 v[12:15], v[140:143], v[228:231], v[12:15]
	v_mfma_f32_16x16x32_bf16 v[8:11], v[148:151], v[228:231], v[8:11]
	s_setprio 0
	s_setprio 1
	v_mfma_f32_16x16x32_bf16 v[52:55], v[152:155], v[168:171], 0
	v_mfma_f32_16x16x32_bf16 v[48:51], v[160:163], v[168:171], 0
	v_mfma_f32_16x16x32_bf16 v[36:39], v[152:155], v[184:187], 0
	v_mfma_f32_16x16x32_bf16 v[32:35], v[160:163], v[184:187], 0
	v_mfma_f32_16x16x32_bf16 v[20:23], v[152:155], v[204:207], 0
	v_mfma_f32_16x16x32_bf16 v[16:19], v[160:163], v[204:207], 0
	v_mfma_f32_16x16x32_bf16 v[4:7], v[152:155], v[224:227], 0
	v_mfma_f32_16x16x32_bf16 v[0:3], v[160:163], v[224:227], 0
	v_mfma_f32_16x16x32_bf16 v[52:55], v[156:159], v[172:175], v[52:55]
	v_mfma_f32_16x16x32_bf16 v[48:51], v[164:167], v[172:175], v[48:51]
	v_mfma_f32_16x16x32_bf16 v[36:39], v[156:159], v[200:203], v[36:39]
	v_mfma_f32_16x16x32_bf16 v[32:35], v[164:167], v[200:203], v[32:35]
	v_mfma_f32_16x16x32_bf16 v[20:23], v[156:159], v[208:211], v[20:23]
	v_mfma_f32_16x16x32_bf16 v[16:19], v[164:167], v[208:211], v[16:19]
	v_mfma_f32_16x16x32_bf16 v[4:7], v[156:159], v[228:231], v[4:7]
	v_mfma_f32_16x16x32_bf16 v[0:3], v[164:167], v[228:231], v[0:3]
	s_setprio 0
	s_barrier
	s_add_i32 s54, 0, 0x18000
	s_add_i32 s55, 0, 0x1c000
	v_add_u32_e32 v148, s54, v179
	v_add_u32_e32 v164, s55, v179
	ds_read_b128 v[136:139], v148
	ds_read_b128 v[140:143], v148 offset:1024
	ds_read_b128 v[144:147], v148 offset:2048
	ds_read_b128 v[148:151], v148 offset:3072
	ds_read_b128 v[152:155], v164
	ds_read_b128 v[156:159], v164 offset:1024
	ds_read_b128 v[160:163], v164 offset:2048
	ds_read_b128 v[164:167], v164 offset:3072
	s_add_u32 s12, s12, 0x100000
	s_addc_u32 s13, s13, 0
	s_mov_b32 m0, s22
	v_lshl_add_u64 v[236:237], s[12:13], 0, v[112:113]
	ds_read_b128 v[168:171], v181 offset:32768
	ds_read_b128 v[172:175], v181 offset:33792
	ds_read_b128 v[184:187], v181 offset:34816
	ds_read_b128 v[200:203], v181 offset:35840
	ds_read_b128 v[204:207], v181 offset:36864
	ds_read_b128 v[208:211], v181 offset:37888
	ds_read_b128 v[224:227], v181 offset:38912
	ds_read_b128 v[228:231], v181 offset:39936
	global_load_lds_dwordx4 v[236:237], off
	v_lshl_add_u64 v[236:237], s[12:13], 0, v[130:131]
	s_mov_b32 m0, s23
	s_nop 0
	global_load_lds_dwordx4 v[236:237], off
	s_waitcnt vmcnt(8)
	s_waitcnt lgkmcnt(0)
	s_barrier
	s_setprio 1
	s_waitcnt lgkmcnt(0)
	v_mfma_f32_16x16x32_bf16 v[126:129], v[136:139], v[168:171], v[126:129]
	v_mfma_f32_16x16x32_bf16 v[122:125], v[144:147], v[168:171], v[122:125]
	v_mfma_f32_16x16x32_bf16 v[108:111], v[136:139], v[184:187], v[108:111]
	v_mfma_f32_16x16x32_bf16 v[104:107], v[144:147], v[184:187], v[104:107]
	v_mfma_f32_16x16x32_bf16 v[92:95], v[136:139], v[204:207], v[92:95]
	v_mfma_f32_16x16x32_bf16 v[88:91], v[144:147], v[204:207], v[88:91]
	v_mfma_f32_16x16x32_bf16 v[76:79], v[136:139], v[224:227], v[76:79]
	v_mfma_f32_16x16x32_bf16 v[72:75], v[144:147], v[224:227], v[72:75]
	v_mfma_f32_16x16x32_bf16 v[126:129], v[140:143], v[172:175], v[126:129]
	v_mfma_f32_16x16x32_bf16 v[122:125], v[148:151], v[172:175], v[122:125]
	v_mfma_f32_16x16x32_bf16 v[108:111], v[140:143], v[200:203], v[108:111]
	v_mfma_f32_16x16x32_bf16 v[104:107], v[148:151], v[200:203], v[104:107]
	v_mfma_f32_16x16x32_bf16 v[92:95], v[140:143], v[208:211], v[92:95]
	v_mfma_f32_16x16x32_bf16 v[88:91], v[148:151], v[208:211], v[88:91]
	v_mfma_f32_16x16x32_bf16 v[76:79], v[140:143], v[228:231], v[76:79]
	v_mfma_f32_16x16x32_bf16 v[72:75], v[148:151], v[228:231], v[72:75]
	s_setprio 0
	s_setprio 1
	v_mfma_f32_16x16x32_bf16 v[118:121], v[152:155], v[168:171], v[118:121]
	v_mfma_f32_16x16x32_bf16 v[114:117], v[160:163], v[168:171], v[114:117]
	v_mfma_f32_16x16x32_bf16 v[100:103], v[152:155], v[184:187], v[100:103]
	v_mfma_f32_16x16x32_bf16 v[96:99], v[160:163], v[184:187], v[96:99]
	v_mfma_f32_16x16x32_bf16 v[84:87], v[152:155], v[204:207], v[84:87]
	v_mfma_f32_16x16x32_bf16 v[80:83], v[160:163], v[204:207], v[80:83]
	v_mfma_f32_16x16x32_bf16 v[68:71], v[152:155], v[224:227], v[68:71]
	v_mfma_f32_16x16x32_bf16 v[64:67], v[160:163], v[224:227], v[64:67]
	v_mfma_f32_16x16x32_bf16 v[118:121], v[156:159], v[172:175], v[118:121]
	v_mfma_f32_16x16x32_bf16 v[114:117], v[164:167], v[172:175], v[114:117]
	v_mfma_f32_16x16x32_bf16 v[100:103], v[156:159], v[200:203], v[100:103]
	v_mfma_f32_16x16x32_bf16 v[96:99], v[164:167], v[200:203], v[96:99]
	v_mfma_f32_16x16x32_bf16 v[84:87], v[156:159], v[208:211], v[84:87]
	v_mfma_f32_16x16x32_bf16 v[80:83], v[164:167], v[208:211], v[80:83]
	v_mfma_f32_16x16x32_bf16 v[68:71], v[156:159], v[228:231], v[68:71]
	v_mfma_f32_16x16x32_bf16 v[64:67], v[164:167], v[228:231], v[64:67]
	s_setprio 0
	s_barrier
; #define PG8_STAGE(bufoff, gbase, voff) do { _Pragma("unroll") for (int _i = 0; _i < 2; ++_i) \
;         __builtin_amdgcn_global_load_lds((const unsigned*)((const char*)(gbase) + (voff)[_i]), (PG8_LAS unsigned*)(lds + (bufoff) + ldsw + _i * 8192), 16, 0, 0); } while (0)
; #define PG8_LDA(dst, b, h) do { _Pragma("unroll") for (int m = 0; m < 4; ++m) _Pragma("unroll") for (int k = 0; k < 2; ++k) dst[m][k] = *(const PG8_LAS bf16x8*)(lds + PG8_SA(b, h) + aoff + m * 2048 + k * 1024); } while (0)
; #define PG8_MMA(ai, bj, At, Bt) do { __builtin_amdgcn_s_setprio(1); _Pragma("unroll") for (int m = 0; m < 4; ++m) _Pragma("unroll") for (int n = 0; n < 2; ++n) _Pragma("unroll") for (int k = 0; k < 2; ++k) \
;         acc[ai][bj][m][n] = __builtin_amdgcn_mfma_f32_16x16x32_bf16(Bt[n][k], At[m][k], acc[ai][bj][m][n], 0, 0, 0); __builtin_amdgcn_s_setprio(0); } while (0)
; #define PG8_WAIT_V(n) asm volatile("s_waitcnt vmcnt(" #n ")" ::: "memory")
; #define PG8_WAIT_L(n) asm volatile("s_waitcnt lgkmcnt(" #n ")" ::: "memory")
; #define PG8_BAR __builtin_amdgcn_s_barrier()
; #define PG8_SCHED __builtin_amdgcn_sched_barrier(0)
; template <class Epi, class Sched, bool ALIGN_EPI = false, bool SP2 = false>
; __device__ __forceinline__ void gemm_phase(PG8_LAS unsigned char* lds, const Gemm g, const Sched& S, const Epi& E) {
;     ...
;             PG8_LDA(At, 1, 1); PG8_STAGE(PG8_SB(1, 0), b3, voffB); PG8_STAGE(PG8_SB(1, 1), b3 + hstep, voffB); PG8_STAGE(PG8_SA(1, 0), a3, voffA);
;             PG8_WAIT_V(8); PG8_WAIT_L(0); PG8_BAR; PG8_MMA(1, 0, At, B0); PG8_MMA(1, 1, At, B1); PG8_BAR; PG8_SCHED;
	s_add_i32 s12, s54, s19
	v_lshl_add_u64 v[176:177], v[176:177], 0, s[36:37]
	s_mov_b32 m0, s12
	ds_read_b128 v[168:171], v181 offset:49152
	ds_read_b128 v[172:175], v181 offset:50176
	ds_read_b128 v[184:187], v181 offset:51200
	ds_read_b128 v[200:203], v181 offset:52224
	ds_read_b128 v[204:207], v181 offset:53248
	ds_read_b128 v[208:211], v181 offset:54272
	ds_read_b128 v[224:227], v181 offset:55296
	ds_read_b128 v[228:231], v181 offset:56320
	global_load_lds_dwordx4 v[176:177], off
	s_add_i32 m0, s12, 0x2000
	s_add_u32 s12, s62, 0x100080
	v_lshl_add_u64 v[176:177], v[212:213], 0, s[36:37]
	s_addc_u32 s13, s63, 0
	s_add_i32 s54, s55, s19
	global_load_lds_dwordx4 v[176:177], off
	v_lshl_add_u64 v[176:177], s[12:13], 0, v[112:113]
	s_mov_b32 m0, s54
	s_nop 0
	global_load_lds_dwordx4 v[176:177], off
	v_lshl_add_u64 v[176:177], s[12:13], 0, v[130:131]
	s_add_i32 m0, s54, 0x2000
	s_nop 0
	global_load_lds_dwordx4 v[176:177], off
	v_lshl_add_u64 v[176:177], v[232:233], 0, s[36:37]
	s_mov_b32 m0, s26
	s_nop 0
	global_load_lds_dwordx4 v[176:177], off
	v_lshl_add_u64 v[176:177], v[234:235], 0, s[36:37]
	s_mov_b32 m0, s33
	s_nop 0
	global_load_lds_dwordx4 v[176:177], off
	s_waitcnt vmcnt(8)
	s_waitcnt lgkmcnt(0)
	s_barrier
	s_setprio 1
	s_waitcnt lgkmcnt(0)
	v_mfma_f32_16x16x32_bf16 v[60:63], v[136:139], v[168:171], v[60:63]
	v_mfma_f32_16x16x32_bf16 v[56:59], v[144:147], v[168:171], v[56:59]
	v_mfma_f32_16x16x32_bf16 v[44:47], v[136:139], v[184:187], v[44:47]
	v_mfma_f32_16x16x32_bf16 v[40:43], v[144:147], v[184:187], v[40:43]
	v_mfma_f32_16x16x32_bf16 v[28:31], v[136:139], v[204:207], v[28:31]
	v_mfma_f32_16x16x32_bf16 v[24:27], v[144:147], v[204:207], v[24:27]
	v_mfma_f32_16x16x32_bf16 v[12:15], v[136:139], v[224:227], v[12:15]
	v_mfma_f32_16x16x32_bf16 v[8:11], v[144:147], v[224:227], v[8:11]
	v_mfma_f32_16x16x32_bf16 v[60:63], v[140:143], v[172:175], v[60:63]
	v_mfma_f32_16x16x32_bf16 v[56:59], v[148:151], v[172:175], v[56:59]
	v_mfma_f32_16x16x32_bf16 v[44:47], v[140:143], v[200:203], v[44:47]
	v_mfma_f32_16x16x32_bf16 v[40:43], v[148:151], v[200:203], v[40:43]
	v_mfma_f32_16x16x32_bf16 v[28:31], v[140:143], v[208:211], v[28:31]
	v_mfma_f32_16x16x32_bf16 v[24:27], v[148:151], v[208:211], v[24:27]
	v_mfma_f32_16x16x32_bf16 v[12:15], v[140:143], v[228:231], v[12:15]
	v_mfma_f32_16x16x32_bf16 v[8:11], v[148:151], v[228:231], v[8:11]
	s_setprio 0
	s_setprio 1
	v_mfma_f32_16x16x32_bf16 v[52:55], v[152:155], v[168:171], v[52:55]
	v_mfma_f32_16x16x32_bf16 v[48:51], v[160:163], v[168:171], v[48:51]
	v_mfma_f32_16x16x32_bf16 v[36:39], v[152:155], v[184:187], v[36:39]
	v_mfma_f32_16x16x32_bf16 v[32:35], v[160:163], v[184:187], v[32:35]
	v_mfma_f32_16x16x32_bf16 v[20:23], v[152:155], v[204:207], v[20:23]
	v_mfma_f32_16x16x32_bf16 v[16:19], v[160:163], v[204:207], v[16:19]
	v_mfma_f32_16x16x32_bf16 v[4:7], v[152:155], v[224:227], v[4:7]
	v_mfma_f32_16x16x32_bf16 v[0:3], v[160:163], v[224:227], v[0:3]
	v_mfma_f32_16x16x32_bf16 v[52:55], v[156:159], v[172:175], v[52:55]
	v_mfma_f32_16x16x32_bf16 v[48:51], v[164:167], v[172:175], v[48:51]
	v_mfma_f32_16x16x32_bf16 v[36:39], v[156:159], v[200:203], v[36:39]
	v_mfma_f32_16x16x32_bf16 v[32:35], v[164:167], v[200:203], v[32:35]
	v_mfma_f32_16x16x32_bf16 v[20:23], v[156:159], v[208:211], v[20:23]
	v_mfma_f32_16x16x32_bf16 v[16:19], v[164:167], v[208:211], v[16:19]
	v_mfma_f32_16x16x32_bf16 v[4:7], v[156:159], v[228:231], v[4:7]
	v_mfma_f32_16x16x32_bf16 v[0:3], v[164:167], v[228:231], v[0:3]
	s_setprio 0
	s_barrier
	s_add_i32 s60, s60, 2
	s_add_u32 s61, s61, 0x100
	s_addc_u32 s65, s65, 0
	s_cmp_gt_u32 s60, 61
	s_mov_b64 s[54:55], vcc


; #define PG8_STAGE(bufoff, gbase, voff) do { _Pragma("unroll") for (int _i = 0; _i < 2; ++_i) \
;         __builtin_amdgcn_global_load_lds((const unsigned*)((const char*)(gbase) + (voff)[_i]), (PG8_LAS unsigned*)(lds + (bufoff) + ldsw + _i * 8192), 16, 0, 0); } while (0)
; #define PG8_LDA(dst, b, h) do { _Pragma("unroll") for (int m = 0; m < 4; ++m) _Pragma("unroll") for (int k = 0; k < 2; ++k) dst[m][k] = *(const PG8_LAS bf16x8*)(lds + PG8_SA(b, h) + aoff + m * 2048 + k * 1024); } while (0)
; #define PG8_LDB(dst, b, h) do { _Pragma("unroll") for (int n = 0; n < 2; ++n) _Pragma("unroll") for (int k = 0; k < 2; ++k) dst[n][k] = *(const PG8_LAS bf16x8*)(lds + PG8_SB(b, h) + boff + n * 2048 + k * 1024); } while (0)
; #define PG8_MMA(ai, bj, At, Bt) do { __builtin_amdgcn_s_setprio(1); _Pragma("unroll") for (int m = 0; m < 4; ++m) _Pragma("unroll") for (int n = 0; n < 2; ++n) _Pragma("unroll") for (int k = 0; k < 2; ++k) \
;         acc[ai][bj][m][n] = __builtin_amdgcn_mfma_f32_16x16x32_bf16(Bt[n][k], At[m][k], acc[ai][bj][m][n], 0, 0, 0); __builtin_amdgcn_s_setprio(0); } while (0)
; #define PG8_WAIT_V(n) asm volatile("s_waitcnt vmcnt(" #n ")" ::: "memory")
; template <class Epi, class Sched, bool ALIGN_EPI = false, bool SP2 = false>
; __device__ __forceinline__ void gemm_phase(PG8_LAS unsigned char* lds, const Gemm g, const Sched& S, const Epi& E) {
;     ...
;         const char* nA = has_next ? (const char*)g.A + (size_t)nxt.pm * tstep : cA; const char* nB = has_next ? (const char*)g.Bt + (size_t)nxt.pn * tstep : cB;
;         for (int t = 0; t < nt; t += 2) {
;             const bool last = (t == nt - 2);
;             const char* a1 = cA + (size_t)(t + 1) * kstep;
;             const char* a2 = last ? nA : cA + (size_t)(t + 2) * kstep; const char* b2 = last ? nB : cB + (size_t)(t + 2) * kstep;
;             const char* a3 = a2 + kstep; const char* b3 = b2 + kstep;
;             if (last && has_next) S.a_ready(nxt);
;             if constexpr (SP2) {
;             PG8_LDB(B0, 0, 0); PG8_LDB(B1, 0, 1); PG8_SCHED; PG8_LDA(At, 0, 0); PG8_STAGE(PG8_SA(1, 1), a1 + hstep, voffA);
;             PG8_WAIT_V(8); PG8_WAIT_L(0); PG8_BAR; PG8_MMA(0, 0, At, B0); PG8_MMA(0, 1, At, B1); PG8_BAR; PG8_SCHED;
;             PG8_LDA(At, 0, 1); PG8_STAGE(PG8_SB(0, 0), b2, voffB); PG8_STAGE(PG8_SB(0, 1), b2 + hstep, voffB); PG8_STAGE(PG8_SA(0, 0), a2, voffA);
.LBB0_759:
	s_ashr_i32 s47, s46, 31
	s_lshl_b64 s[12:13], s[46:47], 21
	s_add_u32 s48, s15, s12
	s_addc_u32 s49, s16, s13
	s_and_b64 s[12:13], s[4:5], exec
	s_cselect_b32 s47, s49, s55
	s_cselect_b32 s53, s48, s54
	s_ashr_i32 s43, s42, 31
	s_lshl_b64 s[12:13], s[42:43], 21
	s_add_u32 s50, s17, s12
	s_addc_u32 s51, s18, s13
	s_and_b64 s[12:13], s[4:5], exec
	s_cselect_b32 s43, s51, s41
	s_cselect_b32 s56, s50, s40
	s_add_u32 s54, s54, 0x100080
	s_addc_u32 s55, s55, 0
	s_add_u32 s57, s40, 0x100
	s_addc_u32 s58, s41, 0
	s_mov_b32 s60, -2
	v_mov_b32_e32 v129, v0
	s_add_u32 s12, s54, 0xfff00080
	s_addc_u32 s13, s55, -1
	s_add_i32 s61, 0, 0x10000
	s_cmp_eq_u32 s60, 60
	s_cselect_b32 s13, s47, s13
	s_cselect_b32 s12, s53, s12
	s_cselect_b32 s41, s43, s58
	s_cselect_b32 s40, s56, s57
	s_add_i32 s64, 0, 0x14000
	v_add_u32_e32 v152, s61, v141
	v_add_u32_e32 v168, s64, v141
	ds_read_b128 v[136:139], v152
	ds_read_b128 v[144:147], v152 offset:1024
	ds_read_b128 v[148:151], v152 offset:2048
	ds_read_b128 v[152:155], v152 offset:3072
	ds_read_b128 v[156:159], v168
	ds_read_b128 v[160:163], v168 offset:1024
	ds_read_b128 v[164:167], v168 offset:2048
	ds_read_b128 v[168:171], v168 offset:3072
	v_lshl_add_u64 v[180:181], s[54:55], 0, v[132:133]
	s_add_i32 m0, s21, 0xc000
	ds_read_b128 v[172:175], v143
	ds_read_b128 v[176:179], v143 offset:1024
	ds_read_b128 v[184:187], v143 offset:2048
	ds_read_b128 v[200:203], v143 offset:3072
	ds_read_b128 v[204:207], v143 offset:4096
	ds_read_b128 v[208:211], v143 offset:5120
	ds_read_b128 v[222:225], v143 offset:6144
	ds_read_b128 v[226:229], v143 offset:7168
	global_load_lds_dwordx4 v[180:181], off
	v_lshl_add_u64 v[180:181], s[54:55], 0, v[134:135]
	s_add_i32 m0, s21, 0xe000
	s_nop 0
	global_load_lds_dwordx4 v[180:181], off
	s_waitcnt vmcnt(8)
	s_waitcnt lgkmcnt(0)
	s_barrier
	s_setprio 1
	s_waitcnt lgkmcnt(0)
	v_mfma_f32_16x16x32_bf16 v[126:129], v[136:139], v[172:175], 0
	v_mfma_f32_16x16x32_bf16 v[122:125], v[148:151], v[172:175], 0
	v_mfma_f32_16x16x32_bf16 v[114:117], v[136:139], v[184:187], 0
	v_mfma_f32_16x16x32_bf16 v[104:107], v[148:151], v[184:187], 0
	v_mfma_f32_16x16x32_bf16 v[96:99], v[136:139], v[204:207], 0
	v_mfma_f32_16x16x32_bf16 v[88:91], v[148:151], v[204:207], 0
	v_mfma_f32_16x16x32_bf16 v[80:83], v[136:139], v[222:225], 0
	v_mfma_f32_16x16x32_bf16 v[72:75], v[148:151], v[222:225], 0
	v_mfma_f32_16x16x32_bf16 v[126:129], v[144:147], v[176:179], v[126:129]
	v_mfma_f32_16x16x32_bf16 v[122:125], v[152:155], v[176:179], v[122:125]
	v_mfma_f32_16x16x32_bf16 v[114:117], v[144:147], v[200:203], v[114:117]
	v_mfma_f32_16x16x32_bf16 v[104:107], v[152:155], v[200:203], v[104:107]
	v_mfma_f32_16x16x32_bf16 v[96:99], v[144:147], v[208:211], v[96:99]
	v_mfma_f32_16x16x32_bf16 v[88:91], v[152:155], v[208:211], v[88:91]
	v_mfma_f32_16x16x32_bf16 v[80:83], v[144:147], v[226:229], v[80:83]
	v_mfma_f32_16x16x32_bf16 v[72:75], v[152:155], v[226:229], v[72:75]
	s_setprio 0
	s_setprio 1
	v_mfma_f32_16x16x32_bf16 v[118:121], v[156:159], v[172:175], 0
	v_mfma_f32_16x16x32_bf16 v[108:111], v[164:167], v[172:175], 0
	v_mfma_f32_16x16x32_bf16 v[100:103], v[156:159], v[184:187], 0
	v_mfma_f32_16x16x32_bf16 v[92:95], v[164:167], v[184:187], 0
	v_mfma_f32_16x16x32_bf16 v[84:87], v[156:159], v[204:207], 0
	v_mfma_f32_16x16x32_bf16 v[76:79], v[164:167], v[204:207], 0
	v_mfma_f32_16x16x32_bf16 v[68:71], v[156:159], v[222:225], 0
	v_mfma_f32_16x16x32_bf16 v[64:67], v[164:167], v[222:225], 0
	v_mfma_f32_16x16x32_bf16 v[118:121], v[160:163], v[176:179], v[118:121]
	v_mfma_f32_16x16x32_bf16 v[108:111], v[168:171], v[176:179], v[108:111]
	v_mfma_f32_16x16x32_bf16 v[100:103], v[160:163], v[200:203], v[100:103]
	v_mfma_f32_16x16x32_bf16 v[92:95], v[168:171], v[200:203], v[92:95]
	v_mfma_f32_16x16x32_bf16 v[84:87], v[160:163], v[208:211], v[84:87]
	v_mfma_f32_16x16x32_bf16 v[76:79], v[168:171], v[208:211], v[76:79]
	v_mfma_f32_16x16x32_bf16 v[68:71], v[160:163], v[226:229], v[68:71]
	v_mfma_f32_16x16x32_bf16 v[64:67], v[168:171], v[226:229], v[64:67]
	s_setprio 0
	s_barrier
	s_add_i32 s61, s61, s20
	v_lshl_add_u64 v[180:181], s[40:41], 0, v[112:113]
	s_mov_b32 m0, s61
	ds_read_b128 v[172:175], v143 offset:16384
	ds_read_b128 v[176:179], v143 offset:17408
	ds_read_b128 v[184:187], v143 offset:18432
	ds_read_b128 v[200:203], v143 offset:19456
	ds_read_b128 v[204:207], v143 offset:20480
	ds_read_b128 v[208:211], v143 offset:21504
	ds_read_b128 v[222:225], v143 offset:22528
	ds_read_b128 v[226:229], v143 offset:23552
	global_load_lds_dwordx4 v[180:181], off
	s_add_i32 m0, s61, 0x2000
	s_add_u32 s62, s40, 0x100000
	v_lshl_add_u64 v[212:213], s[40:41], 0, v[130:131]
	s_addc_u32 s63, s41, 0
	s_add_i32 s61, s64, s20
	global_load_lds_dwordx4 v[212:213], off
	v_lshl_add_u64 v[230:231], s[62:63], 0, v[112:113]
	s_mov_b32 m0, s61
	v_lshl_add_u64 v[232:233], s[12:13], 0, v[130:131]
	global_load_lds_dwordx4 v[230:231], off
	v_lshl_add_u64 v[230:231], s[62:63], 0, v[130:131]
	s_add_i32 m0, s61, 0x2000
	s_nop 0
	global_load_lds_dwordx4 v[230:231], off
	v_lshl_add_u64 v[230:231], s[12:13], 0, v[112:113]
	s_mov_b32 m0, s21
	s_nop 0
	global_load_lds_dwordx4 v[230:231], off
	s_mov_b32 m0, s22
	s_nop 0
	global_load_lds_dwordx4 v[232:233], off
	s_waitcnt vmcnt(8)
	s_waitcnt lgkmcnt(0)
	s_barrier
; #define PG8_STAGE(bufoff, gbase, voff) do { _Pragma("unroll") for (int _i = 0; _i < 2; ++_i) \
;         __builtin_amdgcn_global_load_lds((const unsigned*)((const char*)(gbase) + (voff)[_i]), (PG8_LAS unsigned*)(lds + (bufoff) + ldsw + _i * 8192), 16, 0, 0); } while (0)
; #define PG8_LDA(dst, b, h) do { _Pragma("unroll") for (int m = 0; m < 4; ++m) _Pragma("unroll") for (int k = 0; k < 2; ++k) dst[m][k] = *(const PG8_LAS bf16x8*)(lds + PG8_SA(b, h) + aoff + m * 2048 + k * 1024); } while (0)
; #define PG8_LDB(dst, b, h) do { _Pragma("unroll") for (int n = 0; n < 2; ++n) _Pragma("unroll") for (int k = 0; k < 2; ++k) dst[n][k] = *(const PG8_LAS bf16x8*)(lds + PG8_SB(b, h) + boff + n * 2048 + k * 1024); } while (0)
; #define PG8_MMA(ai, bj, At, Bt) do { __builtin_amdgcn_s_setprio(1); _Pragma("unroll") for (int m = 0; m < 4; ++m) _Pragma("unroll") for (int n = 0; n < 2; ++n) _Pragma("unroll") for (int k = 0; k < 2; ++k) \
;         acc[ai][bj][m][n] = __builtin_amdgcn_mfma_f32_16x16x32_bf16(Bt[n][k], At[m][k], acc[ai][bj][m][n], 0, 0, 0); __builtin_amdgcn_s_setprio(0); } while (0)
; #define PG8_WAIT_V(n) asm volatile("s_waitcnt vmcnt(" #n ")" ::: "memory")
; #define PG8_WAIT_L(n) asm volatile("s_waitcnt lgkmcnt(" #n ")" ::: "memory")
; #define PG8_BAR __builtin_amdgcn_s_barrier()
; #define PG8_SCHED __builtin_amdgcn_sched_barrier(0)
; template <class Epi, class Sched, bool ALIGN_EPI = false, bool SP2 = false>
; __device__ __forceinline__ void gemm_phase(PG8_LAS unsigned char* lds, const Gemm g, const Sched& S, const Epi& E) {
;     ...
;             PG8_WAIT_V(8); PG8_WAIT_L(0); PG8_BAR; PG8_MMA(1, 0, At, B0); PG8_MMA(1, 1, At, B1); PG8_BAR; PG8_SCHED;
;             PG8_LDB(B0, 1, 0); PG8_LDB(B1, 1, 1); PG8_SCHED; PG8_LDA(At, 1, 0); PG8_STAGE(PG8_SA(0, 1), a2 + hstep, voffA);
;             PG8_WAIT_V(8); PG8_WAIT_L(0); PG8_BAR; PG8_MMA(0, 0, At, B0); PG8_MMA(0, 1, At, B1); PG8_BAR; PG8_SCHED;
	s_setprio 1
	s_waitcnt lgkmcnt(0)
	v_mfma_f32_16x16x32_bf16 v[60:63], v[136:139], v[172:175], 0
	v_mfma_f32_16x16x32_bf16 v[56:59], v[148:151], v[172:175], 0
	v_mfma_f32_16x16x32_bf16 v[48:51], v[136:139], v[184:187], 0
	v_mfma_f32_16x16x32_bf16 v[40:43], v[148:151], v[184:187], 0
	v_mfma_f32_16x16x32_bf16 v[32:35], v[136:139], v[204:207], 0
	v_mfma_f32_16x16x32_bf16 v[24:27], v[148:151], v[204:207], 0
	v_mfma_f32_16x16x32_bf16 v[16:19], v[136:139], v[222:225], 0
	v_mfma_f32_16x16x32_bf16 v[8:11], v[148:151], v[222:225], 0
	v_mfma_f32_16x16x32_bf16 v[60:63], v[144:147], v[176:179], v[60:63]
	v_mfma_f32_16x16x32_bf16 v[56:59], v[152:155], v[176:179], v[56:59]
	v_mfma_f32_16x16x32_bf16 v[48:51], v[144:147], v[200:203], v[48:51]
	v_mfma_f32_16x16x32_bf16 v[40:43], v[152:155], v[200:203], v[40:43]
	v_mfma_f32_16x16x32_bf16 v[32:35], v[144:147], v[208:211], v[32:35]
	v_mfma_f32_16x16x32_bf16 v[24:27], v[152:155], v[208:211], v[24:27]
	v_mfma_f32_16x16x32_bf16 v[16:19], v[144:147], v[226:229], v[16:19]
	v_mfma_f32_16x16x32_bf16 v[8:11], v[152:155], v[226:229], v[8:11]
	s_setprio 0
	s_setprio 1
	v_mfma_f32_16x16x32_bf16 v[52:55], v[156:159], v[172:175], 0
	v_mfma_f32_16x16x32_bf16 v[44:47], v[164:167], v[172:175], 0
	v_mfma_f32_16x16x32_bf16 v[36:39], v[156:159], v[184:187], 0
	v_mfma_f32_16x16x32_bf16 v[28:31], v[164:167], v[184:187], 0
	v_mfma_f32_16x16x32_bf16 v[20:23], v[156:159], v[204:207], 0
	v_mfma_f32_16x16x32_bf16 v[12:15], v[164:167], v[204:207], 0
	v_mfma_f32_16x16x32_bf16 v[4:7], v[156:159], v[222:225], 0
	v_mfma_f32_16x16x32_bf16 v[0:3], v[164:167], v[222:225], 0
	v_mfma_f32_16x16x32_bf16 v[52:55], v[160:163], v[176:179], v[52:55]
	v_mfma_f32_16x16x32_bf16 v[44:47], v[168:171], v[176:179], v[44:47]
	v_mfma_f32_16x16x32_bf16 v[36:39], v[160:163], v[200:203], v[36:39]
	v_mfma_f32_16x16x32_bf16 v[28:31], v[168:171], v[200:203], v[28:31]
	v_mfma_f32_16x16x32_bf16 v[20:23], v[160:163], v[208:211], v[20:23]
	v_mfma_f32_16x16x32_bf16 v[12:15], v[168:171], v[208:211], v[12:15]
	v_mfma_f32_16x16x32_bf16 v[4:7], v[160:163], v[226:229], v[4:7]
	v_mfma_f32_16x16x32_bf16 v[0:3], v[168:171], v[226:229], v[0:3]
	s_setprio 0
	s_barrier
	s_add_i32 s61, 0, 0x18000
	s_add_i32 s62, 0, 0x1c000
	v_add_u32_e32 v152, s61, v141
	v_add_u32_e32 v168, s62, v141
	ds_read_b128 v[136:139], v152
	ds_read_b128 v[144:147], v152 offset:1024
	ds_read_b128 v[148:151], v152 offset:2048
	ds_read_b128 v[152:155], v152 offset:3072
	ds_read_b128 v[156:159], v168
	ds_read_b128 v[160:163], v168 offset:1024
	ds_read_b128 v[164:167], v168 offset:2048
	ds_read_b128 v[168:171], v168 offset:3072
	s_add_u32 s12, s12, 0x100000
	s_addc_u32 s13, s13, 0
	s_mov_b32 m0, s23
	v_lshl_add_u64 v[234:235], s[12:13], 0, v[112:113]
	ds_read_b128 v[172:175], v143 offset:32768
	ds_read_b128 v[176:179], v143 offset:33792
	ds_read_b128 v[184:187], v143 offset:34816
	ds_read_b128 v[200:203], v143 offset:35840
	ds_read_b128 v[204:207], v143 offset:36864
	ds_read_b128 v[208:211], v143 offset:37888
	ds_read_b128 v[222:225], v143 offset:38912
	ds_read_b128 v[226:229], v143 offset:39936
	global_load_lds_dwordx4 v[234:235], off
	v_lshl_add_u64 v[234:235], s[12:13], 0, v[130:131]
	s_mov_b32 m0, s24
	s_nop 0
	global_load_lds_dwordx4 v[234:235], off
	s_waitcnt vmcnt(8)
	s_waitcnt lgkmcnt(0)
	s_barrier
	s_setprio 1
	s_waitcnt lgkmcnt(0)
	v_mfma_f32_16x16x32_bf16 v[126:129], v[136:139], v[172:175], v[126:129]
	v_mfma_f32_16x16x32_bf16 v[122:125], v[148:151], v[172:175], v[122:125]
	v_mfma_f32_16x16x32_bf16 v[114:117], v[136:139], v[184:187], v[114:117]
	v_mfma_f32_16x16x32_bf16 v[104:107], v[148:151], v[184:187], v[104:107]
	v_mfma_f32_16x16x32_bf16 v[96:99], v[136:139], v[204:207], v[96:99]
	v_mfma_f32_16x16x32_bf16 v[88:91], v[148:151], v[204:207], v[88:91]
	v_mfma_f32_16x16x32_bf16 v[80:83], v[136:139], v[222:225], v[80:83]
	v_mfma_f32_16x16x32_bf16 v[72:75], v[148:151], v[222:225], v[72:75]
	v_mfma_f32_16x16x32_bf16 v[126:129], v[144:147], v[176:179], v[126:129]
	v_mfma_f32_16x16x32_bf16 v[122:125], v[152:155], v[176:179], v[122:125]
	v_mfma_f32_16x16x32_bf16 v[114:117], v[144:147], v[200:203], v[114:117]
	v_mfma_f32_16x16x32_bf16 v[104:107], v[152:155], v[200:203], v[104:107]
	v_mfma_f32_16x16x32_bf16 v[96:99], v[144:147], v[208:211], v[96:99]
	v_mfma_f32_16x16x32_bf16 v[88:91], v[152:155], v[208:211], v[88:91]
	v_mfma_f32_16x16x32_bf16 v[80:83], v[144:147], v[226:229], v[80:83]
	v_mfma_f32_16x16x32_bf16 v[72:75], v[152:155], v[226:229], v[72:75]
	s_setprio 0
	s_setprio 1
	v_mfma_f32_16x16x32_bf16 v[118:121], v[156:159], v[172:175], v[118:121]
	v_mfma_f32_16x16x32_bf16 v[108:111], v[164:167], v[172:175], v[108:111]
	v_mfma_f32_16x16x32_bf16 v[100:103], v[156:159], v[184:187], v[100:103]
	v_mfma_f32_16x16x32_bf16 v[92:95], v[164:167], v[184:187], v[92:95]
	v_mfma_f32_16x16x32_bf16 v[84:87], v[156:159], v[204:207], v[84:87]
	v_mfma_f32_16x16x32_bf16 v[76:79], v[164:167], v[204:207], v[76:79]
	v_mfma_f32_16x16x32_bf16 v[68:71], v[156:159], v[222:225], v[68:71]
	v_mfma_f32_16x16x32_bf16 v[64:67], v[164:167], v[222:225], v[64:67]
	v_mfma_f32_16x16x32_bf16 v[118:121], v[160:163], v[176:179], v[118:121]
	v_mfma_f32_16x16x32_bf16 v[108:111], v[168:171], v[176:179], v[108:111]
	v_mfma_f32_16x16x32_bf16 v[100:103], v[160:163], v[200:203], v[100:103]
	v_mfma_f32_16x16x32_bf16 v[92:95], v[168:171], v[200:203], v[92:95]
	v_mfma_f32_16x16x32_bf16 v[84:87], v[160:163], v[208:211], v[84:87]
	v_mfma_f32_16x16x32_bf16 v[76:79], v[168:171], v[208:211], v[76:79]
	v_mfma_f32_16x16x32_bf16 v[68:71], v[160:163], v[226:229], v[68:71]
	v_mfma_f32_16x16x32_bf16 v[64:67], v[168:171], v[226:229], v[64:67]
	s_setprio 0
	s_barrier
; #define PG8_STAGE(bufoff, gbase, voff) do { _Pragma("unroll") for (int _i = 0; _i < 2; ++_i) \
;         __builtin_amdgcn_global_load_lds((const unsigned*)((const char*)(gbase) + (voff)[_i]), (PG8_LAS unsigned*)(lds + (bufoff) + ldsw + _i * 8192), 16, 0, 0); } while (0)
; #define PG8_LDA(dst, b, h) do { _Pragma("unroll") for (int m = 0; m < 4; ++m) _Pragma("unroll") for (int k = 0; k < 2; ++k) dst[m][k] = *(const PG8_LAS bf16x8*)(lds + PG8_SA(b, h) + aoff + m * 2048 + k * 1024); } while (0)
; #define PG8_MMA(ai, bj, At, Bt) do { __builtin_amdgcn_s_setprio(1); _Pragma("unroll") for (int m = 0; m < 4; ++m) _Pragma("unroll") for (int n = 0; n < 2; ++n) _Pragma("unroll") for (int k = 0; k < 2; ++k) \
;         acc[ai][bj][m][n] = __builtin_amdgcn_mfma_f32_16x16x32_bf16(Bt[n][k], At[m][k], acc[ai][bj][m][n], 0, 0, 0); __builtin_amdgcn_s_setprio(0); } while (0)
; #define PG8_WAIT_V(n) asm volatile("s_waitcnt vmcnt(" #n ")" ::: "memory")
; #define PG8_WAIT_L(n) asm volatile("s_waitcnt lgkmcnt(" #n ")" ::: "memory")
; #define PG8_BAR __builtin_amdgcn_s_barrier()
; #define PG8_SCHED __builtin_amdgcn_sched_barrier(0)
; template <class Epi, class Sched, bool ALIGN_EPI = false, bool SP2 = false>
; __device__ __forceinline__ void gemm_phase(PG8_LAS unsigned char* lds, const Gemm g, const Sched& S, const Epi& E) {
;     ...
;             PG8_LDA(At, 1, 1); PG8_STAGE(PG8_SB(1, 0), b3, voffB); PG8_STAGE(PG8_SB(1, 1), b3 + hstep, voffB); PG8_STAGE(PG8_SA(1, 0), a3, voffA);
;             PG8_WAIT_V(8); PG8_WAIT_L(0); PG8_BAR; PG8_MMA(1, 0, At, B0); PG8_MMA(1, 1, At, B1); PG8_BAR; PG8_SCHED;
	s_add_i32 s12, s61, s20
	v_lshl_add_u64 v[180:181], v[180:181], 0, s[36:37]
	s_mov_b32 m0, s12
	ds_read_b128 v[172:175], v143 offset:49152
	ds_read_b128 v[176:179], v143 offset:50176
	ds_read_b128 v[184:187], v143 offset:51200
	ds_read_b128 v[200:203], v143 offset:52224
	ds_read_b128 v[204:207], v143 offset:53248
	ds_read_b128 v[208:211], v143 offset:54272
	ds_read_b128 v[222:225], v143 offset:55296
	ds_read_b128 v[226:229], v143 offset:56320
	global_load_lds_dwordx4 v[180:181], off
	s_add_i32 m0, s12, 0x2000
	s_add_u32 s12, s40, 0x100080
	v_lshl_add_u64 v[180:181], v[212:213], 0, s[36:37]
	s_addc_u32 s13, s41, 0
	s_add_i32 s40, s62, s20
	global_load_lds_dwordx4 v[180:181], off
	v_lshl_add_u64 v[180:181], s[12:13], 0, v[112:113]
	s_mov_b32 m0, s40
	s_nop 0
	global_load_lds_dwordx4 v[180:181], off
	v_lshl_add_u64 v[180:181], s[12:13], 0, v[130:131]
	s_add_i32 m0, s40, 0x2000
	s_nop 0
	global_load_lds_dwordx4 v[180:181], off
	v_lshl_add_u64 v[180:181], v[230:231], 0, s[36:37]
	s_mov_b32 m0, s26
	s_nop 0
	global_load_lds_dwordx4 v[180:181], off
	v_lshl_add_u64 v[180:181], v[232:233], 0, s[36:37]
	s_mov_b32 m0, s33
	s_nop 0
	global_load_lds_dwordx4 v[180:181], off
	s_waitcnt vmcnt(8)
	s_waitcnt lgkmcnt(0)
	s_barrier
	s_setprio 1
	s_waitcnt lgkmcnt(0)
	v_mfma_f32_16x16x32_bf16 v[60:63], v[136:139], v[172:175], v[60:63]
	v_mfma_f32_16x16x32_bf16 v[56:59], v[148:151], v[172:175], v[56:59]
	v_mfma_f32_16x16x32_bf16 v[48:51], v[136:139], v[184:187], v[48:51]
	v_mfma_f32_16x16x32_bf16 v[40:43], v[148:151], v[184:187], v[40:43]
	v_mfma_f32_16x16x32_bf16 v[32:35], v[136:139], v[204:207], v[32:35]
	v_mfma_f32_16x16x32_bf16 v[24:27], v[148:151], v[204:207], v[24:27]
	v_mfma_f32_16x16x32_bf16 v[16:19], v[136:139], v[222:225], v[16:19]
	v_mfma_f32_16x16x32_bf16 v[8:11], v[148:151], v[222:225], v[8:11]
	v_mfma_f32_16x16x32_bf16 v[60:63], v[144:147], v[176:179], v[60:63]
	v_mfma_f32_16x16x32_bf16 v[56:59], v[152:155], v[176:179], v[56:59]
	v_mfma_f32_16x16x32_bf16 v[48:51], v[144:147], v[200:203], v[48:51]
	v_mfma_f32_16x16x32_bf16 v[40:43], v[152:155], v[200:203], v[40:43]
	v_mfma_f32_16x16x32_bf16 v[32:35], v[144:147], v[208:211], v[32:35]
	v_mfma_f32_16x16x32_bf16 v[24:27], v[152:155], v[208:211], v[24:27]
	v_mfma_f32_16x16x32_bf16 v[16:19], v[144:147], v[226:229], v[16:19]
	v_mfma_f32_16x16x32_bf16 v[8:11], v[152:155], v[226:229], v[8:11]
	s_setprio 0
	s_setprio 1
	v_mfma_f32_16x16x32_bf16 v[52:55], v[156:159], v[172:175], v[52:55]
	v_mfma_f32_16x16x32_bf16 v[44:47], v[164:167], v[172:175], v[44:47]
	v_mfma_f32_16x16x32_bf16 v[36:39], v[156:159], v[184:187], v[36:39]
	v_mfma_f32_16x16x32_bf16 v[28:31], v[164:167], v[184:187], v[28:31]
	v_mfma_f32_16x16x32_bf16 v[20:23], v[156:159], v[204:207], v[20:23]
	v_mfma_f32_16x16x32_bf16 v[12:15], v[164:167], v[204:207], v[12:15]
	v_mfma_f32_16x16x32_bf16 v[4:7], v[156:159], v[222:225], v[4:7]
	v_mfma_f32_16x16x32_bf16 v[0:3], v[164:167], v[222:225], v[0:3]
	v_mfma_f32_16x16x32_bf16 v[52:55], v[160:163], v[176:179], v[52:55]
	v_mfma_f32_16x16x32_bf16 v[44:47], v[168:171], v[176:179], v[44:47]
	v_mfma_f32_16x16x32_bf16 v[36:39], v[160:163], v[200:203], v[36:39]
	v_mfma_f32_16x16x32_bf16 v[28:31], v[168:171], v[200:203], v[28:31]
	v_mfma_f32_16x16x32_bf16 v[20:23], v[160:163], v[208:211], v[20:23]
	v_mfma_f32_16x16x32_bf16 v[12:15], v[168:171], v[208:211], v[12:15]
	v_mfma_f32_16x16x32_bf16 v[4:7], v[160:163], v[226:229], v[4:7]
	v_mfma_f32_16x16x32_bf16 v[0:3], v[168:171], v[226:229], v[0:3]
	s_setprio 0
	s_barrier
	s_add_i32 s60, s60, 2
	s_add_u32 s54, s54, 0x100
	s_addc_u32 s55, s55, 0
	s_add_u32 s57, s57, 0x100
	s_addc_u32 s58, s58, 0
	s_cmp_gt_u32 s60, 61

